# ladder + A reads by first use + fragment ds_reads issued before the scalar bookkeeping in the 12-read load blocks
# baseline (speedup 1.0000x reference)
.LBB0_134:
	s_add_i32 s88, 0, 0x10000
	v_add_u32_e32 v152, s88, v191
	ds_read_b128 v[128:131], v152
	ds_read_b128 v[132:135], v152 offset:1024
	ds_read_b128 v[148:151], v152 offset:2048
	ds_read_b128 v[152:155], v152 offset:3072
	ds_read_b128 v[156:159], v192
	ds_read_b128 v[164:167], v192 offset:2048
	ds_read_b128 v[194:197], v192 offset:4096
	ds_read_b128 v[202:205], v192 offset:6144
	ds_read_b128 v[160:163], v192 offset:1024
	ds_read_b128 v[168:171], v192 offset:3072
	ds_read_b128 v[198:201], v192 offset:5120
	ds_read_b128 v[206:209], v192 offset:7168
	s_add_u32 s28, s66, 0xfffc0080
	s_addc_u32 s29, s67, -1
	s_cmp_eq_u32 vcc_lo, 12
	s_cselect_b32 s71, s5, s29
	s_cselect_b32 s70, s7, s28
	s_cselect_b32 s69, s17, s91
	s_cselect_b32 s68, s19, s85
	s_add_i32 m0, s73, 0xc000
	v_lshl_add_u64 v[172:173], s[66:67], 0, v[144:145]
	global_load_lds_dwordx4 v[172:173], off
	v_lshl_add_u64 v[172:173], s[66:67], 0, v[146:147]
	s_add_i32 m0, s73, 0xe000
	s_nop 0
	global_load_lds_dwordx4 v[172:173], off
	s_waitcnt lgkmcnt(8)
	s_barrier
	s_setprio 1
	s_waitcnt lgkmcnt(7)
	v_mfma_f32_16x16x32_bf16 v[124:127], v[128:131], v[156:159], v[124:127]
	v_mfma_f32_16x16x32_bf16 v[120:123], v[148:151], v[156:159], v[120:123]
	s_waitcnt lgkmcnt(6)
	v_mfma_f32_16x16x32_bf16 v[108:111], v[128:131], v[164:167], v[108:111]
	v_mfma_f32_16x16x32_bf16 v[104:107], v[148:151], v[164:167], v[104:107]
	s_waitcnt lgkmcnt(5)
	v_mfma_f32_16x16x32_bf16 v[92:95], v[128:131], v[194:197], v[92:95]
	v_mfma_f32_16x16x32_bf16 v[88:91], v[148:151], v[194:197], v[88:91]
	s_waitcnt lgkmcnt(4)
	v_mfma_f32_16x16x32_bf16 v[76:79], v[128:131], v[202:205], v[76:79]
	v_mfma_f32_16x16x32_bf16 v[72:75], v[148:151], v[202:205], v[72:75]
	s_waitcnt lgkmcnt(3)
	v_mfma_f32_16x16x32_bf16 v[124:127], v[132:135], v[160:163], v[124:127]
	v_mfma_f32_16x16x32_bf16 v[120:123], v[152:155], v[160:163], v[120:123]
	s_waitcnt lgkmcnt(2)
	v_mfma_f32_16x16x32_bf16 v[108:111], v[132:135], v[168:171], v[108:111]
	v_mfma_f32_16x16x32_bf16 v[104:107], v[152:155], v[168:171], v[104:107]
	s_waitcnt lgkmcnt(1)
	v_mfma_f32_16x16x32_bf16 v[92:95], v[132:135], v[198:201], v[92:95]
	v_mfma_f32_16x16x32_bf16 v[88:91], v[152:155], v[198:201], v[88:91]
	s_waitcnt lgkmcnt(0)
	v_mfma_f32_16x16x32_bf16 v[76:79], v[132:135], v[206:209], v[76:79]
	v_mfma_f32_16x16x32_bf16 v[72:75], v[152:155], v[206:209], v[72:75]
	s_setprio 0
	s_barrier
	s_add_i32 s89, 0, 0x14000
	v_add_u32_e32 v172, s89, v191
	s_add_i32 s28, s88, s72
	ds_read_b128 v[210:213], v172
	ds_read_b128 v[214:217], v172 offset:1024
	ds_read_b128 v[232:235], v172 offset:2048
	ds_read_b128 v[236:239], v172 offset:3072
	v_lshl_add_u64 v[172:173], s[68:69], 0, v[138:139]
	s_mov_b32 m0, s28
	v_lshl_add_u64 v[188:189], s[68:69], 0, v[142:143]
	global_load_lds_dwordx4 v[172:173], off
	s_add_i32 m0, s28, 0x2000
	s_nop 0
	global_load_lds_dwordx4 v[188:189], off
	s_barrier
	s_setprio 1
	s_waitcnt lgkmcnt(3)
	v_mfma_f32_16x16x32_bf16 v[116:119], v[210:213], v[156:159], v[116:119]
	s_waitcnt lgkmcnt(1)
	v_mfma_f32_16x16x32_bf16 v[112:115], v[232:235], v[156:159], v[112:115]
	v_mfma_f32_16x16x32_bf16 v[100:103], v[210:213], v[164:167], v[100:103]
	v_mfma_f32_16x16x32_bf16 v[96:99], v[232:235], v[164:167], v[96:99]
	v_mfma_f32_16x16x32_bf16 v[84:87], v[210:213], v[194:197], v[84:87]
	v_mfma_f32_16x16x32_bf16 v[80:83], v[232:235], v[194:197], v[80:83]
	v_mfma_f32_16x16x32_bf16 v[68:71], v[210:213], v[202:205], v[68:71]
	v_mfma_f32_16x16x32_bf16 v[64:67], v[232:235], v[202:205], v[64:67]
	v_mfma_f32_16x16x32_bf16 v[116:119], v[214:217], v[160:163], v[116:119]
	s_waitcnt lgkmcnt(0)
	v_mfma_f32_16x16x32_bf16 v[112:115], v[236:239], v[160:163], v[112:115]
	v_mfma_f32_16x16x32_bf16 v[100:103], v[214:217], v[168:171], v[100:103]
	v_mfma_f32_16x16x32_bf16 v[96:99], v[236:239], v[168:171], v[96:99]
	v_mfma_f32_16x16x32_bf16 v[84:87], v[214:217], v[198:201], v[84:87]
	v_mfma_f32_16x16x32_bf16 v[80:83], v[236:239], v[198:201], v[80:83]
	v_mfma_f32_16x16x32_bf16 v[68:71], v[214:217], v[206:209], v[68:71]
	v_mfma_f32_16x16x32_bf16 v[64:67], v[236:239], v[206:209], v[64:67]
	s_setprio 0
	s_mov_b32 m0, s73
	v_lshl_add_u64 v[240:241], s[70:71], 0, v[136:137]
	s_barrier
	ds_read_b128 v[156:159], v192 offset:16384
	ds_read_b128 v[164:167], v192 offset:18432
	ds_read_b128 v[194:197], v192 offset:20480
	ds_read_b128 v[202:205], v192 offset:22528
	ds_read_b128 v[160:163], v192 offset:17408
	ds_read_b128 v[168:171], v192 offset:19456
	ds_read_b128 v[198:201], v192 offset:21504
	ds_read_b128 v[206:209], v192 offset:23552
	global_load_lds_dwordx4 v[240:241], off
	v_lshl_add_u64 v[242:243], s[70:71], 0, v[140:141]
	s_mov_b32 m0, s74
	s_nop 0
	global_load_lds_dwordx4 v[242:243], off
	s_barrier
	s_setprio 1
	s_waitcnt lgkmcnt(7)
	v_mfma_f32_16x16x32_bf16 v[60:63], v[128:131], v[156:159], v[60:63]
	v_mfma_f32_16x16x32_bf16 v[56:59], v[148:151], v[156:159], v[56:59]
	s_waitcnt lgkmcnt(6)
	v_mfma_f32_16x16x32_bf16 v[44:47], v[128:131], v[164:167], v[44:47]
	v_mfma_f32_16x16x32_bf16 v[40:43], v[148:151], v[164:167], v[40:43]
	s_waitcnt lgkmcnt(5)
	v_mfma_f32_16x16x32_bf16 v[28:31], v[128:131], v[194:197], v[28:31]
	v_mfma_f32_16x16x32_bf16 v[24:27], v[148:151], v[194:197], v[24:27]
	s_waitcnt lgkmcnt(4)
	v_mfma_f32_16x16x32_bf16 v[12:15], v[128:131], v[202:205], v[12:15]
	v_mfma_f32_16x16x32_bf16 v[8:11], v[148:151], v[202:205], v[8:11]
	s_waitcnt lgkmcnt(3)
	v_mfma_f32_16x16x32_bf16 v[60:63], v[132:135], v[160:163], v[60:63]
	v_mfma_f32_16x16x32_bf16 v[56:59], v[152:155], v[160:163], v[56:59]
	s_waitcnt lgkmcnt(2)
	v_mfma_f32_16x16x32_bf16 v[44:47], v[132:135], v[168:171], v[44:47]
	v_mfma_f32_16x16x32_bf16 v[40:43], v[152:155], v[168:171], v[40:43]
	s_waitcnt lgkmcnt(1)
	v_mfma_f32_16x16x32_bf16 v[28:31], v[132:135], v[198:201], v[28:31]
	v_mfma_f32_16x16x32_bf16 v[24:27], v[152:155], v[198:201], v[24:27]
	s_waitcnt lgkmcnt(0)
	v_mfma_f32_16x16x32_bf16 v[12:15], v[132:135], v[206:209], v[12:15]
	v_mfma_f32_16x16x32_bf16 v[8:11], v[152:155], v[206:209], v[8:11]
	s_setprio 0
	s_barrier
	s_add_u32 s28, s68, 0x40000
	s_addc_u32 s29, s69, 0
	s_add_i32 s88, s89, s72
	v_lshl_add_u64 v[128:129], s[28:29], 0, v[138:139]
	s_mov_b32 m0, s88
	s_nop 0
	global_load_lds_dwordx4 v[128:129], off
	v_lshl_add_u64 v[128:129], s[28:29], 0, v[142:143]
	s_add_i32 m0, s88, 0x2000
	s_nop 0
	global_load_lds_dwordx4 v[128:129], off
	s_waitcnt vmcnt(6)
	s_barrier
	s_setprio 1
	v_mfma_f32_16x16x32_bf16 v[52:55], v[210:213], v[156:159], v[52:55]
	v_mfma_f32_16x16x32_bf16 v[48:51], v[232:235], v[156:159], v[48:51]
	v_mfma_f32_16x16x32_bf16 v[36:39], v[210:213], v[164:167], v[36:39]
	v_mfma_f32_16x16x32_bf16 v[32:35], v[232:235], v[164:167], v[32:35]
	v_mfma_f32_16x16x32_bf16 v[20:23], v[210:213], v[194:197], v[20:23]
	v_mfma_f32_16x16x32_bf16 v[16:19], v[232:235], v[194:197], v[16:19]
	v_mfma_f32_16x16x32_bf16 v[4:7], v[210:213], v[202:205], v[4:7]
	v_mfma_f32_16x16x32_bf16 v[0:3], v[232:235], v[202:205], v[0:3]
	v_mfma_f32_16x16x32_bf16 v[52:55], v[214:217], v[160:163], v[52:55]
	v_mfma_f32_16x16x32_bf16 v[48:51], v[236:239], v[160:163], v[48:51]
	v_mfma_f32_16x16x32_bf16 v[36:39], v[214:217], v[168:171], v[36:39]
	v_mfma_f32_16x16x32_bf16 v[32:35], v[236:239], v[168:171], v[32:35]
	v_mfma_f32_16x16x32_bf16 v[20:23], v[214:217], v[198:201], v[20:23]
	v_mfma_f32_16x16x32_bf16 v[16:19], v[236:239], v[198:201], v[16:19]
	v_mfma_f32_16x16x32_bf16 v[4:7], v[214:217], v[206:209], v[4:7]
	v_mfma_f32_16x16x32_bf16 v[0:3], v[236:239], v[206:209], v[0:3]
	s_setprio 0
	s_add_i32 s88, 0, 0x18000
	v_add_u32_e32 v152, s88, v191
	s_barrier
	ds_read_b128 v[128:131], v152
	ds_read_b128 v[132:135], v152 offset:1024
	ds_read_b128 v[148:151], v152 offset:2048
	ds_read_b128 v[152:155], v152 offset:3072
	ds_read_b128 v[156:159], v192 offset:32768
	ds_read_b128 v[164:167], v192 offset:34816
	ds_read_b128 v[194:197], v192 offset:36864
	ds_read_b128 v[202:205], v192 offset:38912
	ds_read_b128 v[160:163], v192 offset:33792
	ds_read_b128 v[168:171], v192 offset:35840
	ds_read_b128 v[198:201], v192 offset:37888
	ds_read_b128 v[206:209], v192 offset:39936
	s_add_u32 s28, s70, 0x40000
	s_addc_u32 s29, s71, 0
	s_mov_b32 m0, s75
	v_lshl_add_u64 v[210:211], s[28:29], 0, v[136:137]
	global_load_lds_dwordx4 v[210:211], off
	v_lshl_add_u64 v[210:211], s[28:29], 0, v[140:141]
	s_mov_b32 m0, s76
	s_nop 0
	global_load_lds_dwordx4 v[210:211], off
	s_waitcnt lgkmcnt(8)
	s_barrier
	s_setprio 1
	s_waitcnt lgkmcnt(7)
	v_mfma_f32_16x16x32_bf16 v[124:127], v[128:131], v[156:159], v[124:127]
	v_mfma_f32_16x16x32_bf16 v[120:123], v[148:151], v[156:159], v[120:123]
	s_waitcnt lgkmcnt(6)
	v_mfma_f32_16x16x32_bf16 v[108:111], v[128:131], v[164:167], v[108:111]
	v_mfma_f32_16x16x32_bf16 v[104:107], v[148:151], v[164:167], v[104:107]
	s_waitcnt lgkmcnt(5)
	v_mfma_f32_16x16x32_bf16 v[92:95], v[128:131], v[194:197], v[92:95]
	v_mfma_f32_16x16x32_bf16 v[88:91], v[148:151], v[194:197], v[88:91]
	s_waitcnt lgkmcnt(4)
	v_mfma_f32_16x16x32_bf16 v[76:79], v[128:131], v[202:205], v[76:79]
	v_mfma_f32_16x16x32_bf16 v[72:75], v[148:151], v[202:205], v[72:75]
	s_waitcnt lgkmcnt(3)
	v_mfma_f32_16x16x32_bf16 v[124:127], v[132:135], v[160:163], v[124:127]
	v_mfma_f32_16x16x32_bf16 v[120:123], v[152:155], v[160:163], v[120:123]
	s_waitcnt lgkmcnt(2)
	v_mfma_f32_16x16x32_bf16 v[108:111], v[132:135], v[168:171], v[108:111]
	v_mfma_f32_16x16x32_bf16 v[104:107], v[152:155], v[168:171], v[104:107]
	s_waitcnt lgkmcnt(1)
	v_mfma_f32_16x16x32_bf16 v[92:95], v[132:135], v[198:201], v[92:95]
	v_mfma_f32_16x16x32_bf16 v[88:91], v[152:155], v[198:201], v[88:91]
	s_waitcnt lgkmcnt(0)
	v_mfma_f32_16x16x32_bf16 v[76:79], v[132:135], v[206:209], v[76:79]
	v_mfma_f32_16x16x32_bf16 v[72:75], v[152:155], v[206:209], v[72:75]
	s_setprio 0
	s_barrier
	s_add_i32 s70, 0, 0x1c000
	s_add_i32 s28, s88, s72
	v_add_u32_e32 v174, s70, v191
	v_lshl_add_u64 v[172:173], v[172:173], 0, s[40:41]
	s_mov_b32 m0, s28
	ds_read_b128 v[210:213], v174
	ds_read_b128 v[214:217], v174 offset:1024
	ds_read_b128 v[232:235], v174 offset:2048
	ds_read_b128 v[236:239], v174 offset:3072
	global_load_lds_dwordx4 v[172:173], off
	v_lshl_add_u64 v[172:173], v[188:189], 0, s[40:41]
	s_add_i32 m0, s28, 0x2000
	s_nop 0
	global_load_lds_dwordx4 v[172:173], off
	s_barrier
	s_setprio 1
	s_waitcnt lgkmcnt(3)
	v_mfma_f32_16x16x32_bf16 v[116:119], v[210:213], v[156:159], v[116:119]
	s_waitcnt lgkmcnt(1)
	v_mfma_f32_16x16x32_bf16 v[112:115], v[232:235], v[156:159], v[112:115]
	v_mfma_f32_16x16x32_bf16 v[100:103], v[210:213], v[164:167], v[100:103]
	v_mfma_f32_16x16x32_bf16 v[96:99], v[232:235], v[164:167], v[96:99]
	v_mfma_f32_16x16x32_bf16 v[84:87], v[210:213], v[194:197], v[84:87]
	v_mfma_f32_16x16x32_bf16 v[80:83], v[232:235], v[194:197], v[80:83]
	v_mfma_f32_16x16x32_bf16 v[68:71], v[210:213], v[202:205], v[68:71]
	v_mfma_f32_16x16x32_bf16 v[64:67], v[232:235], v[202:205], v[64:67]
	v_mfma_f32_16x16x32_bf16 v[116:119], v[214:217], v[160:163], v[116:119]
	s_waitcnt lgkmcnt(0)
	v_mfma_f32_16x16x32_bf16 v[112:115], v[236:239], v[160:163], v[112:115]
	v_mfma_f32_16x16x32_bf16 v[100:103], v[214:217], v[168:171], v[100:103]
	v_mfma_f32_16x16x32_bf16 v[96:99], v[236:239], v[168:171], v[96:99]
	v_mfma_f32_16x16x32_bf16 v[84:87], v[214:217], v[198:201], v[84:87]
	v_mfma_f32_16x16x32_bf16 v[80:83], v[236:239], v[198:201], v[80:83]
	v_mfma_f32_16x16x32_bf16 v[68:71], v[214:217], v[206:209], v[68:71]
	v_mfma_f32_16x16x32_bf16 v[64:67], v[236:239], v[206:209], v[64:67]
	s_setprio 0
	s_mov_b32 m0, s79
	v_lshl_add_u64 v[172:173], v[240:241], 0, s[40:41]
	s_barrier
	ds_read_b128 v[156:159], v192 offset:49152
	ds_read_b128 v[164:167], v192 offset:51200
	ds_read_b128 v[194:197], v192 offset:53248
	ds_read_b128 v[202:205], v192 offset:55296
	ds_read_b128 v[160:163], v192 offset:50176
	ds_read_b128 v[168:171], v192 offset:52224
	ds_read_b128 v[198:201], v192 offset:54272
	ds_read_b128 v[206:209], v192 offset:56320
	global_load_lds_dwordx4 v[172:173], off
	v_lshl_add_u64 v[172:173], v[242:243], 0, s[40:41]
	s_mov_b32 m0, s80
	s_nop 0
	global_load_lds_dwordx4 v[172:173], off
	s_barrier
	s_setprio 1
	s_waitcnt lgkmcnt(7)
	v_mfma_f32_16x16x32_bf16 v[60:63], v[128:131], v[156:159], v[60:63]
	v_mfma_f32_16x16x32_bf16 v[56:59], v[148:151], v[156:159], v[56:59]
	s_waitcnt lgkmcnt(6)
	v_mfma_f32_16x16x32_bf16 v[44:47], v[128:131], v[164:167], v[44:47]
	v_mfma_f32_16x16x32_bf16 v[40:43], v[148:151], v[164:167], v[40:43]
	s_waitcnt lgkmcnt(5)
	v_mfma_f32_16x16x32_bf16 v[28:31], v[128:131], v[194:197], v[28:31]
	v_mfma_f32_16x16x32_bf16 v[24:27], v[148:151], v[194:197], v[24:27]
	s_waitcnt lgkmcnt(4)
	v_mfma_f32_16x16x32_bf16 v[12:15], v[128:131], v[202:205], v[12:15]
	v_mfma_f32_16x16x32_bf16 v[8:11], v[148:151], v[202:205], v[8:11]
	s_waitcnt lgkmcnt(3)
	v_mfma_f32_16x16x32_bf16 v[60:63], v[132:135], v[160:163], v[60:63]
	v_mfma_f32_16x16x32_bf16 v[56:59], v[152:155], v[160:163], v[56:59]
	s_waitcnt lgkmcnt(2)
	v_mfma_f32_16x16x32_bf16 v[44:47], v[132:135], v[168:171], v[44:47]
	v_mfma_f32_16x16x32_bf16 v[40:43], v[152:155], v[168:171], v[40:43]
	s_waitcnt lgkmcnt(1)
	v_mfma_f32_16x16x32_bf16 v[28:31], v[132:135], v[198:201], v[28:31]
	v_mfma_f32_16x16x32_bf16 v[24:27], v[152:155], v[198:201], v[24:27]
	s_waitcnt lgkmcnt(0)
	v_mfma_f32_16x16x32_bf16 v[12:15], v[132:135], v[206:209], v[12:15]
	v_mfma_f32_16x16x32_bf16 v[8:11], v[152:155], v[206:209], v[8:11]
	s_setprio 0
	s_barrier
	s_add_u32 s28, s68, 0x40080
	s_addc_u32 s29, s69, 0
	s_add_i32 s68, s70, s72
	v_lshl_add_u64 v[128:129], s[28:29], 0, v[138:139]
	s_mov_b32 m0, s68
	s_nop 0
	global_load_lds_dwordx4 v[128:129], off
	v_lshl_add_u64 v[128:129], s[28:29], 0, v[142:143]
	s_add_i32 m0, s68, 0x2000
	s_nop 0
	global_load_lds_dwordx4 v[128:129], off
	s_waitcnt vmcnt(6)
	s_barrier
	s_setprio 1
	v_mfma_f32_16x16x32_bf16 v[52:55], v[210:213], v[156:159], v[52:55]
	v_mfma_f32_16x16x32_bf16 v[48:51], v[232:235], v[156:159], v[48:51]
	v_mfma_f32_16x16x32_bf16 v[36:39], v[210:213], v[164:167], v[36:39]
	v_mfma_f32_16x16x32_bf16 v[32:35], v[232:235], v[164:167], v[32:35]
	v_mfma_f32_16x16x32_bf16 v[20:23], v[210:213], v[194:197], v[20:23]
	v_mfma_f32_16x16x32_bf16 v[16:19], v[232:235], v[194:197], v[16:19]
	v_mfma_f32_16x16x32_bf16 v[4:7], v[210:213], v[202:205], v[4:7]
	v_mfma_f32_16x16x32_bf16 v[0:3], v[232:235], v[202:205], v[0:3]
	v_mfma_f32_16x16x32_bf16 v[52:55], v[214:217], v[160:163], v[52:55]
	v_mfma_f32_16x16x32_bf16 v[48:51], v[236:239], v[160:163], v[48:51]
	v_mfma_f32_16x16x32_bf16 v[36:39], v[214:217], v[168:171], v[36:39]
	v_mfma_f32_16x16x32_bf16 v[32:35], v[236:239], v[168:171], v[32:35]
	v_mfma_f32_16x16x32_bf16 v[20:23], v[214:217], v[198:201], v[20:23]
	v_mfma_f32_16x16x32_bf16 v[16:19], v[236:239], v[198:201], v[16:19]
	v_mfma_f32_16x16x32_bf16 v[4:7], v[214:217], v[206:209], v[4:7]
	v_mfma_f32_16x16x32_bf16 v[0:3], v[236:239], v[206:209], v[0:3]
	s_setprio 0
	s_add_i32 vcc_lo, vcc_lo, 2
	s_add_u32 s66, s66, 0x100
	s_addc_u32 s67, s67, 0
	s_add_u32 s85, s85, 0x100
	s_addc_u32 s91, s91, 0
	s_cmp_lt_u32 vcc_lo, 14
	s_barrier
	s_cbranch_scc1 .LBB0_134
	s_lshl_b32 s4, s4, 8
	v_mov_b32_e32 v176, v175
	v_mov_b32_e32 v188, v190
	s_add_i32 s4, s4, s77
	s_cmp_gt_i32 s6, 7
	v_add_u32_e32 v148, s4, v176
	v_lshlrev_b32_e32 v128, 2, v188
	v_ashrrev_i32_e32 v129, 31, v128
	v_ashrrev_i32_e32 v149, 31, v148
	v_lshl_add_u64 v[128:129], v[128:129], 2, s[8:9]
	v_lshlrev_b64 v[130:131], 6, v[148:149]
	v_add_u32_e32 v166, 16, v148
	v_lshl_add_u64 v[130:131], v[128:129], 0, v[130:131]
	v_ashrrev_i32_e32 v167, 31, v166
	global_load_dwordx4 v[160:163], v[130:131], off
	v_lshlrev_b64 v[130:131], 6, v[166:167]
	v_lshl_add_u64 v[130:131], v[128:129], 0, v[130:131]
	global_load_dwordx4 v[168:171], v[130:131], off
	v_add_u32_e32 v164, 32, v148
	v_ashrrev_i32_e32 v165, 31, v164
	v_lshlrev_b64 v[130:131], 6, v[164:165]
	v_add_u32_e32 v158, 48, v148
	v_lshl_add_u64 v[130:131], v[128:129], 0, v[130:131]
	v_ashrrev_i32_e32 v159, 31, v158
	global_load_dwordx4 v[194:197], v[130:131], off
	v_lshlrev_b64 v[130:131], 6, v[158:159]
	v_lshl_add_u64 v[130:131], v[128:129], 0, v[130:131]
	global_load_dwordx4 v[198:201], v[130:131], off
	v_add_u32_e32 v156, 0x80, v148
	v_ashrrev_i32_e32 v157, 31, v156
	v_lshlrev_b64 v[130:131], 6, v[156:157]
	v_add_u32_e32 v154, 0x90, v148
	v_lshl_add_u64 v[130:131], v[128:129], 0, v[130:131]
	v_ashrrev_i32_e32 v155, 31, v154
	global_load_dwordx4 v[202:205], v[130:131], off
	v_lshlrev_b64 v[130:131], 6, v[154:155]
	v_add_u32_e32 v152, 0xa0, v148
	v_lshl_add_u64 v[130:131], v[128:129], 0, v[130:131]
	v_ashrrev_i32_e32 v153, 31, v152
	global_load_dwordx4 v[206:209], v[130:131], off
	v_lshlrev_b64 v[130:131], 6, v[152:153]
	v_add_u32_e32 v150, 0xb0, v148
	v_lshl_add_u64 v[130:131], v[128:129], 0, v[130:131]
	v_ashrrev_i32_e32 v151, 31, v150
	global_load_dwordx4 v[132:135], v[130:131], off
	v_lshlrev_b64 v[130:131], 6, v[150:151]
	v_lshl_add_u64 v[128:129], v[128:129], 0, v[130:131]
	global_load_dwordx4 v[128:131], v[128:129], off
	s_cselect_b64 s[66:67], -1, 0
	s_lshl_b32 s7, s6, 8
	s_add_i32 s7, s81, s7
	s_cmp_lt_i32 s6, 8
	s_mov_b64 s[68:69], -1
	s_waitcnt vmcnt(0)
	v_mov_b32_e32 v172, v161
	v_mov_b32_e32 v173, v162
	v_mov_b32_e32 v161, v163
	v_mov_b32_e32 v162, v169
	v_mov_b32_e32 v163, v170
	v_mov_b32_e32 v169, v171
	v_pk_add_f32 v[160:161], v[172:173], v[160:161]
	v_pk_add_f32 v[162:163], v[162:163], v[168:169]
	v_mov_b32_e32 v169, v160
	v_mov_b32_e32 v168, v162
	v_mov_b32_e32 v160, v163
	v_pk_add_f32 v[160:161], v[168:169], v[160:161]
	ds_bpermute_b32 v163, v219, v161
	ds_bpermute_b32 v162, v219, v160
	s_waitcnt lgkmcnt(0)
	v_pk_add_f32 v[160:161], v[160:161], v[162:163]
	ds_bpermute_b32 v163, v218, v161
	ds_bpermute_b32 v162, v218, v160
	s_waitcnt lgkmcnt(0)
	v_pk_add_f32 v[160:161], v[160:161], v[162:163]
	s_nop 0
	v_pk_fma_f32 v[172:173], v[160:161], s[30:31], v[178:179] op_sel_hi:[1,0,0]
	v_mov_b32_e32 v162, v199
	v_mul_f32_e32 v160, 0x4b800000, v173
	v_cmp_gt_f32_e32 vcc, s86, v173
	v_mov_b32_e32 v163, v200
	v_mov_b32_e32 v199, v201
	v_cndmask_b32_e32 v160, v173, v160, vcc
	v_rsq_f32_e32 v160, v160
	v_pk_add_f32 v[162:163], v[162:163], v[198:199]
	v_cmp_gt_f32_e64 s[4:5], s86, v172
	v_mov_b32_e32 v168, v162
	v_mul_f32_e32 v161, 0x45800000, v160
	v_cndmask_b32_e32 v174, v160, v161, vcc
	v_mov_b32_e32 v160, v195
	v_mov_b32_e32 v161, v196
	v_mov_b32_e32 v195, v197
	v_pk_add_f32 v[160:161], v[160:161], v[194:195]
	s_nop 0
	v_mov_b32_e32 v169, v160
	v_mov_b32_e32 v160, v163
	v_pk_add_f32 v[160:161], v[168:169], v[160:161]
	ds_bpermute_b32 v163, v219, v161
	ds_bpermute_b32 v162, v219, v160
	s_waitcnt lgkmcnt(0)
	v_pk_add_f32 v[168:169], v[160:161], v[162:163]
	v_mov_b32_e32 v160, v203
	v_mov_b32_e32 v161, v204
	v_mov_b32_e32 v203, v205
	v_mov_b32_e32 v162, v207
	v_mov_b32_e32 v163, v208
	v_mov_b32_e32 v207, v209
	v_pk_add_f32 v[160:161], v[160:161], v[202:203]
	v_pk_add_f32 v[162:163], v[162:163], v[206:207]
	v_mov_b32_e32 v195, v160
	v_mov_b32_e32 v194, v162
	v_mov_b32_e32 v160, v163
	v_pk_add_f32 v[160:161], v[194:195], v[160:161]
	v_mov_b32_e32 v194, v133
	v_mov_b32_e32 v195, v134
	v_mov_b32_e32 v133, v135
	v_mov_b32_e32 v134, v129
	v_mov_b32_e32 v135, v130
	v_mov_b32_e32 v129, v131
	v_pk_add_f32 v[132:133], v[194:195], v[132:133]
	v_pk_add_f32 v[128:129], v[134:135], v[128:129]
	v_mov_b32_e32 v131, v132
	v_mov_b32_e32 v130, v128
	v_mov_b32_e32 v132, v129
	v_pk_add_f32 v[128:129], v[130:131], v[132:133]
	ds_bpermute_b32 v163, v219, v161
	ds_bpermute_b32 v162, v219, v160
	ds_bpermute_b32 v131, v219, v129
	ds_bpermute_b32 v130, v219, v128
	ds_bpermute_b32 v171, v218, v169
	ds_bpermute_b32 v170, v218, v168
	s_waitcnt lgkmcnt(4)
	v_pk_add_f32 v[160:161], v[160:161], v[162:163]
	ds_bpermute_b32 v163, v218, v161
	s_waitcnt lgkmcnt(3)
	v_pk_add_f32 v[132:133], v[128:129], v[130:131]
	ds_bpermute_b32 v162, v218, v160
	ds_bpermute_b32 v135, v218, v133
	ds_bpermute_b32 v134, v218, v132
	v_lshlrev_b32_e32 v128, 3, v188
	v_add_u32_e32 v130, s7, v128
	v_lshlrev_b64 v[188:189], 11, v[148:149]
	v_ashrrev_i32_e32 v131, 31, v130
	s_cbranch_scc1 .LBB0_137
	v_mul_f32_e32 v196, v120, v174
	v_mul_f32_e32 v197, v121, v174
	v_mul_f32_e32 v198, v122, v174
	v_mul_f32_e32 v199, v123, v174
	v_mul_f32_e32 v129, v124, v174
	v_mul_f32_e32 v149, v125, v174
	v_mul_f32_e32 v173, v126, v174
	v_mul_f32_e32 v193, v127, v174
	v_cvt_pk_bf16_f32 v194, v129, v149
	v_cvt_pk_bf16_f32 v195, v173, v193
	v_cvt_pk_bf16_f32 v196, v196, v197
	v_cvt_pk_bf16_f32 v197, v198, v199
	v_lshl_add_u64 v[198:199], s[12:13], 0, v[188:189]
	v_lshl_add_u64 v[198:199], v[130:131], 1, v[198:199]
	global_store_dwordx4 v[198:199], v[194:197], off
	s_mov_b64 s[68:69], 0
	v_mul_f32_e32 v129, v116, v174
	v_mul_f32_e32 v196, v112, v174
	v_mul_f32_e32 v197, v113, v174
	v_mul_f32_e32 v149, v117, v174
	v_mul_f32_e32 v173, v118, v174
	v_mul_f32_e32 v193, v119, v174
	v_mul_f32_e32 v200, v114, v174
	v_mul_f32_e32 v201, v115, v174
	v_cvt_pk_bf16_f32 v194, v129, v149
	v_cvt_pk_bf16_f32 v195, v173, v193
	v_cvt_pk_bf16_f32 v196, v196, v197
	v_cvt_pk_bf16_f32 v197, v200, v201
	global_store_dwordx4 v[198:199], v[194:197], off offset:256

.LBB0_413:
	s_add_i32 s28, 0, 0x10000
	v_add_u32_e32 v140, s28, v164
	ds_read_b128 v[128:131], v140
	ds_read_b128 v[132:135], v140 offset:1024
	ds_read_b128 v[136:139], v140 offset:2048
	ds_read_b128 v[140:143], v140 offset:3072
	ds_read_b128 v[154:157], v165
	ds_read_b128 v[166:169], v165 offset:2048
	ds_read_b128 v[188:191], v165 offset:4096
	ds_read_b128 v[196:199], v165 offset:6144
	ds_read_b128 v[158:161], v165 offset:1024
	ds_read_b128 v[170:173], v165 offset:3072
	ds_read_b128 v[192:195], v165 offset:5120
	ds_read_b128 v[200:203], v165 offset:7168
	s_add_i32 vcc_lo, s62, 2
	s_add_u32 s4, s18, 0x100
	s_addc_u32 s5, s19, 0
	s_cmp_eq_u32 s13, s62
	s_cselect_b32 s62, s6, s85
	s_cselect_b32 s65, s17, s5
	s_cselect_b32 s64, s16, s4
	s_cselect_b32 s63, s7, s91
	s_add_i32 m0, s69, 0xc000
	v_lshl_add_u64 v[174:175], s[18:19], 0, v[150:151]
	global_load_lds_dwordx4 v[174:175], off
	v_lshl_add_u64 v[174:175], s[18:19], 0, v[152:153]
	s_add_i32 m0, s69, 0xe000
	s_nop 0
	global_load_lds_dwordx4 v[174:175], off
	s_waitcnt lgkmcnt(8)
	s_barrier
	s_setprio 1
	s_waitcnt lgkmcnt(7)
	v_mfma_f32_16x16x32_bf16 v[124:127], v[128:131], v[154:157], v[124:127]
	v_mfma_f32_16x16x32_bf16 v[120:123], v[136:139], v[154:157], v[120:123]
	s_waitcnt lgkmcnt(6)
	v_mfma_f32_16x16x32_bf16 v[108:111], v[128:131], v[166:169], v[108:111]
	v_mfma_f32_16x16x32_bf16 v[104:107], v[136:139], v[166:169], v[104:107]
	s_waitcnt lgkmcnt(5)
	v_mfma_f32_16x16x32_bf16 v[92:95], v[128:131], v[188:191], v[92:95]
	v_mfma_f32_16x16x32_bf16 v[88:91], v[136:139], v[188:191], v[88:91]
	s_waitcnt lgkmcnt(4)
	v_mfma_f32_16x16x32_bf16 v[76:79], v[128:131], v[196:199], v[76:79]
	v_mfma_f32_16x16x32_bf16 v[72:75], v[136:139], v[196:199], v[72:75]
	s_waitcnt lgkmcnt(3)
	v_mfma_f32_16x16x32_bf16 v[124:127], v[132:135], v[158:161], v[124:127]
	v_mfma_f32_16x16x32_bf16 v[120:123], v[140:143], v[158:161], v[120:123]
	s_waitcnt lgkmcnt(2)
	v_mfma_f32_16x16x32_bf16 v[108:111], v[132:135], v[170:173], v[108:111]
	v_mfma_f32_16x16x32_bf16 v[104:107], v[140:143], v[170:173], v[104:107]
	s_waitcnt lgkmcnt(1)
	v_mfma_f32_16x16x32_bf16 v[92:95], v[132:135], v[192:195], v[92:95]
	v_mfma_f32_16x16x32_bf16 v[88:91], v[140:143], v[192:195], v[88:91]
	s_waitcnt lgkmcnt(0)
	v_mfma_f32_16x16x32_bf16 v[76:79], v[132:135], v[200:203], v[76:79]
	v_mfma_f32_16x16x32_bf16 v[72:75], v[140:143], v[200:203], v[72:75]
	s_setprio 0
	s_barrier
	s_add_i32 s29, 0, 0x14000
	v_add_u32_e32 v174, s29, v164
	s_add_i32 s18, s28, s68
	ds_read_b128 v[204:207], v174
	ds_read_b128 v[208:211], v174 offset:1024
	ds_read_b128 v[212:215], v174 offset:2048
	ds_read_b128 v[232:235], v174 offset:3072
	v_lshl_add_u64 v[174:175], s[62:63], 0, v[176:177]
	s_mov_b32 m0, s18
	v_lshl_add_u64 v[216:217], s[62:63], 0, v[148:149]
	global_load_lds_dwordx4 v[174:175], off
	s_add_i32 m0, s18, 0x2000
	s_nop 0
	global_load_lds_dwordx4 v[216:217], off
	s_barrier
	s_setprio 1
	s_waitcnt lgkmcnt(3)
	v_mfma_f32_16x16x32_bf16 v[116:119], v[204:207], v[154:157], v[116:119]
	s_waitcnt lgkmcnt(1)
	v_mfma_f32_16x16x32_bf16 v[112:115], v[212:215], v[154:157], v[112:115]
	v_mfma_f32_16x16x32_bf16 v[100:103], v[204:207], v[166:169], v[100:103]
	v_mfma_f32_16x16x32_bf16 v[96:99], v[212:215], v[166:169], v[96:99]
	v_mfma_f32_16x16x32_bf16 v[84:87], v[204:207], v[188:191], v[84:87]
	v_mfma_f32_16x16x32_bf16 v[80:83], v[212:215], v[188:191], v[80:83]
	v_mfma_f32_16x16x32_bf16 v[68:71], v[204:207], v[196:199], v[68:71]
	v_mfma_f32_16x16x32_bf16 v[64:67], v[212:215], v[196:199], v[64:67]
	v_mfma_f32_16x16x32_bf16 v[116:119], v[208:211], v[158:161], v[116:119]
	s_waitcnt lgkmcnt(0)
	v_mfma_f32_16x16x32_bf16 v[112:115], v[232:235], v[158:161], v[112:115]
	v_mfma_f32_16x16x32_bf16 v[100:103], v[208:211], v[170:173], v[100:103]
	v_mfma_f32_16x16x32_bf16 v[96:99], v[232:235], v[170:173], v[96:99]
	v_mfma_f32_16x16x32_bf16 v[84:87], v[208:211], v[192:195], v[84:87]
	v_mfma_f32_16x16x32_bf16 v[80:83], v[232:235], v[192:195], v[80:83]
	v_mfma_f32_16x16x32_bf16 v[68:71], v[208:211], v[200:203], v[68:71]
	v_mfma_f32_16x16x32_bf16 v[64:67], v[232:235], v[200:203], v[64:67]
	s_setprio 0
	s_mov_b32 m0, s69
	v_lshl_add_u64 v[236:237], s[64:65], 0, v[144:145]
	s_barrier
	ds_read_b128 v[154:157], v165 offset:16384
	ds_read_b128 v[166:169], v165 offset:18432
	ds_read_b128 v[188:191], v165 offset:20480
	ds_read_b128 v[196:199], v165 offset:22528
	ds_read_b128 v[158:161], v165 offset:17408
	ds_read_b128 v[170:173], v165 offset:19456
	ds_read_b128 v[192:195], v165 offset:21504
	ds_read_b128 v[200:203], v165 offset:23552
	global_load_lds_dwordx4 v[236:237], off
	v_lshl_add_u64 v[238:239], s[64:65], 0, v[146:147]
	s_mov_b32 m0, s70
	s_nop 0
	global_load_lds_dwordx4 v[238:239], off
	s_barrier
	s_setprio 1
	s_waitcnt lgkmcnt(7)
	v_mfma_f32_16x16x32_bf16 v[60:63], v[128:131], v[154:157], v[60:63]
	v_mfma_f32_16x16x32_bf16 v[56:59], v[136:139], v[154:157], v[56:59]
	s_waitcnt lgkmcnt(6)
	v_mfma_f32_16x16x32_bf16 v[44:47], v[128:131], v[166:169], v[44:47]
	v_mfma_f32_16x16x32_bf16 v[40:43], v[136:139], v[166:169], v[40:43]
	s_waitcnt lgkmcnt(5)
	v_mfma_f32_16x16x32_bf16 v[28:31], v[128:131], v[188:191], v[28:31]
	v_mfma_f32_16x16x32_bf16 v[24:27], v[136:139], v[188:191], v[24:27]
	s_waitcnt lgkmcnt(4)
	v_mfma_f32_16x16x32_bf16 v[12:15], v[128:131], v[196:199], v[12:15]
	v_mfma_f32_16x16x32_bf16 v[8:11], v[136:139], v[196:199], v[8:11]
	s_waitcnt lgkmcnt(3)
	v_mfma_f32_16x16x32_bf16 v[60:63], v[132:135], v[158:161], v[60:63]
	v_mfma_f32_16x16x32_bf16 v[56:59], v[140:143], v[158:161], v[56:59]
	s_waitcnt lgkmcnt(2)
	v_mfma_f32_16x16x32_bf16 v[44:47], v[132:135], v[170:173], v[44:47]
	v_mfma_f32_16x16x32_bf16 v[40:43], v[140:143], v[170:173], v[40:43]
	s_waitcnt lgkmcnt(1)
	v_mfma_f32_16x16x32_bf16 v[28:31], v[132:135], v[192:195], v[28:31]
	v_mfma_f32_16x16x32_bf16 v[24:27], v[140:143], v[192:195], v[24:27]
	s_waitcnt lgkmcnt(0)
	v_mfma_f32_16x16x32_bf16 v[12:15], v[132:135], v[200:203], v[12:15]
	v_mfma_f32_16x16x32_bf16 v[8:11], v[140:143], v[200:203], v[8:11]
	s_setprio 0
	s_barrier
	s_add_u32 s18, s62, 0x18000
	s_addc_u32 s19, s63, 0
	s_add_i32 s28, s29, s68
	v_lshl_add_u64 v[128:129], s[18:19], 0, v[176:177]
	s_mov_b32 m0, s28
	s_nop 0
	global_load_lds_dwordx4 v[128:129], off
	v_lshl_add_u64 v[128:129], s[18:19], 0, v[148:149]
	s_add_i32 m0, s28, 0x2000
	s_nop 0
	global_load_lds_dwordx4 v[128:129], off
	s_waitcnt vmcnt(6)
	s_barrier
	s_setprio 1
	v_mfma_f32_16x16x32_bf16 v[52:55], v[204:207], v[154:157], v[52:55]
	v_mfma_f32_16x16x32_bf16 v[48:51], v[212:215], v[154:157], v[48:51]
	v_mfma_f32_16x16x32_bf16 v[36:39], v[204:207], v[166:169], v[36:39]
	v_mfma_f32_16x16x32_bf16 v[32:35], v[212:215], v[166:169], v[32:35]
	v_mfma_f32_16x16x32_bf16 v[20:23], v[204:207], v[188:191], v[20:23]
	v_mfma_f32_16x16x32_bf16 v[16:19], v[212:215], v[188:191], v[16:19]
	v_mfma_f32_16x16x32_bf16 v[4:7], v[204:207], v[196:199], v[4:7]
	v_mfma_f32_16x16x32_bf16 v[0:3], v[212:215], v[196:199], v[0:3]
	v_mfma_f32_16x16x32_bf16 v[52:55], v[208:211], v[158:161], v[52:55]
	v_mfma_f32_16x16x32_bf16 v[48:51], v[232:235], v[158:161], v[48:51]
	v_mfma_f32_16x16x32_bf16 v[36:39], v[208:211], v[170:173], v[36:39]
	v_mfma_f32_16x16x32_bf16 v[32:35], v[232:235], v[170:173], v[32:35]
	v_mfma_f32_16x16x32_bf16 v[20:23], v[208:211], v[192:195], v[20:23]
	v_mfma_f32_16x16x32_bf16 v[16:19], v[232:235], v[192:195], v[16:19]
	v_mfma_f32_16x16x32_bf16 v[4:7], v[208:211], v[200:203], v[4:7]
	v_mfma_f32_16x16x32_bf16 v[0:3], v[232:235], v[200:203], v[0:3]
	s_setprio 0
	s_add_i32 s28, 0, 0x18000
	v_add_u32_e32 v140, s28, v164
	s_barrier
	ds_read_b128 v[128:131], v140
	ds_read_b128 v[132:135], v140 offset:1024
	ds_read_b128 v[136:139], v140 offset:2048
	ds_read_b128 v[140:143], v140 offset:3072
	ds_read_b128 v[154:157], v165 offset:32768
	ds_read_b128 v[166:169], v165 offset:34816
	ds_read_b128 v[188:191], v165 offset:36864
	ds_read_b128 v[196:199], v165 offset:38912
	ds_read_b128 v[158:161], v165 offset:33792
	ds_read_b128 v[170:173], v165 offset:35840
	ds_read_b128 v[192:195], v165 offset:37888
	ds_read_b128 v[200:203], v165 offset:39936
	s_add_u32 s18, s64, 0x18000
	s_addc_u32 s19, s65, 0
	s_mov_b32 m0, s71
	v_lshl_add_u64 v[204:205], s[18:19], 0, v[144:145]
	global_load_lds_dwordx4 v[204:205], off
	v_lshl_add_u64 v[204:205], s[18:19], 0, v[146:147]
	s_mov_b32 m0, s72
	s_nop 0
	global_load_lds_dwordx4 v[204:205], off
	s_waitcnt lgkmcnt(8)
	s_barrier
	s_setprio 1
	s_waitcnt lgkmcnt(7)
	v_mfma_f32_16x16x32_bf16 v[124:127], v[128:131], v[154:157], v[124:127]
	v_mfma_f32_16x16x32_bf16 v[120:123], v[136:139], v[154:157], v[120:123]
	s_waitcnt lgkmcnt(6)
	v_mfma_f32_16x16x32_bf16 v[108:111], v[128:131], v[166:169], v[108:111]
	v_mfma_f32_16x16x32_bf16 v[104:107], v[136:139], v[166:169], v[104:107]
	s_waitcnt lgkmcnt(5)
	v_mfma_f32_16x16x32_bf16 v[92:95], v[128:131], v[188:191], v[92:95]
	v_mfma_f32_16x16x32_bf16 v[88:91], v[136:139], v[188:191], v[88:91]
	s_waitcnt lgkmcnt(4)
	v_mfma_f32_16x16x32_bf16 v[76:79], v[128:131], v[196:199], v[76:79]
	v_mfma_f32_16x16x32_bf16 v[72:75], v[136:139], v[196:199], v[72:75]
	s_waitcnt lgkmcnt(3)
	v_mfma_f32_16x16x32_bf16 v[124:127], v[132:135], v[158:161], v[124:127]
	v_mfma_f32_16x16x32_bf16 v[120:123], v[140:143], v[158:161], v[120:123]
	s_waitcnt lgkmcnt(2)
	v_mfma_f32_16x16x32_bf16 v[108:111], v[132:135], v[170:173], v[108:111]
	v_mfma_f32_16x16x32_bf16 v[104:107], v[140:143], v[170:173], v[104:107]
	s_waitcnt lgkmcnt(1)
	v_mfma_f32_16x16x32_bf16 v[92:95], v[132:135], v[192:195], v[92:95]
	v_mfma_f32_16x16x32_bf16 v[88:91], v[140:143], v[192:195], v[88:91]
	s_waitcnt lgkmcnt(0)
	v_mfma_f32_16x16x32_bf16 v[76:79], v[132:135], v[200:203], v[76:79]
	v_mfma_f32_16x16x32_bf16 v[72:75], v[140:143], v[200:203], v[72:75]
	s_setprio 0
	s_barrier
	s_add_i32 s29, 0, 0x1c000
	s_add_i32 s18, s28, s68
	v_add_u32_e32 v232, s29, v164
	v_lshl_add_u64 v[174:175], v[174:175], 0, s[40:41]
	s_mov_b32 m0, s18
	ds_read_b128 v[204:207], v232
	ds_read_b128 v[208:211], v232 offset:1024
	ds_read_b128 v[212:215], v232 offset:2048
	ds_read_b128 v[232:235], v232 offset:3072
	global_load_lds_dwordx4 v[174:175], off
	v_lshl_add_u64 v[174:175], v[216:217], 0, s[40:41]
	s_add_i32 m0, s18, 0x2000
	s_nop 0
	global_load_lds_dwordx4 v[174:175], off
	s_barrier
	s_setprio 1
	s_waitcnt lgkmcnt(3)
	v_mfma_f32_16x16x32_bf16 v[116:119], v[204:207], v[154:157], v[116:119]
	s_waitcnt lgkmcnt(1)
	v_mfma_f32_16x16x32_bf16 v[112:115], v[212:215], v[154:157], v[112:115]
	v_mfma_f32_16x16x32_bf16 v[100:103], v[204:207], v[166:169], v[100:103]
	v_mfma_f32_16x16x32_bf16 v[96:99], v[212:215], v[166:169], v[96:99]
	v_mfma_f32_16x16x32_bf16 v[84:87], v[204:207], v[188:191], v[84:87]
	v_mfma_f32_16x16x32_bf16 v[80:83], v[212:215], v[188:191], v[80:83]
	v_mfma_f32_16x16x32_bf16 v[68:71], v[204:207], v[196:199], v[68:71]
	v_mfma_f32_16x16x32_bf16 v[64:67], v[212:215], v[196:199], v[64:67]
	v_mfma_f32_16x16x32_bf16 v[116:119], v[208:211], v[158:161], v[116:119]
	s_waitcnt lgkmcnt(0)
	v_mfma_f32_16x16x32_bf16 v[112:115], v[232:235], v[158:161], v[112:115]
	v_mfma_f32_16x16x32_bf16 v[100:103], v[208:211], v[170:173], v[100:103]
	v_mfma_f32_16x16x32_bf16 v[96:99], v[232:235], v[170:173], v[96:99]
	v_mfma_f32_16x16x32_bf16 v[84:87], v[208:211], v[192:195], v[84:87]
	v_mfma_f32_16x16x32_bf16 v[80:83], v[232:235], v[192:195], v[80:83]
	v_mfma_f32_16x16x32_bf16 v[68:71], v[208:211], v[200:203], v[68:71]
	v_mfma_f32_16x16x32_bf16 v[64:67], v[232:235], v[200:203], v[64:67]
	s_setprio 0
	s_mov_b32 m0, s75
	v_lshl_add_u64 v[174:175], v[236:237], 0, s[40:41]
	s_barrier
	ds_read_b128 v[154:157], v165 offset:49152
	ds_read_b128 v[166:169], v165 offset:51200
	ds_read_b128 v[188:191], v165 offset:53248
	ds_read_b128 v[196:199], v165 offset:55296
	ds_read_b128 v[158:161], v165 offset:50176
	ds_read_b128 v[170:173], v165 offset:52224
	ds_read_b128 v[192:195], v165 offset:54272
	ds_read_b128 v[200:203], v165 offset:56320
	global_load_lds_dwordx4 v[174:175], off
	v_lshl_add_u64 v[174:175], v[238:239], 0, s[40:41]
	s_mov_b32 m0, s76
	s_nop 0
	global_load_lds_dwordx4 v[174:175], off
	s_barrier
	s_setprio 1
	s_waitcnt lgkmcnt(7)
	v_mfma_f32_16x16x32_bf16 v[60:63], v[128:131], v[154:157], v[60:63]
	v_mfma_f32_16x16x32_bf16 v[56:59], v[136:139], v[154:157], v[56:59]
	s_waitcnt lgkmcnt(6)
	v_mfma_f32_16x16x32_bf16 v[44:47], v[128:131], v[166:169], v[44:47]
	v_mfma_f32_16x16x32_bf16 v[40:43], v[136:139], v[166:169], v[40:43]
	s_waitcnt lgkmcnt(5)
	v_mfma_f32_16x16x32_bf16 v[28:31], v[128:131], v[188:191], v[28:31]
	v_mfma_f32_16x16x32_bf16 v[24:27], v[136:139], v[188:191], v[24:27]
	s_waitcnt lgkmcnt(4)
	v_mfma_f32_16x16x32_bf16 v[12:15], v[128:131], v[196:199], v[12:15]
	v_mfma_f32_16x16x32_bf16 v[8:11], v[136:139], v[196:199], v[8:11]
	s_waitcnt lgkmcnt(3)
	v_mfma_f32_16x16x32_bf16 v[60:63], v[132:135], v[158:161], v[60:63]
	v_mfma_f32_16x16x32_bf16 v[56:59], v[140:143], v[158:161], v[56:59]
	s_waitcnt lgkmcnt(2)
	v_mfma_f32_16x16x32_bf16 v[44:47], v[132:135], v[170:173], v[44:47]
	v_mfma_f32_16x16x32_bf16 v[40:43], v[140:143], v[170:173], v[40:43]
	s_waitcnt lgkmcnt(1)
	v_mfma_f32_16x16x32_bf16 v[28:31], v[132:135], v[192:195], v[28:31]
	v_mfma_f32_16x16x32_bf16 v[24:27], v[140:143], v[192:195], v[24:27]
	s_waitcnt lgkmcnt(0)
	v_mfma_f32_16x16x32_bf16 v[12:15], v[132:135], v[200:203], v[12:15]
	v_mfma_f32_16x16x32_bf16 v[8:11], v[140:143], v[200:203], v[8:11]
	s_setprio 0
	s_barrier
	s_add_u32 s18, s62, 0x18080
	s_addc_u32 s19, s63, 0
	s_add_i32 s28, s29, s68
	v_lshl_add_u64 v[128:129], s[18:19], 0, v[176:177]
	s_mov_b32 m0, s28
	s_nop 0
	global_load_lds_dwordx4 v[128:129], off
	v_lshl_add_u64 v[128:129], s[18:19], 0, v[148:149]
	s_add_i32 m0, s28, 0x2000
	s_nop 0
	global_load_lds_dwordx4 v[128:129], off
	s_waitcnt vmcnt(6)
	s_barrier
	s_setprio 1
	v_mfma_f32_16x16x32_bf16 v[52:55], v[204:207], v[154:157], v[52:55]
	v_mfma_f32_16x16x32_bf16 v[48:51], v[212:215], v[154:157], v[48:51]
	v_mfma_f32_16x16x32_bf16 v[36:39], v[204:207], v[166:169], v[36:39]
	v_mfma_f32_16x16x32_bf16 v[32:35], v[212:215], v[166:169], v[32:35]
	v_mfma_f32_16x16x32_bf16 v[20:23], v[204:207], v[188:191], v[20:23]
	v_mfma_f32_16x16x32_bf16 v[16:19], v[212:215], v[188:191], v[16:19]
	v_mfma_f32_16x16x32_bf16 v[4:7], v[204:207], v[196:199], v[4:7]
	v_mfma_f32_16x16x32_bf16 v[0:3], v[212:215], v[196:199], v[0:3]
	v_mfma_f32_16x16x32_bf16 v[52:55], v[208:211], v[158:161], v[52:55]
	v_mfma_f32_16x16x32_bf16 v[48:51], v[232:235], v[158:161], v[48:51]
	v_mfma_f32_16x16x32_bf16 v[36:39], v[208:211], v[170:173], v[36:39]
	v_mfma_f32_16x16x32_bf16 v[32:35], v[232:235], v[170:173], v[32:35]
	v_mfma_f32_16x16x32_bf16 v[20:23], v[208:211], v[192:195], v[20:23]
	v_mfma_f32_16x16x32_bf16 v[16:19], v[232:235], v[192:195], v[16:19]
	v_mfma_f32_16x16x32_bf16 v[4:7], v[208:211], v[200:203], v[4:7]
	v_mfma_f32_16x16x32_bf16 v[0:3], v[232:235], v[200:203], v[0:3]
	s_setprio 0
	s_add_u32 s85, s85, 0x100
	s_addc_u32 s91, s91, 0
	s_cmp_lt_i32 vcc_lo, s67
	s_mov_b64 s[18:19], s[4:5]
	s_mov_b32 s62, vcc_lo
	s_barrier
	s_cbranch_scc1 .LBB0_413
	s_ashr_i32 s4, s66, 2
	v_mov_b32_e32 v128, v163
	v_mov_b32_e32 v166, v162
	s_cmp_eq_u32 s4, 2
	s_cbranch_scc1 .LBB0_416
	s_mul_i32 s13, s4, 0x2280000
	s_mul_hi_i32 s5, s4, 0x2280000
	s_add_u32 s18, s13, 0x5858000
	s_addc_u32 s19, s5, 0
	s_mov_b32 s62, 1.0
	s_branch .LBB0_417

.LBB0_505:
	s_add_i32 s28, 0, 0x10000
	v_add_u32_e32 v154, s28, v144
	ds_read_b128 v[138:141], v154
	ds_read_b128 v[146:149], v154 offset:1024
	ds_read_b128 v[150:153], v154 offset:2048
	ds_read_b128 v[154:157], v154 offset:3072
	ds_read_b128 v[158:161], v145
	ds_read_b128 v[166:169], v145 offset:2048
	ds_read_b128 v[188:191], v145 offset:4096
	ds_read_b128 v[196:199], v145 offset:6144
	ds_read_b128 v[162:165], v145 offset:1024
	ds_read_b128 v[170:173], v145 offset:3072
	ds_read_b128 v[192:195], v145 offset:5120
	ds_read_b128 v[200:203], v145 offset:7168
	s_add_u32 s6, s4, 0xfff80080
	s_addc_u32 s7, s5, -1
	s_cmp_eq_u32 s72, 28
	s_cselect_b32 s9, s10, s7
	s_cselect_b32 s8, s11, s6
	s_cselect_b32 s7, s63, s71
	s_cselect_b32 s6, s65, s70
	s_add_i32 m0, s17, 0xc000
	v_lshl_add_u64 v[174:175], s[4:5], 0, v[134:135]
	global_load_lds_dwordx4 v[174:175], off
	v_lshl_add_u64 v[174:175], s[4:5], 0, v[136:137]
	s_add_i32 m0, s17, 0xe000
	s_nop 0
	global_load_lds_dwordx4 v[174:175], off
	s_waitcnt lgkmcnt(8)
	s_barrier
	s_setprio 1
	s_waitcnt lgkmcnt(7)
	v_mfma_f32_16x16x32_bf16 v[124:127], v[138:141], v[158:161], v[124:127]
	v_mfma_f32_16x16x32_bf16 v[120:123], v[150:153], v[158:161], v[120:123]
	s_waitcnt lgkmcnt(6)
	v_mfma_f32_16x16x32_bf16 v[116:119], v[138:141], v[166:169], v[116:119]
	v_mfma_f32_16x16x32_bf16 v[108:111], v[150:153], v[166:169], v[108:111]
	s_waitcnt lgkmcnt(5)
	v_mfma_f32_16x16x32_bf16 v[100:103], v[138:141], v[188:191], v[100:103]
	v_mfma_f32_16x16x32_bf16 v[92:95], v[150:153], v[188:191], v[92:95]
	s_waitcnt lgkmcnt(4)
	v_mfma_f32_16x16x32_bf16 v[84:87], v[138:141], v[196:199], v[84:87]
	v_mfma_f32_16x16x32_bf16 v[76:79], v[150:153], v[196:199], v[76:79]
	s_waitcnt lgkmcnt(3)
	v_mfma_f32_16x16x32_bf16 v[124:127], v[146:149], v[162:165], v[124:127]
	v_mfma_f32_16x16x32_bf16 v[120:123], v[154:157], v[162:165], v[120:123]
	s_waitcnt lgkmcnt(2)
	v_mfma_f32_16x16x32_bf16 v[116:119], v[146:149], v[170:173], v[116:119]
	v_mfma_f32_16x16x32_bf16 v[108:111], v[154:157], v[170:173], v[108:111]
	s_waitcnt lgkmcnt(1)
	v_mfma_f32_16x16x32_bf16 v[100:103], v[146:149], v[192:195], v[100:103]
	v_mfma_f32_16x16x32_bf16 v[92:95], v[154:157], v[192:195], v[92:95]
	s_waitcnt lgkmcnt(0)
	v_mfma_f32_16x16x32_bf16 v[84:87], v[146:149], v[200:203], v[84:87]
	v_mfma_f32_16x16x32_bf16 v[76:79], v[154:157], v[200:203], v[76:79]
	s_setprio 0
	s_barrier
	s_add_i32 s29, 0, 0x14000
	v_add_u32_e32 v174, s29, v144
	s_add_i32 s28, s28, s77
	ds_read_b128 v[204:207], v174
	ds_read_b128 v[208:211], v174 offset:1024
	ds_read_b128 v[212:215], v174 offset:2048
	ds_read_b128 v[232:235], v174 offset:3072
	v_lshl_add_u64 v[174:175], s[6:7], 0, v[176:177]
	s_mov_b32 m0, s28
	v_lshl_add_u64 v[216:217], s[6:7], 0, v[132:133]
	global_load_lds_dwordx4 v[174:175], off
	s_add_i32 m0, s28, 0x2000
	s_nop 0
	global_load_lds_dwordx4 v[216:217], off
	s_barrier
	s_setprio 1
	s_waitcnt lgkmcnt(3)
	v_mfma_f32_16x16x32_bf16 v[112:115], v[204:207], v[158:161], v[112:115]
	s_waitcnt lgkmcnt(1)
	v_mfma_f32_16x16x32_bf16 v[104:107], v[212:215], v[158:161], v[104:107]
	v_mfma_f32_16x16x32_bf16 v[96:99], v[204:207], v[166:169], v[96:99]
	v_mfma_f32_16x16x32_bf16 v[88:91], v[212:215], v[166:169], v[88:91]
	v_mfma_f32_16x16x32_bf16 v[80:83], v[204:207], v[188:191], v[80:83]
	v_mfma_f32_16x16x32_bf16 v[72:75], v[212:215], v[188:191], v[72:75]
	v_mfma_f32_16x16x32_bf16 v[68:71], v[204:207], v[196:199], v[68:71]
	v_mfma_f32_16x16x32_bf16 v[64:67], v[212:215], v[196:199], v[64:67]
	v_mfma_f32_16x16x32_bf16 v[112:115], v[208:211], v[162:165], v[112:115]
	s_waitcnt lgkmcnt(0)
	v_mfma_f32_16x16x32_bf16 v[104:107], v[232:235], v[162:165], v[104:107]
	v_mfma_f32_16x16x32_bf16 v[96:99], v[208:211], v[170:173], v[96:99]
	v_mfma_f32_16x16x32_bf16 v[88:91], v[232:235], v[170:173], v[88:91]
	v_mfma_f32_16x16x32_bf16 v[80:83], v[208:211], v[192:195], v[80:83]
	v_mfma_f32_16x16x32_bf16 v[72:75], v[232:235], v[192:195], v[72:75]
	v_mfma_f32_16x16x32_bf16 v[68:71], v[208:211], v[200:203], v[68:71]
	v_mfma_f32_16x16x32_bf16 v[64:67], v[232:235], v[200:203], v[64:67]
	s_setprio 0
	s_mov_b32 m0, s17
	v_lshl_add_u64 v[236:237], s[8:9], 0, v[128:129]
	s_barrier
	ds_read_b128 v[158:161], v145 offset:16384
	ds_read_b128 v[166:169], v145 offset:18432
	ds_read_b128 v[188:191], v145 offset:20480
	ds_read_b128 v[196:199], v145 offset:22528
	ds_read_b128 v[162:165], v145 offset:17408
	ds_read_b128 v[170:173], v145 offset:19456
	ds_read_b128 v[192:195], v145 offset:21504
	ds_read_b128 v[200:203], v145 offset:23552
	global_load_lds_dwordx4 v[236:237], off
	v_lshl_add_u64 v[238:239], s[8:9], 0, v[130:131]
	s_mov_b32 m0, s19
	s_nop 0
	global_load_lds_dwordx4 v[238:239], off
	s_barrier
	s_setprio 1
	s_waitcnt lgkmcnt(7)
	v_mfma_f32_16x16x32_bf16 v[60:63], v[138:141], v[158:161], v[60:63]
	v_mfma_f32_16x16x32_bf16 v[56:59], v[150:153], v[158:161], v[56:59]
	s_waitcnt lgkmcnt(6)
	v_mfma_f32_16x16x32_bf16 v[52:55], v[138:141], v[166:169], v[52:55]
	v_mfma_f32_16x16x32_bf16 v[44:47], v[150:153], v[166:169], v[44:47]
	s_waitcnt lgkmcnt(5)
	v_mfma_f32_16x16x32_bf16 v[36:39], v[138:141], v[188:191], v[36:39]
	v_mfma_f32_16x16x32_bf16 v[28:31], v[150:153], v[188:191], v[28:31]
	s_waitcnt lgkmcnt(4)
	v_mfma_f32_16x16x32_bf16 v[20:23], v[138:141], v[196:199], v[20:23]
	v_mfma_f32_16x16x32_bf16 v[12:15], v[150:153], v[196:199], v[12:15]
	s_waitcnt lgkmcnt(3)
	v_mfma_f32_16x16x32_bf16 v[60:63], v[146:149], v[162:165], v[60:63]
	v_mfma_f32_16x16x32_bf16 v[56:59], v[154:157], v[162:165], v[56:59]
	s_waitcnt lgkmcnt(2)
	v_mfma_f32_16x16x32_bf16 v[52:55], v[146:149], v[170:173], v[52:55]
	v_mfma_f32_16x16x32_bf16 v[44:47], v[154:157], v[170:173], v[44:47]
	s_waitcnt lgkmcnt(1)
	v_mfma_f32_16x16x32_bf16 v[36:39], v[146:149], v[192:195], v[36:39]
	v_mfma_f32_16x16x32_bf16 v[28:31], v[154:157], v[192:195], v[28:31]
	s_waitcnt lgkmcnt(0)
	v_mfma_f32_16x16x32_bf16 v[20:23], v[146:149], v[200:203], v[20:23]
	v_mfma_f32_16x16x32_bf16 v[12:15], v[154:157], v[200:203], v[12:15]
	s_setprio 0
	s_barrier
	s_add_u32 vcc_lo, s6, 0x80000
	s_addc_u32 vcc_hi, s7, 0
	s_add_i32 s28, s29, s77
	v_lshl_add_u64 v[138:139], vcc, 0, v[176:177]
	s_mov_b32 m0, s28
	s_nop 0
	global_load_lds_dwordx4 v[138:139], off
	v_lshl_add_u64 v[138:139], vcc, 0, v[132:133]
	s_add_i32 m0, s28, 0x2000
	s_nop 0
	global_load_lds_dwordx4 v[138:139], off
	s_waitcnt vmcnt(6)
	s_barrier
	s_setprio 1
	v_mfma_f32_16x16x32_bf16 v[48:51], v[204:207], v[158:161], v[48:51]
	v_mfma_f32_16x16x32_bf16 v[40:43], v[212:215], v[158:161], v[40:43]
	v_mfma_f32_16x16x32_bf16 v[32:35], v[204:207], v[166:169], v[32:35]
	v_mfma_f32_16x16x32_bf16 v[24:27], v[212:215], v[166:169], v[24:27]
	v_mfma_f32_16x16x32_bf16 v[16:19], v[204:207], v[188:191], v[16:19]
	v_mfma_f32_16x16x32_bf16 v[8:11], v[212:215], v[188:191], v[8:11]
	v_mfma_f32_16x16x32_bf16 v[4:7], v[204:207], v[196:199], v[4:7]
	v_mfma_f32_16x16x32_bf16 v[0:3], v[212:215], v[196:199], v[0:3]
	v_mfma_f32_16x16x32_bf16 v[48:51], v[208:211], v[162:165], v[48:51]
	v_mfma_f32_16x16x32_bf16 v[40:43], v[232:235], v[162:165], v[40:43]
	v_mfma_f32_16x16x32_bf16 v[32:35], v[208:211], v[170:173], v[32:35]
	v_mfma_f32_16x16x32_bf16 v[24:27], v[232:235], v[170:173], v[24:27]
	v_mfma_f32_16x16x32_bf16 v[16:19], v[208:211], v[192:195], v[16:19]
	v_mfma_f32_16x16x32_bf16 v[8:11], v[232:235], v[192:195], v[8:11]
	v_mfma_f32_16x16x32_bf16 v[4:7], v[208:211], v[200:203], v[4:7]
	v_mfma_f32_16x16x32_bf16 v[0:3], v[232:235], v[200:203], v[0:3]
	s_setprio 0
	s_add_i32 s28, 0, 0x18000
	v_add_u32_e32 v154, s28, v144
	s_barrier
	ds_read_b128 v[138:141], v154
	ds_read_b128 v[146:149], v154 offset:1024
	ds_read_b128 v[150:153], v154 offset:2048
	ds_read_b128 v[154:157], v154 offset:3072
	ds_read_b128 v[158:161], v145 offset:32768
	ds_read_b128 v[166:169], v145 offset:34816
	ds_read_b128 v[188:191], v145 offset:36864
	ds_read_b128 v[196:199], v145 offset:38912
	ds_read_b128 v[162:165], v145 offset:33792
	ds_read_b128 v[170:173], v145 offset:35840
	ds_read_b128 v[192:195], v145 offset:37888
	ds_read_b128 v[200:203], v145 offset:39936
	s_add_u32 s8, s8, 0x80000
	s_addc_u32 s9, s9, 0
	s_mov_b32 m0, s78
	v_lshl_add_u64 v[204:205], s[8:9], 0, v[128:129]
	global_load_lds_dwordx4 v[204:205], off
	v_lshl_add_u64 v[204:205], s[8:9], 0, v[130:131]
	s_mov_b32 m0, s79
	s_nop 0
	global_load_lds_dwordx4 v[204:205], off
	s_waitcnt lgkmcnt(8)
	s_barrier
	s_setprio 1
	s_waitcnt lgkmcnt(7)
	v_mfma_f32_16x16x32_bf16 v[124:127], v[138:141], v[158:161], v[124:127]
	v_mfma_f32_16x16x32_bf16 v[120:123], v[150:153], v[158:161], v[120:123]
	s_waitcnt lgkmcnt(6)
	v_mfma_f32_16x16x32_bf16 v[116:119], v[138:141], v[166:169], v[116:119]
	v_mfma_f32_16x16x32_bf16 v[108:111], v[150:153], v[166:169], v[108:111]
	s_waitcnt lgkmcnt(5)
	v_mfma_f32_16x16x32_bf16 v[100:103], v[138:141], v[188:191], v[100:103]
	v_mfma_f32_16x16x32_bf16 v[92:95], v[150:153], v[188:191], v[92:95]
	s_waitcnt lgkmcnt(4)
	v_mfma_f32_16x16x32_bf16 v[84:87], v[138:141], v[196:199], v[84:87]
	v_mfma_f32_16x16x32_bf16 v[76:79], v[150:153], v[196:199], v[76:79]
	s_waitcnt lgkmcnt(3)
	v_mfma_f32_16x16x32_bf16 v[124:127], v[146:149], v[162:165], v[124:127]
	v_mfma_f32_16x16x32_bf16 v[120:123], v[154:157], v[162:165], v[120:123]
	s_waitcnt lgkmcnt(2)
	v_mfma_f32_16x16x32_bf16 v[116:119], v[146:149], v[170:173], v[116:119]
	v_mfma_f32_16x16x32_bf16 v[108:111], v[154:157], v[170:173], v[108:111]
	s_waitcnt lgkmcnt(1)
	v_mfma_f32_16x16x32_bf16 v[100:103], v[146:149], v[192:195], v[100:103]
	v_mfma_f32_16x16x32_bf16 v[92:95], v[154:157], v[192:195], v[92:95]
	s_waitcnt lgkmcnt(0)
	v_mfma_f32_16x16x32_bf16 v[84:87], v[146:149], v[200:203], v[84:87]
	v_mfma_f32_16x16x32_bf16 v[76:79], v[154:157], v[200:203], v[76:79]
	s_setprio 0
	s_barrier
	s_add_i32 s8, 0, 0x1c000
	s_add_i32 s9, s28, s77
	v_add_u32_e32 v232, s8, v144
	v_lshl_add_u64 v[174:175], v[174:175], 0, s[40:41]
	s_mov_b32 m0, s9
	ds_read_b128 v[204:207], v232
	ds_read_b128 v[208:211], v232 offset:1024
	ds_read_b128 v[212:215], v232 offset:2048
	ds_read_b128 v[232:235], v232 offset:3072
	global_load_lds_dwordx4 v[174:175], off
	v_lshl_add_u64 v[174:175], v[216:217], 0, s[40:41]
	s_add_i32 m0, s9, 0x2000
	s_nop 0
	global_load_lds_dwordx4 v[174:175], off
	s_barrier
	s_setprio 1
	s_waitcnt lgkmcnt(3)
	v_mfma_f32_16x16x32_bf16 v[112:115], v[204:207], v[158:161], v[112:115]
	s_waitcnt lgkmcnt(1)
	v_mfma_f32_16x16x32_bf16 v[104:107], v[212:215], v[158:161], v[104:107]
	v_mfma_f32_16x16x32_bf16 v[96:99], v[204:207], v[166:169], v[96:99]
	v_mfma_f32_16x16x32_bf16 v[88:91], v[212:215], v[166:169], v[88:91]
	v_mfma_f32_16x16x32_bf16 v[80:83], v[204:207], v[188:191], v[80:83]
	v_mfma_f32_16x16x32_bf16 v[72:75], v[212:215], v[188:191], v[72:75]
	v_mfma_f32_16x16x32_bf16 v[68:71], v[204:207], v[196:199], v[68:71]
	v_mfma_f32_16x16x32_bf16 v[64:67], v[212:215], v[196:199], v[64:67]
	v_mfma_f32_16x16x32_bf16 v[112:115], v[208:211], v[162:165], v[112:115]
	s_waitcnt lgkmcnt(0)
	v_mfma_f32_16x16x32_bf16 v[104:107], v[232:235], v[162:165], v[104:107]
	v_mfma_f32_16x16x32_bf16 v[96:99], v[208:211], v[170:173], v[96:99]
	v_mfma_f32_16x16x32_bf16 v[88:91], v[232:235], v[170:173], v[88:91]
	v_mfma_f32_16x16x32_bf16 v[80:83], v[208:211], v[192:195], v[80:83]
	v_mfma_f32_16x16x32_bf16 v[72:75], v[232:235], v[192:195], v[72:75]
	v_mfma_f32_16x16x32_bf16 v[68:71], v[208:211], v[200:203], v[68:71]
	v_mfma_f32_16x16x32_bf16 v[64:67], v[232:235], v[200:203], v[64:67]
	s_setprio 0
	s_mov_b32 m0, s82
	v_lshl_add_u64 v[174:175], v[236:237], 0, s[40:41]
	s_barrier
	ds_read_b128 v[158:161], v145 offset:49152
	ds_read_b128 v[166:169], v145 offset:51200
	ds_read_b128 v[188:191], v145 offset:53248
	ds_read_b128 v[196:199], v145 offset:55296
	ds_read_b128 v[162:165], v145 offset:50176
	ds_read_b128 v[170:173], v145 offset:52224
	ds_read_b128 v[192:195], v145 offset:54272
	ds_read_b128 v[200:203], v145 offset:56320
	global_load_lds_dwordx4 v[174:175], off
	v_lshl_add_u64 v[174:175], v[238:239], 0, s[40:41]
	s_mov_b32 m0, s83
	s_nop 0
	global_load_lds_dwordx4 v[174:175], off
	s_barrier
	s_setprio 1
	s_waitcnt lgkmcnt(7)
	v_mfma_f32_16x16x32_bf16 v[60:63], v[138:141], v[158:161], v[60:63]
	v_mfma_f32_16x16x32_bf16 v[56:59], v[150:153], v[158:161], v[56:59]
	s_waitcnt lgkmcnt(6)
	v_mfma_f32_16x16x32_bf16 v[52:55], v[138:141], v[166:169], v[52:55]
	v_mfma_f32_16x16x32_bf16 v[44:47], v[150:153], v[166:169], v[44:47]
	s_waitcnt lgkmcnt(5)
	v_mfma_f32_16x16x32_bf16 v[36:39], v[138:141], v[188:191], v[36:39]
	v_mfma_f32_16x16x32_bf16 v[28:31], v[150:153], v[188:191], v[28:31]
	s_waitcnt lgkmcnt(4)
	v_mfma_f32_16x16x32_bf16 v[20:23], v[138:141], v[196:199], v[20:23]
	v_mfma_f32_16x16x32_bf16 v[12:15], v[150:153], v[196:199], v[12:15]
	s_waitcnt lgkmcnt(3)
	v_mfma_f32_16x16x32_bf16 v[60:63], v[146:149], v[162:165], v[60:63]
	v_mfma_f32_16x16x32_bf16 v[56:59], v[154:157], v[162:165], v[56:59]
	s_waitcnt lgkmcnt(2)
	v_mfma_f32_16x16x32_bf16 v[52:55], v[146:149], v[170:173], v[52:55]
	v_mfma_f32_16x16x32_bf16 v[44:47], v[154:157], v[170:173], v[44:47]
	s_waitcnt lgkmcnt(1)
	v_mfma_f32_16x16x32_bf16 v[36:39], v[146:149], v[192:195], v[36:39]
	v_mfma_f32_16x16x32_bf16 v[28:31], v[154:157], v[192:195], v[28:31]
	s_waitcnt lgkmcnt(0)
	v_mfma_f32_16x16x32_bf16 v[20:23], v[146:149], v[200:203], v[20:23]
	v_mfma_f32_16x16x32_bf16 v[12:15], v[154:157], v[200:203], v[12:15]
	s_setprio 0
	s_barrier
	s_add_u32 s6, s6, 0x80080
	s_addc_u32 s7, s7, 0
	s_add_i32 s8, s8, s77
	v_lshl_add_u64 v[138:139], s[6:7], 0, v[176:177]
	s_mov_b32 m0, s8
	s_nop 0
	global_load_lds_dwordx4 v[138:139], off
	v_lshl_add_u64 v[138:139], s[6:7], 0, v[132:133]
	s_add_i32 m0, s8, 0x2000
	s_nop 0
	global_load_lds_dwordx4 v[138:139], off
	s_waitcnt vmcnt(6)
	s_barrier
	s_setprio 1
	v_mfma_f32_16x16x32_bf16 v[48:51], v[204:207], v[158:161], v[48:51]
	v_mfma_f32_16x16x32_bf16 v[40:43], v[212:215], v[158:161], v[40:43]
	v_mfma_f32_16x16x32_bf16 v[32:35], v[204:207], v[166:169], v[32:35]
	v_mfma_f32_16x16x32_bf16 v[24:27], v[212:215], v[166:169], v[24:27]
	v_mfma_f32_16x16x32_bf16 v[16:19], v[204:207], v[188:191], v[16:19]
	v_mfma_f32_16x16x32_bf16 v[8:11], v[212:215], v[188:191], v[8:11]
	v_mfma_f32_16x16x32_bf16 v[4:7], v[204:207], v[196:199], v[4:7]
	v_mfma_f32_16x16x32_bf16 v[0:3], v[212:215], v[196:199], v[0:3]
	v_mfma_f32_16x16x32_bf16 v[48:51], v[208:211], v[162:165], v[48:51]
	v_mfma_f32_16x16x32_bf16 v[40:43], v[232:235], v[162:165], v[40:43]
	v_mfma_f32_16x16x32_bf16 v[32:35], v[208:211], v[170:173], v[32:35]
	v_mfma_f32_16x16x32_bf16 v[24:27], v[232:235], v[170:173], v[24:27]
	v_mfma_f32_16x16x32_bf16 v[16:19], v[208:211], v[192:195], v[16:19]
	v_mfma_f32_16x16x32_bf16 v[8:11], v[232:235], v[192:195], v[8:11]
	v_mfma_f32_16x16x32_bf16 v[4:7], v[208:211], v[200:203], v[4:7]
	v_mfma_f32_16x16x32_bf16 v[0:3], v[232:235], v[200:203], v[0:3]
	s_setprio 0
	s_add_i32 s72, s72, 2
	s_add_u32 s4, s4, 0x100
	s_addc_u32 s5, s5, 0
	s_add_u32 s70, s70, 0x100
	s_addc_u32 s71, s71, 0
	s_cmp_lt_u32 s72, 30
	s_barrier
	s_cbranch_scc1 .LBB0_505
	v_mov_b32_e32 v147, v142
	v_mov_b32_e32 v146, v143
	s_cmp_lt_i32 s16, 12
	s_mov_b64 s[4:5], -1
	s_cbranch_scc1 .LBB0_1052
	s_lshl_b32 s4, s18, 8
	s_add_i32 s4, s4, s80
	v_add_u32_e32 v149, s4, v147
	s_lshl_b32 s4, s16, 8
	s_add_i32 s4, s84, s4
	v_lshl_add_u32 v138, v146, 3, s4
	v_mad_i64_i32 v[140:141], s[4:5], v149, s97, 0
	v_cmp_gt_i32_e32 vcc, s34, v138
	s_and_saveexec_b64 s[10:11], vcc
	s_cbranch_execz .LBB0_541
	v_cmp_lt_i32_e64 s[8:9], 63, v138
	v_cmp_gt_u32_e64 s[4:5], s93, v138
	v_cmp_gt_u32_e64 s[6:7], s96, v138
	s_and_saveexec_b64 s[70:71], s[8:9]
	s_xor_b64 s[70:71], exec, s[70:71]
	s_cbranch_execz .LBB0_510
	v_mul_f32_e32 v139, 0xbfb8aa3b, v124
	v_exp_f32_e32 v139, v139
	s_nop 0
	v_add_f32_e32 v139, 1.0, v139
	v_rcp_f32_e32 v139, v139
	s_nop 0
	v_cndmask_b32_e64 v139, 0, v139, s[6:7]
	v_cndmask_b32_e64 v139, v139, v124, s[4:5]
	s_andn2_saveexec_b64 s[70:71], s[70:71]
	s_cbranch_execz .LBB0_512
	s_branch .LBB0_511

.LBB0_1114:
	s_add_i32 s88, 0, 0x10000
	v_add_u32_e32 v140, s88, v194
	ds_read_b128 v[128:131], v140
	ds_read_b128 v[132:135], v140 offset:1024
	ds_read_b128 v[136:139], v140 offset:2048
	ds_read_b128 v[140:143], v140 offset:3072
	ds_read_b128 v[144:147], v195
	ds_read_b128 v[162:165], v195 offset:2048
	ds_read_b128 v[170:173], v195 offset:4096
	ds_read_b128 v[196:199], v195 offset:6144
	ds_read_b128 v[148:151], v195 offset:1024
	ds_read_b128 v[166:169], v195 offset:3072
	ds_read_b128 v[188:191], v195 offset:5120
	ds_read_b128 v[200:203], v195 offset:7168
	s_add_i32 vcc_hi, s66, 2
	s_add_u32 s28, s64, 0x80
	s_addc_u32 s29, s65, 0
	s_cmp_eq_u32 s85, s66
	s_cselect_b32 s66, s4, s28
	s_cselect_b32 s67, s5, s29
	s_cselect_b32 s69, s7, vcc_lo
	s_cselect_b32 s68, s6, s91
	s_add_i32 m0, s70, 0xc000
	v_lshl_add_u64 v[174:175], s[64:65], 0, v[158:159]
	global_load_lds_dwordx4 v[174:175], off
	v_lshl_add_u64 v[174:175], s[64:65], 0, v[160:161]
	s_add_i32 m0, s70, 0xe000
	s_nop 0
	global_load_lds_dwordx4 v[174:175], off
	s_waitcnt lgkmcnt(8)
	s_barrier
	s_setprio 1
	s_waitcnt lgkmcnt(7)
	v_mfma_f32_16x16x32_bf16 v[124:127], v[128:131], v[144:147], v[124:127]
	v_mfma_f32_16x16x32_bf16 v[120:123], v[136:139], v[144:147], v[120:123]
	s_waitcnt lgkmcnt(6)
	v_mfma_f32_16x16x32_bf16 v[108:111], v[128:131], v[162:165], v[108:111]
	v_mfma_f32_16x16x32_bf16 v[104:107], v[136:139], v[162:165], v[104:107]
	s_waitcnt lgkmcnt(5)
	v_mfma_f32_16x16x32_bf16 v[92:95], v[128:131], v[170:173], v[92:95]
	v_mfma_f32_16x16x32_bf16 v[88:91], v[136:139], v[170:173], v[88:91]
	s_waitcnt lgkmcnt(4)
	v_mfma_f32_16x16x32_bf16 v[76:79], v[128:131], v[196:199], v[76:79]
	v_mfma_f32_16x16x32_bf16 v[72:75], v[136:139], v[196:199], v[72:75]
	s_waitcnt lgkmcnt(3)
	v_mfma_f32_16x16x32_bf16 v[124:127], v[132:135], v[148:151], v[124:127]
	v_mfma_f32_16x16x32_bf16 v[120:123], v[140:143], v[148:151], v[120:123]
	s_waitcnt lgkmcnt(2)
	v_mfma_f32_16x16x32_bf16 v[108:111], v[132:135], v[166:169], v[108:111]
	v_mfma_f32_16x16x32_bf16 v[104:107], v[140:143], v[166:169], v[104:107]
	s_waitcnt lgkmcnt(1)
	v_mfma_f32_16x16x32_bf16 v[92:95], v[132:135], v[188:191], v[92:95]
	v_mfma_f32_16x16x32_bf16 v[88:91], v[140:143], v[188:191], v[88:91]
	s_waitcnt lgkmcnt(0)
	v_mfma_f32_16x16x32_bf16 v[76:79], v[132:135], v[200:203], v[76:79]
	v_mfma_f32_16x16x32_bf16 v[72:75], v[140:143], v[200:203], v[72:75]
	s_setprio 0
	s_barrier
	s_add_i32 s28, 0, 0x14000
	v_add_u32_e32 v174, s28, v194
	s_add_i32 s29, s88, s47
	ds_read_b128 v[204:207], v174
	ds_read_b128 v[208:211], v174 offset:1024
	ds_read_b128 v[212:215], v174 offset:2048
	ds_read_b128 v[232:235], v174 offset:3072
	v_lshl_add_u64 v[174:175], s[68:69], 0, v[176:177]
	s_mov_b32 m0, s29
	v_lshl_add_u64 v[216:217], s[68:69], 0, v[156:157]
	global_load_lds_dwordx4 v[174:175], off
	s_add_i32 m0, s29, 0x2000
	s_nop 0
	global_load_lds_dwordx4 v[216:217], off
	s_barrier
	s_setprio 1
	s_waitcnt lgkmcnt(3)
	v_mfma_f32_16x16x32_bf16 v[116:119], v[204:207], v[144:147], v[116:119]
	s_waitcnt lgkmcnt(1)
	v_mfma_f32_16x16x32_bf16 v[112:115], v[212:215], v[144:147], v[112:115]
	v_mfma_f32_16x16x32_bf16 v[100:103], v[204:207], v[162:165], v[100:103]
	v_mfma_f32_16x16x32_bf16 v[96:99], v[212:215], v[162:165], v[96:99]
	v_mfma_f32_16x16x32_bf16 v[84:87], v[204:207], v[170:173], v[84:87]
	v_mfma_f32_16x16x32_bf16 v[80:83], v[212:215], v[170:173], v[80:83]
	v_mfma_f32_16x16x32_bf16 v[68:71], v[204:207], v[196:199], v[68:71]
	v_mfma_f32_16x16x32_bf16 v[64:67], v[212:215], v[196:199], v[64:67]
	v_mfma_f32_16x16x32_bf16 v[116:119], v[208:211], v[148:151], v[116:119]
	s_waitcnt lgkmcnt(0)
	v_mfma_f32_16x16x32_bf16 v[112:115], v[232:235], v[148:151], v[112:115]
	v_mfma_f32_16x16x32_bf16 v[100:103], v[208:211], v[166:169], v[100:103]
	v_mfma_f32_16x16x32_bf16 v[96:99], v[232:235], v[166:169], v[96:99]
	v_mfma_f32_16x16x32_bf16 v[84:87], v[208:211], v[188:191], v[84:87]
	v_mfma_f32_16x16x32_bf16 v[80:83], v[232:235], v[188:191], v[80:83]
	v_mfma_f32_16x16x32_bf16 v[68:71], v[208:211], v[200:203], v[68:71]
	v_mfma_f32_16x16x32_bf16 v[64:67], v[232:235], v[200:203], v[64:67]
	s_setprio 0
	s_mov_b32 m0, s70
	v_lshl_add_u64 v[236:237], s[66:67], 0, v[152:153]
	s_barrier
	ds_read_b128 v[144:147], v195 offset:16384
	ds_read_b128 v[162:165], v195 offset:18432
	ds_read_b128 v[170:173], v195 offset:20480
	ds_read_b128 v[196:199], v195 offset:22528
	ds_read_b128 v[148:151], v195 offset:17408
	ds_read_b128 v[166:169], v195 offset:19456
	ds_read_b128 v[188:191], v195 offset:21504
	ds_read_b128 v[200:203], v195 offset:23552
	global_load_lds_dwordx4 v[236:237], off
	v_lshl_add_u64 v[238:239], s[66:67], 0, v[154:155]
	s_mov_b32 m0, s71
	s_nop 0
	global_load_lds_dwordx4 v[238:239], off
	s_barrier
	s_setprio 1
	s_waitcnt lgkmcnt(7)
	v_mfma_f32_16x16x32_bf16 v[60:63], v[128:131], v[144:147], v[60:63]
	v_mfma_f32_16x16x32_bf16 v[56:59], v[136:139], v[144:147], v[56:59]
	s_waitcnt lgkmcnt(6)
	v_mfma_f32_16x16x32_bf16 v[44:47], v[128:131], v[162:165], v[44:47]
	v_mfma_f32_16x16x32_bf16 v[40:43], v[136:139], v[162:165], v[40:43]
	s_waitcnt lgkmcnt(5)
	v_mfma_f32_16x16x32_bf16 v[28:31], v[128:131], v[170:173], v[28:31]
	v_mfma_f32_16x16x32_bf16 v[24:27], v[136:139], v[170:173], v[24:27]
	s_waitcnt lgkmcnt(4)
	v_mfma_f32_16x16x32_bf16 v[12:15], v[128:131], v[196:199], v[12:15]
	v_mfma_f32_16x16x32_bf16 v[8:11], v[136:139], v[196:199], v[8:11]
	s_waitcnt lgkmcnt(3)
	v_mfma_f32_16x16x32_bf16 v[60:63], v[132:135], v[148:151], v[60:63]
	v_mfma_f32_16x16x32_bf16 v[56:59], v[140:143], v[148:151], v[56:59]
	s_waitcnt lgkmcnt(2)
	v_mfma_f32_16x16x32_bf16 v[44:47], v[132:135], v[166:169], v[44:47]
	v_mfma_f32_16x16x32_bf16 v[40:43], v[140:143], v[166:169], v[40:43]
	s_waitcnt lgkmcnt(1)
	v_mfma_f32_16x16x32_bf16 v[28:31], v[132:135], v[188:191], v[28:31]
	v_mfma_f32_16x16x32_bf16 v[24:27], v[140:143], v[188:191], v[24:27]
	s_waitcnt lgkmcnt(0)
	v_mfma_f32_16x16x32_bf16 v[12:15], v[132:135], v[200:203], v[12:15]
	v_mfma_f32_16x16x32_bf16 v[8:11], v[140:143], v[200:203], v[8:11]
	s_setprio 0
	s_barrier
	s_add_u32 s68, s68, s58
	s_addc_u32 s69, s69, 0
	s_add_i32 s28, s28, s47
	v_lshl_add_u64 v[240:241], s[68:69], 0, v[176:177]
	s_mov_b32 m0, s28
	v_lshl_add_u64 v[242:243], s[68:69], 0, v[156:157]
	global_load_lds_dwordx4 v[240:241], off
	s_add_i32 m0, s28, 0x2000
	s_nop 0
	global_load_lds_dwordx4 v[242:243], off
	s_waitcnt vmcnt(6)
	s_barrier
	s_setprio 1
	v_mfma_f32_16x16x32_bf16 v[52:55], v[204:207], v[144:147], v[52:55]
	v_mfma_f32_16x16x32_bf16 v[48:51], v[212:215], v[144:147], v[48:51]
	v_mfma_f32_16x16x32_bf16 v[36:39], v[204:207], v[162:165], v[36:39]
	v_mfma_f32_16x16x32_bf16 v[32:35], v[212:215], v[162:165], v[32:35]
	v_mfma_f32_16x16x32_bf16 v[20:23], v[204:207], v[170:173], v[20:23]
	v_mfma_f32_16x16x32_bf16 v[16:19], v[212:215], v[170:173], v[16:19]
	v_mfma_f32_16x16x32_bf16 v[4:7], v[204:207], v[196:199], v[4:7]
	v_mfma_f32_16x16x32_bf16 v[0:3], v[212:215], v[196:199], v[0:3]
	v_mfma_f32_16x16x32_bf16 v[52:55], v[208:211], v[148:151], v[52:55]
	v_mfma_f32_16x16x32_bf16 v[48:51], v[232:235], v[148:151], v[48:51]
	v_mfma_f32_16x16x32_bf16 v[36:39], v[208:211], v[166:169], v[36:39]
	v_mfma_f32_16x16x32_bf16 v[32:35], v[232:235], v[166:169], v[32:35]
	v_mfma_f32_16x16x32_bf16 v[20:23], v[208:211], v[188:191], v[20:23]
	v_mfma_f32_16x16x32_bf16 v[16:19], v[232:235], v[188:191], v[16:19]
	v_mfma_f32_16x16x32_bf16 v[4:7], v[208:211], v[200:203], v[4:7]
	v_mfma_f32_16x16x32_bf16 v[0:3], v[232:235], v[200:203], v[0:3]
	s_setprio 0
	s_add_i32 s28, 0, 0x18000
	v_add_u32_e32 v140, s28, v194
	s_barrier
	ds_read_b128 v[128:131], v140
	ds_read_b128 v[132:135], v140 offset:1024
	ds_read_b128 v[136:139], v140 offset:2048
	ds_read_b128 v[140:143], v140 offset:3072
	ds_read_b128 v[144:147], v195 offset:32768
	ds_read_b128 v[162:165], v195 offset:34816
	ds_read_b128 v[170:173], v195 offset:36864
	ds_read_b128 v[196:199], v195 offset:38912
	ds_read_b128 v[148:151], v195 offset:33792
	ds_read_b128 v[166:169], v195 offset:35840
	ds_read_b128 v[188:191], v195 offset:37888
	ds_read_b128 v[200:203], v195 offset:39936
	s_add_u32 s66, s66, s58
	s_addc_u32 s67, s67, 0
	s_mov_b32 m0, s72
	v_lshl_add_u64 v[204:205], s[66:67], 0, v[152:153]
	global_load_lds_dwordx4 v[204:205], off
	v_lshl_add_u64 v[204:205], s[66:67], 0, v[154:155]
	s_mov_b32 m0, s73
	s_nop 0
	global_load_lds_dwordx4 v[204:205], off
	s_waitcnt lgkmcnt(8)
	s_barrier
	s_setprio 1
	s_waitcnt lgkmcnt(7)
	v_mfma_f32_16x16x32_bf16 v[124:127], v[128:131], v[144:147], v[124:127]
	v_mfma_f32_16x16x32_bf16 v[120:123], v[136:139], v[144:147], v[120:123]
	s_waitcnt lgkmcnt(6)
	v_mfma_f32_16x16x32_bf16 v[108:111], v[128:131], v[162:165], v[108:111]
	v_mfma_f32_16x16x32_bf16 v[104:107], v[136:139], v[162:165], v[104:107]
	s_waitcnt lgkmcnt(5)
	v_mfma_f32_16x16x32_bf16 v[92:95], v[128:131], v[170:173], v[92:95]
	v_mfma_f32_16x16x32_bf16 v[88:91], v[136:139], v[170:173], v[88:91]
	s_waitcnt lgkmcnt(4)
	v_mfma_f32_16x16x32_bf16 v[76:79], v[128:131], v[196:199], v[76:79]
	v_mfma_f32_16x16x32_bf16 v[72:75], v[136:139], v[196:199], v[72:75]
	s_waitcnt lgkmcnt(3)
	v_mfma_f32_16x16x32_bf16 v[124:127], v[132:135], v[148:151], v[124:127]
	v_mfma_f32_16x16x32_bf16 v[120:123], v[140:143], v[148:151], v[120:123]
	s_waitcnt lgkmcnt(2)
	v_mfma_f32_16x16x32_bf16 v[108:111], v[132:135], v[166:169], v[108:111]
	v_mfma_f32_16x16x32_bf16 v[104:107], v[140:143], v[166:169], v[104:107]
	s_waitcnt lgkmcnt(1)
	v_mfma_f32_16x16x32_bf16 v[92:95], v[132:135], v[188:191], v[92:95]
	v_mfma_f32_16x16x32_bf16 v[88:91], v[140:143], v[188:191], v[88:91]
	s_waitcnt lgkmcnt(0)
	v_mfma_f32_16x16x32_bf16 v[76:79], v[132:135], v[200:203], v[76:79]
	v_mfma_f32_16x16x32_bf16 v[72:75], v[140:143], v[200:203], v[72:75]
	s_setprio 0
	s_barrier
	s_add_i32 s29, 0, 0x1c000
	s_add_i32 s28, s28, s47
	v_add_u32_e32 v232, s29, v194
	v_lshl_add_u64 v[174:175], v[174:175], 0, s[40:41]
	s_mov_b32 m0, s28
	ds_read_b128 v[204:207], v232
	ds_read_b128 v[208:211], v232 offset:1024
	ds_read_b128 v[212:215], v232 offset:2048
	ds_read_b128 v[232:235], v232 offset:3072
	global_load_lds_dwordx4 v[174:175], off
	v_lshl_add_u64 v[174:175], v[216:217], 0, s[40:41]
	s_add_i32 m0, s28, 0x2000
	s_nop 0
	global_load_lds_dwordx4 v[174:175], off
	s_barrier
	s_setprio 1
	s_waitcnt lgkmcnt(3)
	v_mfma_f32_16x16x32_bf16 v[116:119], v[204:207], v[144:147], v[116:119]
	s_waitcnt lgkmcnt(1)
	v_mfma_f32_16x16x32_bf16 v[112:115], v[212:215], v[144:147], v[112:115]
	v_mfma_f32_16x16x32_bf16 v[100:103], v[204:207], v[162:165], v[100:103]
	v_mfma_f32_16x16x32_bf16 v[96:99], v[212:215], v[162:165], v[96:99]
	v_mfma_f32_16x16x32_bf16 v[84:87], v[204:207], v[170:173], v[84:87]
	v_mfma_f32_16x16x32_bf16 v[80:83], v[212:215], v[170:173], v[80:83]
	v_mfma_f32_16x16x32_bf16 v[68:71], v[204:207], v[196:199], v[68:71]
	v_mfma_f32_16x16x32_bf16 v[64:67], v[212:215], v[196:199], v[64:67]
	v_mfma_f32_16x16x32_bf16 v[116:119], v[208:211], v[148:151], v[116:119]
	s_waitcnt lgkmcnt(0)
	v_mfma_f32_16x16x32_bf16 v[112:115], v[232:235], v[148:151], v[112:115]
	v_mfma_f32_16x16x32_bf16 v[100:103], v[208:211], v[166:169], v[100:103]
	v_mfma_f32_16x16x32_bf16 v[96:99], v[232:235], v[166:169], v[96:99]
	v_mfma_f32_16x16x32_bf16 v[84:87], v[208:211], v[188:191], v[84:87]
	v_mfma_f32_16x16x32_bf16 v[80:83], v[232:235], v[188:191], v[80:83]
	v_mfma_f32_16x16x32_bf16 v[68:71], v[208:211], v[200:203], v[68:71]
	v_mfma_f32_16x16x32_bf16 v[64:67], v[232:235], v[200:203], v[64:67]
	s_setprio 0
	s_mov_b32 m0, s74
	v_lshl_add_u64 v[174:175], v[236:237], 0, s[40:41]
	s_barrier
	ds_read_b128 v[144:147], v195 offset:49152
	ds_read_b128 v[162:165], v195 offset:51200
	ds_read_b128 v[170:173], v195 offset:53248
	ds_read_b128 v[196:199], v195 offset:55296
	ds_read_b128 v[148:151], v195 offset:50176
	ds_read_b128 v[166:169], v195 offset:52224
	ds_read_b128 v[188:191], v195 offset:54272
	ds_read_b128 v[200:203], v195 offset:56320
	global_load_lds_dwordx4 v[174:175], off
	v_lshl_add_u64 v[174:175], v[238:239], 0, s[40:41]
	s_mov_b32 m0, s75
	s_nop 0
	global_load_lds_dwordx4 v[174:175], off
	s_barrier
	s_setprio 1
	s_waitcnt lgkmcnt(7)
	v_mfma_f32_16x16x32_bf16 v[60:63], v[128:131], v[144:147], v[60:63]
	v_mfma_f32_16x16x32_bf16 v[56:59], v[136:139], v[144:147], v[56:59]
	s_waitcnt lgkmcnt(6)
	v_mfma_f32_16x16x32_bf16 v[44:47], v[128:131], v[162:165], v[44:47]
	v_mfma_f32_16x16x32_bf16 v[40:43], v[136:139], v[162:165], v[40:43]
	s_waitcnt lgkmcnt(5)
	v_mfma_f32_16x16x32_bf16 v[28:31], v[128:131], v[170:173], v[28:31]
	v_mfma_f32_16x16x32_bf16 v[24:27], v[136:139], v[170:173], v[24:27]
	s_waitcnt lgkmcnt(4)
	v_mfma_f32_16x16x32_bf16 v[12:15], v[128:131], v[196:199], v[12:15]
	v_mfma_f32_16x16x32_bf16 v[8:11], v[136:139], v[196:199], v[8:11]
	s_waitcnt lgkmcnt(3)
	v_mfma_f32_16x16x32_bf16 v[60:63], v[132:135], v[148:151], v[60:63]
	v_mfma_f32_16x16x32_bf16 v[56:59], v[140:143], v[148:151], v[56:59]
	s_waitcnt lgkmcnt(2)
	v_mfma_f32_16x16x32_bf16 v[44:47], v[132:135], v[166:169], v[44:47]
	v_mfma_f32_16x16x32_bf16 v[40:43], v[140:143], v[166:169], v[40:43]
	s_waitcnt lgkmcnt(1)
	v_mfma_f32_16x16x32_bf16 v[28:31], v[132:135], v[188:191], v[28:31]
	v_mfma_f32_16x16x32_bf16 v[24:27], v[140:143], v[188:191], v[24:27]
	s_waitcnt lgkmcnt(0)
	v_mfma_f32_16x16x32_bf16 v[12:15], v[132:135], v[200:203], v[12:15]
	v_mfma_f32_16x16x32_bf16 v[8:11], v[140:143], v[200:203], v[8:11]
	s_setprio 0
	s_barrier
	s_add_i32 s28, s29, s47
	v_lshl_add_u64 v[128:129], v[240:241], 0, s[40:41]
	s_mov_b32 m0, s28
	s_nop 0
	global_load_lds_dwordx4 v[128:129], off
	v_lshl_add_u64 v[128:129], v[242:243], 0, s[40:41]
	s_add_i32 m0, s28, 0x2000
	s_nop 0
	global_load_lds_dwordx4 v[128:129], off
	s_waitcnt vmcnt(6)
	s_barrier
	s_setprio 1
	v_mfma_f32_16x16x32_bf16 v[52:55], v[204:207], v[144:147], v[52:55]
	v_mfma_f32_16x16x32_bf16 v[48:51], v[212:215], v[144:147], v[48:51]
	v_mfma_f32_16x16x32_bf16 v[36:39], v[204:207], v[162:165], v[36:39]
	v_mfma_f32_16x16x32_bf16 v[32:35], v[212:215], v[162:165], v[32:35]
	v_mfma_f32_16x16x32_bf16 v[20:23], v[204:207], v[170:173], v[20:23]
	v_mfma_f32_16x16x32_bf16 v[16:19], v[212:215], v[170:173], v[16:19]
	v_mfma_f32_16x16x32_bf16 v[4:7], v[204:207], v[196:199], v[4:7]
	v_mfma_f32_16x16x32_bf16 v[0:3], v[212:215], v[196:199], v[0:3]
	v_mfma_f32_16x16x32_bf16 v[52:55], v[208:211], v[148:151], v[52:55]
	v_mfma_f32_16x16x32_bf16 v[48:51], v[232:235], v[148:151], v[48:51]
	v_mfma_f32_16x16x32_bf16 v[36:39], v[208:211], v[166:169], v[36:39]
	v_mfma_f32_16x16x32_bf16 v[32:35], v[232:235], v[166:169], v[32:35]
	v_mfma_f32_16x16x32_bf16 v[20:23], v[208:211], v[188:191], v[20:23]
	v_mfma_f32_16x16x32_bf16 v[16:19], v[232:235], v[188:191], v[16:19]
	v_mfma_f32_16x16x32_bf16 v[4:7], v[208:211], v[200:203], v[4:7]
	v_mfma_f32_16x16x32_bf16 v[0:3], v[232:235], v[200:203], v[0:3]
	s_setprio 0
	s_add_u32 s64, s64, 0x100
	s_addc_u32 s65, s65, 0
	s_add_u32 s91, s91, 0x100
	s_addc_u32 vcc_lo, vcc_lo, 0
	s_cmp_lt_i32 vcc_hi, s76
	s_mov_b32 s66, vcc_hi
	s_barrier
	s_cbranch_scc1 .LBB0_1114
	s_lshl_b32 s28, s84, 8
	v_mov_b32_e32 v128, v193
	v_mov_b32_e32 v129, v192
	s_add_i32 s28, s28, s78
	s_lshl_b32 s64, s24, 2
	v_add_u32_e32 v166, s28, v129
	s_lshl_b32 s28, s24, 8
	s_or_b32 s28, s28, s79
	v_lshl_add_u32 v162, v128, 3, s28
	v_ashrrev_i32_e32 v163, 31, v162
	v_lshlrev_b64 v[204:205], 1, v[162:163]
	v_ashrrev_i32_e32 v167, 31, v166
	v_lshl_add_u64 v[164:165], s[12:13], 0, v[204:205]
	v_lshlrev_b64 v[206:207], 11, v[166:167]
	v_cmp_eq_u32_e32 vcc, 0, v128
	v_lshl_add_u64 v[128:129], v[164:165], 0, v[206:207]
	global_load_dwordx4 v[196:199], v[128:129], off
	global_load_dwordx4 v[200:203], v[128:129], off offset:256
	v_add_u32_e32 v188, 16, v166
	v_ashrrev_i32_e32 v189, 31, v188
	v_add_u32_e32 v172, 32, v166
	v_lshlrev_b64 v[190:191], 11, v[188:189]
	v_ashrrev_i32_e32 v173, 31, v172
	v_add_u32_e32 v168, 48, v166
	v_lshl_add_u64 v[128:129], v[164:165], 0, v[190:191]
	v_lshlrev_b64 v[174:175], 11, v[172:173]
	v_ashrrev_i32_e32 v169, 31, v168
	global_load_dwordx4 v[148:151], v[128:129], off
	global_load_dwordx4 v[144:147], v[128:129], off offset:256
	v_lshl_add_u64 v[128:129], v[164:165], 0, v[174:175]
	v_lshlrev_b64 v[170:171], 11, v[168:169]
	global_load_dwordx4 v[140:143], v[128:129], off
	global_load_dwordx4 v[136:139], v[128:129], off offset:256
	v_lshl_add_u64 v[128:129], v[164:165], 0, v[170:171]
	global_load_dwordx4 v[132:135], v[128:129], off
	s_nop 0
	global_load_dwordx4 v[128:131], v[128:129], off offset:256
	v_lshl_add_u64 v[206:207], s[12:13], 0, v[206:207]
	v_lshl_add_u64 v[204:205], v[206:207], 0, v[204:205]
	s_ashr_i32 s65, s64, 31
	s_waitcnt vmcnt(0)
	v_lshlrev_b32_e32 v208, 16, v196
	v_and_b32_e32 v209, 0xffff0000, v196
	v_lshlrev_b32_e32 v196, 16, v197
	v_and_b32_e32 v197, 0xffff0000, v197
	v_lshlrev_b32_e32 v210, 16, v198
	v_and_b32_e32 v211, 0xffff0000, v198
	v_lshlrev_b32_e32 v198, 16, v199
	v_and_b32_e32 v199, 0xffff0000, v199
	v_pk_fma_f32 v[126:127], s[62:63], v[126:127], v[196:197]
	v_pk_fma_f32 v[124:125], s[10:11], v[124:125], v[208:209]
	v_pk_fma_f32 v[196:197], s[62:63], v[122:123], v[198:199]
	v_pk_fma_f32 v[198:199], s[10:11], v[120:121], v[210:211]
	v_cvt_pk_bf16_f32 v120, v124, v125
	v_cvt_pk_bf16_f32 v121, v126, v127
	s_nop 0
	v_cvt_pk_bf16_f32 v122, v198, v199
	v_cvt_pk_bf16_f32 v123, v196, v197
	global_store_dwordx4 v[204:205], v[120:123], off
	s_nop 1
	v_pk_mul_f32 v[120:121], v[198:199], v[198:199]
	v_pk_mul_f32 v[122:123], v[196:197], v[196:197]
	v_pk_fma_f32 v[120:121], v[124:125], v[124:125], v[120:121]
	v_pk_fma_f32 v[122:123], v[126:127], v[126:127], v[122:123]
	v_add_f32_e32 v120, v120, v121
	v_add_f32_e32 v121, v122, v123
	v_add_f32_e32 v196, v120, v121
	v_lshlrev_b32_e32 v120, 16, v200
	v_and_b32_e32 v121, 0xffff0000, v200
	v_lshlrev_b32_e32 v122, 16, v201
	v_and_b32_e32 v123, 0xffff0000, v201
	v_lshlrev_b32_e32 v124, 16, v202
	v_and_b32_e32 v125, 0xffff0000, v202
	v_lshlrev_b32_e32 v126, 16, v203
	v_and_b32_e32 v127, 0xffff0000, v203
	v_pk_fma_f32 v[118:119], s[62:63], v[118:119], v[122:123]
	v_pk_fma_f32 v[116:117], s[10:11], v[116:117], v[120:121]
	v_pk_fma_f32 v[120:121], s[62:63], v[114:115], v[126:127]
	v_pk_fma_f32 v[122:123], s[10:11], v[112:113], v[124:125]
	v_cvt_pk_bf16_f32 v112, v116, v117
	v_cvt_pk_bf16_f32 v113, v118, v119
	s_nop 0
	v_cvt_pk_bf16_f32 v114, v122, v123
	v_cvt_pk_bf16_f32 v115, v120, v121
	global_store_dwordx4 v[204:205], v[112:115], off offset:256
	s_nop 1
	v_pk_mul_f32 v[112:113], v[122:123], v[122:123]
	v_pk_mul_f32 v[114:115], v[120:121], v[120:121]
	v_pk_fma_f32 v[112:113], v[116:117], v[116:117], v[112:113]
	v_pk_fma_f32 v[114:115], v[118:119], v[118:119], v[114:115]
	v_add_f32_e32 v112, v112, v113
	v_add_f32_e32 v113, v114, v115
	v_add_f32_e32 v112, v112, v113
	v_add_f32_e32 v112, v196, v112
	ds_bpermute_b32 v113, v219, v112
	s_waitcnt lgkmcnt(0)
	v_add_f32_e32 v112, v112, v113
	ds_bpermute_b32 v113, v218, v112
	s_and_saveexec_b64 s[66:67], vcc
	s_cbranch_execz .LBB0_1117
	v_lshlrev_b64 v[114:115], 6, v[166:167]
	v_lshl_add_u64 v[114:115], s[8:9], 0, v[114:115]
	v_lshl_add_u64 v[114:115], s[64:65], 2, v[114:115]
	s_lshl_b32 s24, s77, 2
	v_lshl_add_u64 v[114:115], v[114:115], 0, s[24:25]
	s_waitcnt lgkmcnt(0)
	v_add_f32_e32 v112, v112, v113
	global_store_dword v[114:115], v112, off

.LBB0_1282:
	s_add_i32 s82, 0, 0x10000
	v_add_u32_e32 v140, s82, v195
	ds_read_b128 v[128:131], v140
	ds_read_b128 v[132:135], v140 offset:1024
	ds_read_b128 v[136:139], v140 offset:2048
	ds_read_b128 v[140:143], v140 offset:3072
	ds_read_b128 v[144:147], v196
	ds_read_b128 v[162:165], v196 offset:2048
	ds_read_b128 v[170:173], v196 offset:4096
	ds_read_b128 v[198:201], v196 offset:6144
	ds_read_b128 v[148:151], v196 offset:1024
	ds_read_b128 v[166:169], v196 offset:3072
	ds_read_b128 v[188:191], v196 offset:5120
	ds_read_b128 v[202:205], v196 offset:7168
	s_add_i32 s81, s60, 2
	s_add_u32 s28, s58, 0x80
	s_addc_u32 s29, s59, 0
	s_cmp_eq_u32 s5, s60
	s_cselect_b32 s60, s56, s28
	s_cselect_b32 s61, s57, s29
	s_cselect_b32 s63, s3, s80
	s_cselect_b32 s62, s2, s21
	s_add_i32 m0, s66, 0xc000
	v_lshl_add_u64 v[174:175], s[58:59], 0, v[158:159]
	global_load_lds_dwordx4 v[174:175], off
	v_lshl_add_u64 v[174:175], s[58:59], 0, v[160:161]
	s_add_i32 m0, s66, 0xe000
	s_nop 0
	global_load_lds_dwordx4 v[174:175], off
	s_waitcnt lgkmcnt(8)
	s_barrier
	s_setprio 1
	s_waitcnt lgkmcnt(7)
	v_mfma_f32_16x16x32_bf16 v[124:127], v[128:131], v[144:147], v[124:127]
	v_mfma_f32_16x16x32_bf16 v[120:123], v[136:139], v[144:147], v[120:123]
	s_waitcnt lgkmcnt(6)
	v_mfma_f32_16x16x32_bf16 v[108:111], v[128:131], v[162:165], v[108:111]
	v_mfma_f32_16x16x32_bf16 v[104:107], v[136:139], v[162:165], v[104:107]
	s_waitcnt lgkmcnt(5)
	v_mfma_f32_16x16x32_bf16 v[92:95], v[128:131], v[170:173], v[92:95]
	v_mfma_f32_16x16x32_bf16 v[88:91], v[136:139], v[170:173], v[88:91]
	s_waitcnt lgkmcnt(4)
	v_mfma_f32_16x16x32_bf16 v[76:79], v[128:131], v[198:201], v[76:79]
	v_mfma_f32_16x16x32_bf16 v[72:75], v[136:139], v[198:201], v[72:75]
	s_waitcnt lgkmcnt(3)
	v_mfma_f32_16x16x32_bf16 v[124:127], v[132:135], v[148:151], v[124:127]
	v_mfma_f32_16x16x32_bf16 v[120:123], v[140:143], v[148:151], v[120:123]
	s_waitcnt lgkmcnt(2)
	v_mfma_f32_16x16x32_bf16 v[108:111], v[132:135], v[166:169], v[108:111]
	v_mfma_f32_16x16x32_bf16 v[104:107], v[140:143], v[166:169], v[104:107]
	s_waitcnt lgkmcnt(1)
	v_mfma_f32_16x16x32_bf16 v[92:95], v[132:135], v[188:191], v[92:95]
	v_mfma_f32_16x16x32_bf16 v[88:91], v[140:143], v[188:191], v[88:91]
	s_waitcnt lgkmcnt(0)
	v_mfma_f32_16x16x32_bf16 v[76:79], v[132:135], v[202:205], v[76:79]
	v_mfma_f32_16x16x32_bf16 v[72:75], v[140:143], v[202:205], v[72:75]
	s_setprio 0
	s_barrier
	s_add_i32 s28, 0, 0x14000
	v_add_u32_e32 v174, s28, v195
	s_add_i32 s29, s82, s65
	ds_read_b128 v[206:209], v174
	ds_read_b128 v[210:213], v174 offset:1024
	ds_read_b128 v[214:217], v174 offset:2048
	ds_read_b128 v[232:235], v174 offset:3072
	v_lshl_add_u64 v[174:175], s[62:63], 0, v[176:177]
	s_mov_b32 m0, s29
	v_lshl_add_u64 v[236:237], s[62:63], 0, v[156:157]
	global_load_lds_dwordx4 v[174:175], off
	s_add_i32 m0, s29, 0x2000
	s_nop 0
	global_load_lds_dwordx4 v[236:237], off
	s_barrier
	s_setprio 1
	s_waitcnt lgkmcnt(3)
	v_mfma_f32_16x16x32_bf16 v[116:119], v[206:209], v[144:147], v[116:119]
	s_waitcnt lgkmcnt(1)
	v_mfma_f32_16x16x32_bf16 v[112:115], v[214:217], v[144:147], v[112:115]
	v_mfma_f32_16x16x32_bf16 v[100:103], v[206:209], v[162:165], v[100:103]
	v_mfma_f32_16x16x32_bf16 v[96:99], v[214:217], v[162:165], v[96:99]
	v_mfma_f32_16x16x32_bf16 v[84:87], v[206:209], v[170:173], v[84:87]
	v_mfma_f32_16x16x32_bf16 v[80:83], v[214:217], v[170:173], v[80:83]
	v_mfma_f32_16x16x32_bf16 v[68:71], v[206:209], v[198:201], v[68:71]
	v_mfma_f32_16x16x32_bf16 v[64:67], v[214:217], v[198:201], v[64:67]
	v_mfma_f32_16x16x32_bf16 v[116:119], v[210:213], v[148:151], v[116:119]
	s_waitcnt lgkmcnt(0)
	v_mfma_f32_16x16x32_bf16 v[112:115], v[232:235], v[148:151], v[112:115]
	v_mfma_f32_16x16x32_bf16 v[100:103], v[210:213], v[166:169], v[100:103]
	v_mfma_f32_16x16x32_bf16 v[96:99], v[232:235], v[166:169], v[96:99]
	v_mfma_f32_16x16x32_bf16 v[84:87], v[210:213], v[188:191], v[84:87]
	v_mfma_f32_16x16x32_bf16 v[80:83], v[232:235], v[188:191], v[80:83]
	v_mfma_f32_16x16x32_bf16 v[68:71], v[210:213], v[202:205], v[68:71]
	v_mfma_f32_16x16x32_bf16 v[64:67], v[232:235], v[202:205], v[64:67]
	s_setprio 0
	s_mov_b32 m0, s66
	v_lshl_add_u64 v[238:239], s[60:61], 0, v[152:153]
	s_barrier
	ds_read_b128 v[144:147], v196 offset:16384
	ds_read_b128 v[162:165], v196 offset:18432
	ds_read_b128 v[170:173], v196 offset:20480
	ds_read_b128 v[198:201], v196 offset:22528
	ds_read_b128 v[148:151], v196 offset:17408
	ds_read_b128 v[166:169], v196 offset:19456
	ds_read_b128 v[188:191], v196 offset:21504
	ds_read_b128 v[202:205], v196 offset:23552
	global_load_lds_dwordx4 v[238:239], off
	v_lshl_add_u64 v[240:241], s[60:61], 0, v[154:155]
	s_mov_b32 m0, s67
	s_nop 0
	global_load_lds_dwordx4 v[240:241], off
	s_barrier
	s_setprio 1
	s_waitcnt lgkmcnt(7)
	v_mfma_f32_16x16x32_bf16 v[60:63], v[128:131], v[144:147], v[60:63]
	v_mfma_f32_16x16x32_bf16 v[56:59], v[136:139], v[144:147], v[56:59]
	s_waitcnt lgkmcnt(6)
	v_mfma_f32_16x16x32_bf16 v[44:47], v[128:131], v[162:165], v[44:47]
	v_mfma_f32_16x16x32_bf16 v[40:43], v[136:139], v[162:165], v[40:43]
	s_waitcnt lgkmcnt(5)
	v_mfma_f32_16x16x32_bf16 v[28:31], v[128:131], v[170:173], v[28:31]
	v_mfma_f32_16x16x32_bf16 v[24:27], v[136:139], v[170:173], v[24:27]
	s_waitcnt lgkmcnt(4)
	v_mfma_f32_16x16x32_bf16 v[12:15], v[128:131], v[198:201], v[12:15]
	v_mfma_f32_16x16x32_bf16 v[8:11], v[136:139], v[198:201], v[8:11]
	s_waitcnt lgkmcnt(3)
	v_mfma_f32_16x16x32_bf16 v[60:63], v[132:135], v[148:151], v[60:63]
	v_mfma_f32_16x16x32_bf16 v[56:59], v[140:143], v[148:151], v[56:59]
	s_waitcnt lgkmcnt(2)
	v_mfma_f32_16x16x32_bf16 v[44:47], v[132:135], v[166:169], v[44:47]
	v_mfma_f32_16x16x32_bf16 v[40:43], v[140:143], v[166:169], v[40:43]
	s_waitcnt lgkmcnt(1)
	v_mfma_f32_16x16x32_bf16 v[28:31], v[132:135], v[188:191], v[28:31]
	v_mfma_f32_16x16x32_bf16 v[24:27], v[140:143], v[188:191], v[24:27]
	s_waitcnt lgkmcnt(0)
	v_mfma_f32_16x16x32_bf16 v[12:15], v[132:135], v[202:205], v[12:15]
	v_mfma_f32_16x16x32_bf16 v[8:11], v[140:143], v[202:205], v[8:11]
	s_setprio 0
	s_barrier
	s_add_u32 s62, s62, s4
	s_addc_u32 s63, s63, 0
	s_add_i32 s28, s28, s65
	v_lshl_add_u64 v[242:243], s[62:63], 0, v[176:177]
	s_mov_b32 m0, s28
	v_lshl_add_u64 v[244:245], s[62:63], 0, v[156:157]
	global_load_lds_dwordx4 v[242:243], off
	s_add_i32 m0, s28, 0x2000
	s_nop 0
	global_load_lds_dwordx4 v[244:245], off
	s_waitcnt vmcnt(6)
	s_barrier
	s_setprio 1
	v_mfma_f32_16x16x32_bf16 v[52:55], v[206:209], v[144:147], v[52:55]
	v_mfma_f32_16x16x32_bf16 v[48:51], v[214:217], v[144:147], v[48:51]
	v_mfma_f32_16x16x32_bf16 v[36:39], v[206:209], v[162:165], v[36:39]
	v_mfma_f32_16x16x32_bf16 v[32:35], v[214:217], v[162:165], v[32:35]
	v_mfma_f32_16x16x32_bf16 v[20:23], v[206:209], v[170:173], v[20:23]
	v_mfma_f32_16x16x32_bf16 v[16:19], v[214:217], v[170:173], v[16:19]
	v_mfma_f32_16x16x32_bf16 v[4:7], v[206:209], v[198:201], v[4:7]
	v_mfma_f32_16x16x32_bf16 v[0:3], v[214:217], v[198:201], v[0:3]
	v_mfma_f32_16x16x32_bf16 v[52:55], v[210:213], v[148:151], v[52:55]
	v_mfma_f32_16x16x32_bf16 v[48:51], v[232:235], v[148:151], v[48:51]
	v_mfma_f32_16x16x32_bf16 v[36:39], v[210:213], v[166:169], v[36:39]
	v_mfma_f32_16x16x32_bf16 v[32:35], v[232:235], v[166:169], v[32:35]
	v_mfma_f32_16x16x32_bf16 v[20:23], v[210:213], v[188:191], v[20:23]
	v_mfma_f32_16x16x32_bf16 v[16:19], v[232:235], v[188:191], v[16:19]
	v_mfma_f32_16x16x32_bf16 v[4:7], v[210:213], v[202:205], v[4:7]
	v_mfma_f32_16x16x32_bf16 v[0:3], v[232:235], v[202:205], v[0:3]
	s_setprio 0
	s_add_i32 s28, 0, 0x18000
	v_add_u32_e32 v140, s28, v195
	s_barrier
	ds_read_b128 v[128:131], v140
	ds_read_b128 v[132:135], v140 offset:1024
	ds_read_b128 v[136:139], v140 offset:2048
	ds_read_b128 v[140:143], v140 offset:3072
	ds_read_b128 v[144:147], v196 offset:32768
	ds_read_b128 v[162:165], v196 offset:34816
	ds_read_b128 v[170:173], v196 offset:36864
	ds_read_b128 v[198:201], v196 offset:38912
	ds_read_b128 v[148:151], v196 offset:33792
	ds_read_b128 v[166:169], v196 offset:35840
	ds_read_b128 v[188:191], v196 offset:37888
	ds_read_b128 v[202:205], v196 offset:39936
	s_add_u32 s60, s60, s4
	s_addc_u32 s61, s61, 0
	s_mov_b32 m0, s68
	v_lshl_add_u64 v[206:207], s[60:61], 0, v[152:153]
	global_load_lds_dwordx4 v[206:207], off
	v_lshl_add_u64 v[206:207], s[60:61], 0, v[154:155]
	s_mov_b32 m0, s69
	s_nop 0
	global_load_lds_dwordx4 v[206:207], off
	s_waitcnt lgkmcnt(8)
	s_barrier
	s_setprio 1
	s_waitcnt lgkmcnt(7)
	v_mfma_f32_16x16x32_bf16 v[124:127], v[128:131], v[144:147], v[124:127]
	v_mfma_f32_16x16x32_bf16 v[120:123], v[136:139], v[144:147], v[120:123]
	s_waitcnt lgkmcnt(6)
	v_mfma_f32_16x16x32_bf16 v[108:111], v[128:131], v[162:165], v[108:111]
	v_mfma_f32_16x16x32_bf16 v[104:107], v[136:139], v[162:165], v[104:107]
	s_waitcnt lgkmcnt(5)
	v_mfma_f32_16x16x32_bf16 v[92:95], v[128:131], v[170:173], v[92:95]
	v_mfma_f32_16x16x32_bf16 v[88:91], v[136:139], v[170:173], v[88:91]
	s_waitcnt lgkmcnt(4)
	v_mfma_f32_16x16x32_bf16 v[76:79], v[128:131], v[198:201], v[76:79]
	v_mfma_f32_16x16x32_bf16 v[72:75], v[136:139], v[198:201], v[72:75]
	s_waitcnt lgkmcnt(3)
	v_mfma_f32_16x16x32_bf16 v[124:127], v[132:135], v[148:151], v[124:127]
	v_mfma_f32_16x16x32_bf16 v[120:123], v[140:143], v[148:151], v[120:123]
	s_waitcnt lgkmcnt(2)
	v_mfma_f32_16x16x32_bf16 v[108:111], v[132:135], v[166:169], v[108:111]
	v_mfma_f32_16x16x32_bf16 v[104:107], v[140:143], v[166:169], v[104:107]
	s_waitcnt lgkmcnt(1)
	v_mfma_f32_16x16x32_bf16 v[92:95], v[132:135], v[188:191], v[92:95]
	v_mfma_f32_16x16x32_bf16 v[88:91], v[140:143], v[188:191], v[88:91]
	s_waitcnt lgkmcnt(0)
	v_mfma_f32_16x16x32_bf16 v[76:79], v[132:135], v[202:205], v[76:79]
	v_mfma_f32_16x16x32_bf16 v[72:75], v[140:143], v[202:205], v[72:75]
	s_setprio 0
	s_barrier
	s_add_i32 s29, 0, 0x1c000
	s_add_i32 s28, s28, s65
	v_add_u32_e32 v197, s29, v195
	v_lshl_add_u64 v[174:175], v[174:175], 0, s[40:41]
	s_mov_b32 m0, s28
	ds_read_b128 v[206:209], v197
	ds_read_b128 v[210:213], v197 offset:1024
	ds_read_b128 v[214:217], v197 offset:2048
	ds_read_b128 v[232:235], v197 offset:3072
	global_load_lds_dwordx4 v[174:175], off
	v_lshl_add_u64 v[174:175], v[236:237], 0, s[40:41]
	s_add_i32 m0, s28, 0x2000
	s_nop 0
	global_load_lds_dwordx4 v[174:175], off
	s_barrier
	s_setprio 1
	s_waitcnt lgkmcnt(3)
	v_mfma_f32_16x16x32_bf16 v[116:119], v[206:209], v[144:147], v[116:119]
	s_waitcnt lgkmcnt(1)
	v_mfma_f32_16x16x32_bf16 v[112:115], v[214:217], v[144:147], v[112:115]
	v_mfma_f32_16x16x32_bf16 v[100:103], v[206:209], v[162:165], v[100:103]
	v_mfma_f32_16x16x32_bf16 v[96:99], v[214:217], v[162:165], v[96:99]
	v_mfma_f32_16x16x32_bf16 v[84:87], v[206:209], v[170:173], v[84:87]
	v_mfma_f32_16x16x32_bf16 v[80:83], v[214:217], v[170:173], v[80:83]
	v_mfma_f32_16x16x32_bf16 v[68:71], v[206:209], v[198:201], v[68:71]
	v_mfma_f32_16x16x32_bf16 v[64:67], v[214:217], v[198:201], v[64:67]
	v_mfma_f32_16x16x32_bf16 v[116:119], v[210:213], v[148:151], v[116:119]
	s_waitcnt lgkmcnt(0)
	v_mfma_f32_16x16x32_bf16 v[112:115], v[232:235], v[148:151], v[112:115]
	v_mfma_f32_16x16x32_bf16 v[100:103], v[210:213], v[166:169], v[100:103]
	v_mfma_f32_16x16x32_bf16 v[96:99], v[232:235], v[166:169], v[96:99]
	v_mfma_f32_16x16x32_bf16 v[84:87], v[210:213], v[188:191], v[84:87]
	v_mfma_f32_16x16x32_bf16 v[80:83], v[232:235], v[188:191], v[80:83]
	v_mfma_f32_16x16x32_bf16 v[68:71], v[210:213], v[202:205], v[68:71]
	v_mfma_f32_16x16x32_bf16 v[64:67], v[232:235], v[202:205], v[64:67]
	s_setprio 0
	s_mov_b32 m0, s71
	v_lshl_add_u64 v[174:175], v[238:239], 0, s[40:41]
	s_barrier
	ds_read_b128 v[144:147], v196 offset:49152
	ds_read_b128 v[162:165], v196 offset:51200
	ds_read_b128 v[170:173], v196 offset:53248
	ds_read_b128 v[198:201], v196 offset:55296
	ds_read_b128 v[148:151], v196 offset:50176
	ds_read_b128 v[166:169], v196 offset:52224
	ds_read_b128 v[188:191], v196 offset:54272
	ds_read_b128 v[202:205], v196 offset:56320
	global_load_lds_dwordx4 v[174:175], off
	v_lshl_add_u64 v[174:175], v[240:241], 0, s[40:41]
	s_mov_b32 m0, s72
	s_nop 0
	global_load_lds_dwordx4 v[174:175], off
	s_barrier
	s_setprio 1
	s_waitcnt lgkmcnt(7)
	v_mfma_f32_16x16x32_bf16 v[60:63], v[128:131], v[144:147], v[60:63]
	v_mfma_f32_16x16x32_bf16 v[56:59], v[136:139], v[144:147], v[56:59]
	s_waitcnt lgkmcnt(6)
	v_mfma_f32_16x16x32_bf16 v[44:47], v[128:131], v[162:165], v[44:47]
	v_mfma_f32_16x16x32_bf16 v[40:43], v[136:139], v[162:165], v[40:43]
	s_waitcnt lgkmcnt(5)
	v_mfma_f32_16x16x32_bf16 v[28:31], v[128:131], v[170:173], v[28:31]
	v_mfma_f32_16x16x32_bf16 v[24:27], v[136:139], v[170:173], v[24:27]
	s_waitcnt lgkmcnt(4)
	v_mfma_f32_16x16x32_bf16 v[12:15], v[128:131], v[198:201], v[12:15]
	v_mfma_f32_16x16x32_bf16 v[8:11], v[136:139], v[198:201], v[8:11]
	s_waitcnt lgkmcnt(3)
	v_mfma_f32_16x16x32_bf16 v[60:63], v[132:135], v[148:151], v[60:63]
	v_mfma_f32_16x16x32_bf16 v[56:59], v[140:143], v[148:151], v[56:59]
	s_waitcnt lgkmcnt(2)
	v_mfma_f32_16x16x32_bf16 v[44:47], v[132:135], v[166:169], v[44:47]
	v_mfma_f32_16x16x32_bf16 v[40:43], v[140:143], v[166:169], v[40:43]
	s_waitcnt lgkmcnt(1)
	v_mfma_f32_16x16x32_bf16 v[28:31], v[132:135], v[188:191], v[28:31]
	v_mfma_f32_16x16x32_bf16 v[24:27], v[140:143], v[188:191], v[24:27]
	s_waitcnt lgkmcnt(0)
	v_mfma_f32_16x16x32_bf16 v[12:15], v[132:135], v[202:205], v[12:15]
	v_mfma_f32_16x16x32_bf16 v[8:11], v[140:143], v[202:205], v[8:11]
	s_setprio 0
	s_barrier
	s_add_i32 s28, s29, s65
	v_lshl_add_u64 v[128:129], v[242:243], 0, s[40:41]
	s_mov_b32 m0, s28
	s_nop 0
	global_load_lds_dwordx4 v[128:129], off
	v_lshl_add_u64 v[128:129], v[244:245], 0, s[40:41]
	s_add_i32 m0, s28, 0x2000
	s_nop 0
	global_load_lds_dwordx4 v[128:129], off
	s_waitcnt vmcnt(6)
	s_barrier
	s_setprio 1
	v_mfma_f32_16x16x32_bf16 v[52:55], v[206:209], v[144:147], v[52:55]
	v_mfma_f32_16x16x32_bf16 v[48:51], v[214:217], v[144:147], v[48:51]
	v_mfma_f32_16x16x32_bf16 v[36:39], v[206:209], v[162:165], v[36:39]
	v_mfma_f32_16x16x32_bf16 v[32:35], v[214:217], v[162:165], v[32:35]
	v_mfma_f32_16x16x32_bf16 v[20:23], v[206:209], v[170:173], v[20:23]
	v_mfma_f32_16x16x32_bf16 v[16:19], v[214:217], v[170:173], v[16:19]
	v_mfma_f32_16x16x32_bf16 v[4:7], v[206:209], v[198:201], v[4:7]
	v_mfma_f32_16x16x32_bf16 v[0:3], v[214:217], v[198:201], v[0:3]
	v_mfma_f32_16x16x32_bf16 v[52:55], v[210:213], v[148:151], v[52:55]
	v_mfma_f32_16x16x32_bf16 v[48:51], v[232:235], v[148:151], v[48:51]
	v_mfma_f32_16x16x32_bf16 v[36:39], v[210:213], v[166:169], v[36:39]
	v_mfma_f32_16x16x32_bf16 v[32:35], v[232:235], v[166:169], v[32:35]
	v_mfma_f32_16x16x32_bf16 v[20:23], v[210:213], v[188:191], v[20:23]
	v_mfma_f32_16x16x32_bf16 v[16:19], v[232:235], v[188:191], v[16:19]
	v_mfma_f32_16x16x32_bf16 v[4:7], v[210:213], v[202:205], v[4:7]
	v_mfma_f32_16x16x32_bf16 v[0:3], v[232:235], v[202:205], v[0:3]
	s_setprio 0
	s_add_u32 s58, s58, 0x100
	s_addc_u32 s59, s59, 0
	s_add_u32 s21, s21, 0x100
	s_addc_u32 s80, s80, 0
	s_cmp_ge_i32 s81, s79
	s_mov_b32 s60, s81
	s_barrier
	s_cbranch_scc0 .LBB0_1282
	s_cmp_gt_i32 s24, -1
	s_mov_b64 s[58:59], -1
	s_cbranch_scc0 .LBB0_1285
	s_lshl_b64 s[58:59], s[24:25], 17
	v_mov_b32_e32 v128, v231
	s_add_u32 s58, s37, s58
	s_addc_u32 s59, s46, s59
	v_ashrrev_i32_e32 v129, 31, v128
	v_lshl_add_u64 v[128:129], v[128:129], 4, s[58:59]
	v_add_co_u32_e32 v134, vcc, s36, v128
	v_cvt_pk_bf16_f32 v130, v124, v125
	v_cvt_pk_bf16_f32 v131, v126, v127
	v_cvt_pk_bf16_f32 v132, v120, v121
	v_cvt_pk_bf16_f32 v133, v122, v123
	s_nop 1
	v_addc_co_u32_e32 v135, vcc, 0, v129, vcc
	s_movk_i32 s5, 0x4000
	global_store_dwordx4 v[128:129], v[130:133], off
	s_mov_b64 s[58:59], 0
	s_nop 0
	v_cvt_pk_bf16_f32 v130, v108, v109
	v_cvt_pk_bf16_f32 v131, v110, v111
	v_cvt_pk_bf16_f32 v132, v104, v105
	v_cvt_pk_bf16_f32 v133, v106, v107
	global_store_dwordx4 v[134:135], v[130:133], off
	v_add_co_u32_e32 v134, vcc, s5, v128
	s_movk_i32 s5, 0x6000
	s_nop 0
	v_addc_co_u32_e32 v135, vcc, 0, v129, vcc
	v_cvt_pk_bf16_f32 v130, v92, v93
	v_cvt_pk_bf16_f32 v131, v94, v95
	v_cvt_pk_bf16_f32 v132, v88, v89
	v_cvt_pk_bf16_f32 v133, v90, v91
	global_store_dwordx4 v[134:135], v[130:133], off
	v_add_co_u32_e32 v134, vcc, s5, v128
	s_nop 0
	v_cvt_pk_bf16_f32 v130, v76, v77
	v_cvt_pk_bf16_f32 v131, v78, v79
	v_cvt_pk_bf16_f32 v132, v72, v73
	v_cvt_pk_bf16_f32 v133, v74, v75
	s_nop 0
	v_addc_co_u32_e32 v135, vcc, 0, v129, vcc
	global_store_dwordx4 v[134:135], v[130:133], off
	v_add_co_u32_e32 v134, vcc, s92, v128
	s_mov_b32 s5, 0xa000
	s_nop 0
	v_addc_co_u32_e32 v135, vcc, 0, v129, vcc
	v_cvt_pk_bf16_f32 v130, v116, v117
	v_cvt_pk_bf16_f32 v131, v118, v119
	v_cvt_pk_bf16_f32 v132, v112, v113
	v_cvt_pk_bf16_f32 v133, v114, v115
	global_store_dwordx4 v[134:135], v[130:133], off
	v_add_co_u32_e32 v134, vcc, s5, v128
	s_mov_b32 s5, 0xc000
	s_nop 0
	v_addc_co_u32_e32 v135, vcc, 0, v129, vcc
	v_cvt_pk_bf16_f32 v130, v100, v101
	v_cvt_pk_bf16_f32 v131, v102, v103
	v_cvt_pk_bf16_f32 v132, v96, v97
	v_cvt_pk_bf16_f32 v133, v98, v99
	global_store_dwordx4 v[134:135], v[130:133], off
	v_add_co_u32_e32 v134, vcc, s5, v128
	s_mov_b32 s5, 0xe000
	s_nop 0
	v_addc_co_u32_e32 v135, vcc, 0, v129, vcc
	v_cvt_pk_bf16_f32 v130, v84, v85
	v_cvt_pk_bf16_f32 v131, v86, v87
	v_cvt_pk_bf16_f32 v132, v80, v81
	v_cvt_pk_bf16_f32 v133, v82, v83
	global_store_dwordx4 v[134:135], v[130:133], off
	v_add_co_u32_e32 v134, vcc, s5, v128
	s_mov_b32 s5, 0x10000
	s_nop 0
	v_addc_co_u32_e32 v135, vcc, 0, v129, vcc
	v_cvt_pk_bf16_f32 v130, v68, v69
	v_cvt_pk_bf16_f32 v131, v70, v71
	v_cvt_pk_bf16_f32 v132, v64, v65
	v_cvt_pk_bf16_f32 v133, v66, v67
	global_store_dwordx4 v[134:135], v[130:133], off
	v_add_co_u32_e32 v134, vcc, s5, v128
	s_mov_b32 s5, 0x12000
	s_nop 0
	v_addc_co_u32_e32 v135, vcc, 0, v129, vcc
	v_cvt_pk_bf16_f32 v130, v60, v61
	v_cvt_pk_bf16_f32 v131, v62, v63
	v_cvt_pk_bf16_f32 v132, v56, v57
	v_cvt_pk_bf16_f32 v133, v58, v59
	global_store_dwordx4 v[134:135], v[130:133], off
	v_add_co_u32_e32 v134, vcc, s5, v128
	s_mov_b32 s5, 0x14000
	s_nop 0
	v_addc_co_u32_e32 v135, vcc, 0, v129, vcc
	v_cvt_pk_bf16_f32 v130, v44, v45
	v_cvt_pk_bf16_f32 v131, v46, v47
	v_cvt_pk_bf16_f32 v132, v40, v41
	v_cvt_pk_bf16_f32 v133, v42, v43
	global_store_dwordx4 v[134:135], v[130:133], off
	v_add_co_u32_e32 v134, vcc, s5, v128
	s_mov_b32 s5, 0x16000
	s_nop 0
	v_addc_co_u32_e32 v135, vcc, 0, v129, vcc
	v_cvt_pk_bf16_f32 v130, v28, v29
	v_cvt_pk_bf16_f32 v131, v30, v31
	v_cvt_pk_bf16_f32 v132, v24, v25
	v_cvt_pk_bf16_f32 v133, v26, v27
	global_store_dwordx4 v[134:135], v[130:133], off
	v_add_co_u32_e32 v134, vcc, s5, v128
	s_mov_b32 s5, 0x18000
	s_nop 0
	v_addc_co_u32_e32 v135, vcc, 0, v129, vcc
	v_cvt_pk_bf16_f32 v130, v12, v13
	v_cvt_pk_bf16_f32 v131, v14, v15
	v_cvt_pk_bf16_f32 v132, v8, v9
	v_cvt_pk_bf16_f32 v133, v10, v11
	global_store_dwordx4 v[134:135], v[130:133], off
	v_add_co_u32_e32 v134, vcc, s5, v128
	s_mov_b32 s5, 0x1a000
	s_nop 0
	v_addc_co_u32_e32 v135, vcc, 0, v129, vcc
	v_cvt_pk_bf16_f32 v130, v52, v53
	v_cvt_pk_bf16_f32 v131, v54, v55
	v_cvt_pk_bf16_f32 v132, v48, v49
	v_cvt_pk_bf16_f32 v133, v50, v51
	global_store_dwordx4 v[134:135], v[130:133], off
	v_add_co_u32_e32 v134, vcc, s5, v128
	s_mov_b32 s5, 0x1c000
	s_nop 0
	v_addc_co_u32_e32 v135, vcc, 0, v129, vcc
	v_cvt_pk_bf16_f32 v130, v36, v37
	v_cvt_pk_bf16_f32 v131, v38, v39
	v_cvt_pk_bf16_f32 v132, v32, v33
	v_cvt_pk_bf16_f32 v133, v34, v35
	global_store_dwordx4 v[134:135], v[130:133], off
	v_add_co_u32_e32 v134, vcc, s5, v128
	s_nop 0
	v_cvt_pk_bf16_f32 v130, v20, v21
	v_cvt_pk_bf16_f32 v131, v22, v23
	v_cvt_pk_bf16_f32 v132, v16, v17
	v_cvt_pk_bf16_f32 v133, v18, v19
	s_nop 0
	v_addc_co_u32_e32 v135, vcc, 0, v129, vcc
	v_add_co_u32_e32 v128, vcc, 0x1e000, v128
	global_store_dwordx4 v[134:135], v[130:133], off
	s_nop 0
	v_addc_co_u32_e32 v129, vcc, 0, v129, vcc
	v_cvt_pk_bf16_f32 v130, v4, v5
	v_cvt_pk_bf16_f32 v131, v6, v7
	v_cvt_pk_bf16_f32 v132, v0, v1
	v_cvt_pk_bf16_f32 v133, v2, v3
	global_store_dwordx4 v[128:129], v[130:133], off

.LBB0_1436:
	s_add_i32 s71, 0, 0x10000
	v_add_u32_e32 v140, s71, v200
	ds_read_b128 v[128:131], v140
	ds_read_b128 v[132:135], v140 offset:1024
	ds_read_b128 v[136:139], v140 offset:2048
	ds_read_b128 v[140:143], v140 offset:3072
	ds_read_b128 v[144:147], v201
	ds_read_b128 v[152:155], v201 offset:2048
	ds_read_b128 v[170:173], v201 offset:4096
	ds_read_b128 v[192:195], v201 offset:6144
	ds_read_b128 v[148:151], v201 offset:1024
	ds_read_b128 v[166:169], v201 offset:3072
	ds_read_b128 v[188:191], v201 offset:5120
	ds_read_b128 v[202:205], v201 offset:7168
	s_add_u32 s28, s6, 0xfffc0080
	s_addc_u32 s29, s7, -1
	s_cmp_eq_u32 s70, 12
	s_cselect_b32 s53, s17, s29
	s_cselect_b32 s52, s66, s28
	s_cselect_b32 s51, s13, s69
	s_cselect_b32 s50, s67, s68
	s_add_i32 m0, s56, 0xc000
	v_lshl_add_u64 v[174:175], s[6:7], 0, v[162:163]
	global_load_lds_dwordx4 v[174:175], off
	v_lshl_add_u64 v[174:175], s[6:7], 0, v[164:165]
	s_add_i32 m0, s56, 0xe000
	s_nop 0
	global_load_lds_dwordx4 v[174:175], off
	s_waitcnt lgkmcnt(8)
	s_barrier
	s_setprio 1
	s_waitcnt lgkmcnt(7)
	v_mfma_f32_16x16x32_bf16 v[124:127], v[128:131], v[144:147], v[124:127]
	v_mfma_f32_16x16x32_bf16 v[116:119], v[136:139], v[144:147], v[116:119]
	s_waitcnt lgkmcnt(6)
	v_mfma_f32_16x16x32_bf16 v[108:111], v[128:131], v[152:155], v[108:111]
	v_mfma_f32_16x16x32_bf16 v[100:103], v[136:139], v[152:155], v[100:103]
	s_waitcnt lgkmcnt(5)
	v_mfma_f32_16x16x32_bf16 v[92:95], v[128:131], v[170:173], v[92:95]
	v_mfma_f32_16x16x32_bf16 v[84:87], v[136:139], v[170:173], v[84:87]
	s_waitcnt lgkmcnt(4)
	v_mfma_f32_16x16x32_bf16 v[76:79], v[128:131], v[192:195], v[76:79]
	v_mfma_f32_16x16x32_bf16 v[68:71], v[136:139], v[192:195], v[68:71]
	s_waitcnt lgkmcnt(3)
	v_mfma_f32_16x16x32_bf16 v[124:127], v[132:135], v[148:151], v[124:127]
	v_mfma_f32_16x16x32_bf16 v[116:119], v[140:143], v[148:151], v[116:119]
	s_waitcnt lgkmcnt(2)
	v_mfma_f32_16x16x32_bf16 v[108:111], v[132:135], v[166:169], v[108:111]
	v_mfma_f32_16x16x32_bf16 v[100:103], v[140:143], v[166:169], v[100:103]
	s_waitcnt lgkmcnt(1)
	v_mfma_f32_16x16x32_bf16 v[92:95], v[132:135], v[188:191], v[92:95]
	v_mfma_f32_16x16x32_bf16 v[84:87], v[140:143], v[188:191], v[84:87]
	s_waitcnt lgkmcnt(0)
	v_mfma_f32_16x16x32_bf16 v[76:79], v[132:135], v[202:205], v[76:79]
	v_mfma_f32_16x16x32_bf16 v[68:71], v[140:143], v[202:205], v[68:71]
	s_setprio 0
	s_barrier
	s_add_i32 s28, 0, 0x14000
	v_add_u32_e32 v174, s28, v200
	s_add_i32 s29, s71, s55
	ds_read_b128 v[206:209], v174
	ds_read_b128 v[210:213], v174 offset:1024
	ds_read_b128 v[214:217], v174 offset:2048
	ds_read_b128 v[232:235], v174 offset:3072
	v_lshl_add_u64 v[174:175], s[50:51], 0, v[176:177]
	s_mov_b32 m0, s29
	v_lshl_add_u64 v[196:197], s[50:51], 0, v[160:161]
	global_load_lds_dwordx4 v[174:175], off
	s_add_i32 m0, s29, 0x2000
	s_nop 0
	global_load_lds_dwordx4 v[196:197], off
	s_barrier
	s_setprio 1
	s_waitcnt lgkmcnt(3)
	v_mfma_f32_16x16x32_bf16 v[120:123], v[206:209], v[144:147], v[120:123]
	s_waitcnt lgkmcnt(1)
	v_mfma_f32_16x16x32_bf16 v[112:115], v[214:217], v[144:147], v[112:115]
	v_mfma_f32_16x16x32_bf16 v[104:107], v[206:209], v[152:155], v[104:107]
	v_mfma_f32_16x16x32_bf16 v[96:99], v[214:217], v[152:155], v[96:99]
	v_mfma_f32_16x16x32_bf16 v[88:91], v[206:209], v[170:173], v[88:91]
	v_mfma_f32_16x16x32_bf16 v[80:83], v[214:217], v[170:173], v[80:83]
	v_mfma_f32_16x16x32_bf16 v[72:75], v[206:209], v[192:195], v[72:75]
	v_mfma_f32_16x16x32_bf16 v[64:67], v[214:217], v[192:195], v[64:67]
	v_mfma_f32_16x16x32_bf16 v[120:123], v[210:213], v[148:151], v[120:123]
	s_waitcnt lgkmcnt(0)
	v_mfma_f32_16x16x32_bf16 v[112:115], v[232:235], v[148:151], v[112:115]
	v_mfma_f32_16x16x32_bf16 v[104:107], v[210:213], v[166:169], v[104:107]
	v_mfma_f32_16x16x32_bf16 v[96:99], v[232:235], v[166:169], v[96:99]
	v_mfma_f32_16x16x32_bf16 v[88:91], v[210:213], v[188:191], v[88:91]
	v_mfma_f32_16x16x32_bf16 v[80:83], v[232:235], v[188:191], v[80:83]
	v_mfma_f32_16x16x32_bf16 v[72:75], v[210:213], v[202:205], v[72:75]
	v_mfma_f32_16x16x32_bf16 v[64:67], v[232:235], v[202:205], v[64:67]
	s_setprio 0
	s_mov_b32 m0, s56
	v_lshl_add_u64 v[236:237], s[52:53], 0, v[156:157]
	s_barrier
	ds_read_b128 v[144:147], v201 offset:16384
	ds_read_b128 v[152:155], v201 offset:18432
	ds_read_b128 v[170:173], v201 offset:20480
	ds_read_b128 v[192:195], v201 offset:22528
	ds_read_b128 v[148:151], v201 offset:17408
	ds_read_b128 v[166:169], v201 offset:19456
	ds_read_b128 v[188:191], v201 offset:21504
	ds_read_b128 v[202:205], v201 offset:23552
	global_load_lds_dwordx4 v[236:237], off
	v_lshl_add_u64 v[238:239], s[52:53], 0, v[158:159]
	s_mov_b32 m0, s57
	s_nop 0
	global_load_lds_dwordx4 v[238:239], off
	s_barrier
	s_setprio 1
	s_waitcnt lgkmcnt(7)
	v_mfma_f32_16x16x32_bf16 v[60:63], v[128:131], v[144:147], v[60:63]
	v_mfma_f32_16x16x32_bf16 v[52:55], v[136:139], v[144:147], v[52:55]
	s_waitcnt lgkmcnt(6)
	v_mfma_f32_16x16x32_bf16 v[44:47], v[128:131], v[152:155], v[44:47]
	v_mfma_f32_16x16x32_bf16 v[36:39], v[136:139], v[152:155], v[36:39]
	s_waitcnt lgkmcnt(5)
	v_mfma_f32_16x16x32_bf16 v[28:31], v[128:131], v[170:173], v[28:31]
	v_mfma_f32_16x16x32_bf16 v[20:23], v[136:139], v[170:173], v[20:23]
	s_waitcnt lgkmcnt(4)
	v_mfma_f32_16x16x32_bf16 v[12:15], v[128:131], v[192:195], v[12:15]
	v_mfma_f32_16x16x32_bf16 v[4:7], v[136:139], v[192:195], v[4:7]
	s_waitcnt lgkmcnt(3)
	v_mfma_f32_16x16x32_bf16 v[60:63], v[132:135], v[148:151], v[60:63]
	v_mfma_f32_16x16x32_bf16 v[52:55], v[140:143], v[148:151], v[52:55]
	s_waitcnt lgkmcnt(2)
	v_mfma_f32_16x16x32_bf16 v[44:47], v[132:135], v[166:169], v[44:47]
	v_mfma_f32_16x16x32_bf16 v[36:39], v[140:143], v[166:169], v[36:39]
	s_waitcnt lgkmcnt(1)
	v_mfma_f32_16x16x32_bf16 v[28:31], v[132:135], v[188:191], v[28:31]
	v_mfma_f32_16x16x32_bf16 v[20:23], v[140:143], v[188:191], v[20:23]
	s_waitcnt lgkmcnt(0)
	v_mfma_f32_16x16x32_bf16 v[12:15], v[132:135], v[202:205], v[12:15]
	v_mfma_f32_16x16x32_bf16 v[4:7], v[140:143], v[202:205], v[4:7]
	s_setprio 0
	s_barrier
	s_add_u32 s72, s50, 0x40000
	s_addc_u32 s73, s51, 0
	s_add_i32 s28, s28, s55
	v_lshl_add_u64 v[128:129], s[72:73], 0, v[176:177]
	s_mov_b32 m0, s28
	s_nop 0
	global_load_lds_dwordx4 v[128:129], off
	v_lshl_add_u64 v[128:129], s[72:73], 0, v[160:161]
	s_add_i32 m0, s28, 0x2000
	s_nop 0
	global_load_lds_dwordx4 v[128:129], off
	s_waitcnt vmcnt(6)
	s_barrier
	s_setprio 1
	v_mfma_f32_16x16x32_bf16 v[56:59], v[206:209], v[144:147], v[56:59]
	v_mfma_f32_16x16x32_bf16 v[48:51], v[214:217], v[144:147], v[48:51]
	v_mfma_f32_16x16x32_bf16 v[40:43], v[206:209], v[152:155], v[40:43]
	v_mfma_f32_16x16x32_bf16 v[32:35], v[214:217], v[152:155], v[32:35]
	v_mfma_f32_16x16x32_bf16 v[24:27], v[206:209], v[170:173], v[24:27]
	v_mfma_f32_16x16x32_bf16 v[16:19], v[214:217], v[170:173], v[16:19]
	v_mfma_f32_16x16x32_bf16 v[8:11], v[206:209], v[192:195], v[8:11]
	v_mfma_f32_16x16x32_bf16 v[0:3], v[214:217], v[192:195], v[0:3]
	v_mfma_f32_16x16x32_bf16 v[56:59], v[210:213], v[148:151], v[56:59]
	v_mfma_f32_16x16x32_bf16 v[48:51], v[232:235], v[148:151], v[48:51]
	v_mfma_f32_16x16x32_bf16 v[40:43], v[210:213], v[166:169], v[40:43]
	v_mfma_f32_16x16x32_bf16 v[32:35], v[232:235], v[166:169], v[32:35]
	v_mfma_f32_16x16x32_bf16 v[24:27], v[210:213], v[188:191], v[24:27]
	v_mfma_f32_16x16x32_bf16 v[16:19], v[232:235], v[188:191], v[16:19]
	v_mfma_f32_16x16x32_bf16 v[8:11], v[210:213], v[202:205], v[8:11]
	v_mfma_f32_16x16x32_bf16 v[0:3], v[232:235], v[202:205], v[0:3]
	s_setprio 0
	s_add_i32 s28, 0, 0x18000
	v_add_u32_e32 v140, s28, v200
	s_barrier
	ds_read_b128 v[128:131], v140
	ds_read_b128 v[132:135], v140 offset:1024
	ds_read_b128 v[136:139], v140 offset:2048
	ds_read_b128 v[140:143], v140 offset:3072
	ds_read_b128 v[144:147], v201 offset:32768
	ds_read_b128 v[152:155], v201 offset:34816
	ds_read_b128 v[170:173], v201 offset:36864
	ds_read_b128 v[192:195], v201 offset:38912
	ds_read_b128 v[148:151], v201 offset:33792
	ds_read_b128 v[166:169], v201 offset:35840
	ds_read_b128 v[188:191], v201 offset:37888
	ds_read_b128 v[202:205], v201 offset:39936
	s_add_u32 s52, s52, 0x40000
	s_addc_u32 s53, s53, 0
	s_mov_b32 m0, s58
	v_lshl_add_u64 v[206:207], s[52:53], 0, v[156:157]
	global_load_lds_dwordx4 v[206:207], off
	v_lshl_add_u64 v[206:207], s[52:53], 0, v[158:159]
	s_mov_b32 m0, s59
	s_nop 0
	global_load_lds_dwordx4 v[206:207], off
	s_waitcnt lgkmcnt(8)
	s_barrier
	s_setprio 1
	s_waitcnt lgkmcnt(7)
	v_mfma_f32_16x16x32_bf16 v[124:127], v[128:131], v[144:147], v[124:127]
	v_mfma_f32_16x16x32_bf16 v[116:119], v[136:139], v[144:147], v[116:119]
	s_waitcnt lgkmcnt(6)
	v_mfma_f32_16x16x32_bf16 v[108:111], v[128:131], v[152:155], v[108:111]
	v_mfma_f32_16x16x32_bf16 v[100:103], v[136:139], v[152:155], v[100:103]
	s_waitcnt lgkmcnt(5)
	v_mfma_f32_16x16x32_bf16 v[92:95], v[128:131], v[170:173], v[92:95]
	v_mfma_f32_16x16x32_bf16 v[84:87], v[136:139], v[170:173], v[84:87]
	s_waitcnt lgkmcnt(4)
	v_mfma_f32_16x16x32_bf16 v[76:79], v[128:131], v[192:195], v[76:79]
	v_mfma_f32_16x16x32_bf16 v[68:71], v[136:139], v[192:195], v[68:71]
	s_waitcnt lgkmcnt(3)
	v_mfma_f32_16x16x32_bf16 v[124:127], v[132:135], v[148:151], v[124:127]
	v_mfma_f32_16x16x32_bf16 v[116:119], v[140:143], v[148:151], v[116:119]
	s_waitcnt lgkmcnt(2)
	v_mfma_f32_16x16x32_bf16 v[108:111], v[132:135], v[166:169], v[108:111]
	v_mfma_f32_16x16x32_bf16 v[100:103], v[140:143], v[166:169], v[100:103]
	s_waitcnt lgkmcnt(1)
	v_mfma_f32_16x16x32_bf16 v[92:95], v[132:135], v[188:191], v[92:95]
	v_mfma_f32_16x16x32_bf16 v[84:87], v[140:143], v[188:191], v[84:87]
	s_waitcnt lgkmcnt(0)
	v_mfma_f32_16x16x32_bf16 v[76:79], v[132:135], v[202:205], v[76:79]
	v_mfma_f32_16x16x32_bf16 v[68:71], v[140:143], v[202:205], v[68:71]
	s_setprio 0
	s_barrier
	s_add_i32 s29, 0, 0x1c000
	s_add_i32 s28, s28, s55
	v_add_u32_e32 v232, s29, v200
	v_lshl_add_u64 v[174:175], v[174:175], 0, s[40:41]
	s_mov_b32 m0, s28
	ds_read_b128 v[206:209], v232
	ds_read_b128 v[210:213], v232 offset:1024
	ds_read_b128 v[214:217], v232 offset:2048
	ds_read_b128 v[232:235], v232 offset:3072
	global_load_lds_dwordx4 v[174:175], off
	v_lshl_add_u64 v[174:175], v[196:197], 0, s[40:41]
	s_add_i32 m0, s28, 0x2000
	s_nop 0
	global_load_lds_dwordx4 v[174:175], off
	s_barrier
	s_setprio 1
	s_waitcnt lgkmcnt(3)
	v_mfma_f32_16x16x32_bf16 v[120:123], v[206:209], v[144:147], v[120:123]
	s_waitcnt lgkmcnt(1)
	v_mfma_f32_16x16x32_bf16 v[112:115], v[214:217], v[144:147], v[112:115]
	v_mfma_f32_16x16x32_bf16 v[104:107], v[206:209], v[152:155], v[104:107]
	v_mfma_f32_16x16x32_bf16 v[96:99], v[214:217], v[152:155], v[96:99]
	v_mfma_f32_16x16x32_bf16 v[88:91], v[206:209], v[170:173], v[88:91]
	v_mfma_f32_16x16x32_bf16 v[80:83], v[214:217], v[170:173], v[80:83]
	v_mfma_f32_16x16x32_bf16 v[72:75], v[206:209], v[192:195], v[72:75]
	v_mfma_f32_16x16x32_bf16 v[64:67], v[214:217], v[192:195], v[64:67]
	v_mfma_f32_16x16x32_bf16 v[120:123], v[210:213], v[148:151], v[120:123]
	s_waitcnt lgkmcnt(0)
	v_mfma_f32_16x16x32_bf16 v[112:115], v[232:235], v[148:151], v[112:115]
	v_mfma_f32_16x16x32_bf16 v[104:107], v[210:213], v[166:169], v[104:107]
	v_mfma_f32_16x16x32_bf16 v[96:99], v[232:235], v[166:169], v[96:99]
	v_mfma_f32_16x16x32_bf16 v[88:91], v[210:213], v[188:191], v[88:91]
	v_mfma_f32_16x16x32_bf16 v[80:83], v[232:235], v[188:191], v[80:83]
	v_mfma_f32_16x16x32_bf16 v[72:75], v[210:213], v[202:205], v[72:75]
	v_mfma_f32_16x16x32_bf16 v[64:67], v[232:235], v[202:205], v[64:67]
	s_setprio 0
	s_mov_b32 m0, s62
	v_lshl_add_u64 v[174:175], v[236:237], 0, s[40:41]
	s_barrier
	ds_read_b128 v[144:147], v201 offset:49152
	ds_read_b128 v[152:155], v201 offset:51200
	ds_read_b128 v[170:173], v201 offset:53248
	ds_read_b128 v[192:195], v201 offset:55296
	ds_read_b128 v[148:151], v201 offset:50176
	ds_read_b128 v[166:169], v201 offset:52224
	ds_read_b128 v[188:191], v201 offset:54272
	ds_read_b128 v[202:205], v201 offset:56320
	global_load_lds_dwordx4 v[174:175], off
	v_lshl_add_u64 v[174:175], v[238:239], 0, s[40:41]
	s_mov_b32 m0, s63
	s_nop 0
	global_load_lds_dwordx4 v[174:175], off
	s_barrier
	s_setprio 1
	s_waitcnt lgkmcnt(7)
	v_mfma_f32_16x16x32_bf16 v[60:63], v[128:131], v[144:147], v[60:63]
	v_mfma_f32_16x16x32_bf16 v[52:55], v[136:139], v[144:147], v[52:55]
	s_waitcnt lgkmcnt(6)
	v_mfma_f32_16x16x32_bf16 v[44:47], v[128:131], v[152:155], v[44:47]
	v_mfma_f32_16x16x32_bf16 v[36:39], v[136:139], v[152:155], v[36:39]
	s_waitcnt lgkmcnt(5)
	v_mfma_f32_16x16x32_bf16 v[28:31], v[128:131], v[170:173], v[28:31]
	v_mfma_f32_16x16x32_bf16 v[20:23], v[136:139], v[170:173], v[20:23]
	s_waitcnt lgkmcnt(4)
	v_mfma_f32_16x16x32_bf16 v[12:15], v[128:131], v[192:195], v[12:15]
	v_mfma_f32_16x16x32_bf16 v[4:7], v[136:139], v[192:195], v[4:7]
	s_waitcnt lgkmcnt(3)
	v_mfma_f32_16x16x32_bf16 v[60:63], v[132:135], v[148:151], v[60:63]
	v_mfma_f32_16x16x32_bf16 v[52:55], v[140:143], v[148:151], v[52:55]
	s_waitcnt lgkmcnt(2)
	v_mfma_f32_16x16x32_bf16 v[44:47], v[132:135], v[166:169], v[44:47]
	v_mfma_f32_16x16x32_bf16 v[36:39], v[140:143], v[166:169], v[36:39]
	s_waitcnt lgkmcnt(1)
	v_mfma_f32_16x16x32_bf16 v[28:31], v[132:135], v[188:191], v[28:31]
	v_mfma_f32_16x16x32_bf16 v[20:23], v[140:143], v[188:191], v[20:23]
	s_waitcnt lgkmcnt(0)
	v_mfma_f32_16x16x32_bf16 v[12:15], v[132:135], v[202:205], v[12:15]
	v_mfma_f32_16x16x32_bf16 v[4:7], v[140:143], v[202:205], v[4:7]
	s_setprio 0
	s_barrier
	s_add_u32 s50, s50, 0x40080
	s_addc_u32 s51, s51, 0
	s_add_i32 s28, s29, s55
	v_lshl_add_u64 v[128:129], s[50:51], 0, v[176:177]
	s_mov_b32 m0, s28
	s_nop 0
	global_load_lds_dwordx4 v[128:129], off
	v_lshl_add_u64 v[128:129], s[50:51], 0, v[160:161]
	s_add_i32 m0, s28, 0x2000
	s_nop 0
	global_load_lds_dwordx4 v[128:129], off
	s_waitcnt vmcnt(6)
	s_barrier
	s_setprio 1
	v_mfma_f32_16x16x32_bf16 v[56:59], v[206:209], v[144:147], v[56:59]
	v_mfma_f32_16x16x32_bf16 v[48:51], v[214:217], v[144:147], v[48:51]
	v_mfma_f32_16x16x32_bf16 v[40:43], v[206:209], v[152:155], v[40:43]
	v_mfma_f32_16x16x32_bf16 v[32:35], v[214:217], v[152:155], v[32:35]
	v_mfma_f32_16x16x32_bf16 v[24:27], v[206:209], v[170:173], v[24:27]
	v_mfma_f32_16x16x32_bf16 v[16:19], v[214:217], v[170:173], v[16:19]
	v_mfma_f32_16x16x32_bf16 v[8:11], v[206:209], v[192:195], v[8:11]
	v_mfma_f32_16x16x32_bf16 v[0:3], v[214:217], v[192:195], v[0:3]
	v_mfma_f32_16x16x32_bf16 v[56:59], v[210:213], v[148:151], v[56:59]
	v_mfma_f32_16x16x32_bf16 v[48:51], v[232:235], v[148:151], v[48:51]
	v_mfma_f32_16x16x32_bf16 v[40:43], v[210:213], v[166:169], v[40:43]
	v_mfma_f32_16x16x32_bf16 v[32:35], v[232:235], v[166:169], v[32:35]
	v_mfma_f32_16x16x32_bf16 v[24:27], v[210:213], v[188:191], v[24:27]
	v_mfma_f32_16x16x32_bf16 v[16:19], v[232:235], v[188:191], v[16:19]
	v_mfma_f32_16x16x32_bf16 v[8:11], v[210:213], v[202:205], v[8:11]
	v_mfma_f32_16x16x32_bf16 v[0:3], v[232:235], v[202:205], v[0:3]
	s_setprio 0
	s_add_i32 s70, s70, 2
	s_add_u32 s6, s6, 0x100
	s_addc_u32 s7, s7, 0
	s_add_u32 s68, s68, 0x100
	s_addc_u32 s69, s69, 0
	s_cmp_lt_u32 s70, 14
	s_barrier
	s_cbranch_scc1 .LBB0_1436
	v_mov_b32_e32 v134, v199
	v_mov_b32_e32 v128, v198
	s_lshl_b32 s4, s4, 8
	s_add_i32 s4, s4, s60
	v_add_u32_e32 v192, s4, v128
	v_lshlrev_b32_e32 v128, 2, v134
	v_ashrrev_i32_e32 v129, 31, v128
	v_ashrrev_i32_e32 v193, 31, v192
	v_add_u32_e32 v190, 16, v192
	v_lshl_add_u64 v[132:133], v[128:129], 2, s[8:9]
	v_lshlrev_b64 v[128:129], 6, v[192:193]
	v_ashrrev_i32_e32 v191, 31, v190
	v_add_u32_e32 v188, 32, v192
	v_lshl_add_u64 v[128:129], v[132:133], 0, v[128:129]
	v_lshlrev_b64 v[130:131], 6, v[190:191]
	v_ashrrev_i32_e32 v189, 31, v188
	v_lshl_add_u64 v[130:131], v[132:133], 0, v[130:131]
	global_load_dwordx4 v[202:205], v[128:129], off
	global_load_dwordx4 v[144:147], v[130:131], off
	v_lshlrev_b64 v[128:129], 6, v[188:189]
	v_add_u32_e32 v174, 48, v192
	v_lshl_add_u64 v[128:129], v[132:133], 0, v[128:129]
	v_ashrrev_i32_e32 v175, 31, v174
	global_load_dwordx4 v[148:151], v[128:129], off
	v_lshlrev_b64 v[128:129], 6, v[174:175]
	v_lshl_add_u64 v[128:129], v[132:133], 0, v[128:129]
	global_load_dwordx4 v[152:155], v[128:129], off
	v_add_u32_e32 v172, 0x80, v192
	v_ashrrev_i32_e32 v173, 31, v172
	v_lshlrev_b64 v[128:129], 6, v[172:173]
	v_lshl_add_u64 v[128:129], v[132:133], 0, v[128:129]
	global_load_dwordx4 v[140:143], v[128:129], off
	v_add_u32_e32 v170, 0x90, v192
	v_ashrrev_i32_e32 v171, 31, v170
	v_lshlrev_b64 v[128:129], 6, v[170:171]
	v_lshl_add_u64 v[128:129], v[132:133], 0, v[128:129]
	global_load_dwordx4 v[128:131], v[128:129], off
	s_lshl_b32 s5, s5, 7
	v_add_u32_e32 v168, 0xa0, v192
	v_add_u32_e32 v166, 0xb0, v192
	s_or_b32 s5, s5, s61
	v_ashrrev_i32_e32 v169, 31, v168
	v_ashrrev_i32_e32 v167, 31, v166
	v_lshl_add_u32 v194, v134, 3, s5
	v_lshlrev_b64 v[134:135], 6, v[168:169]
	v_lshlrev_b64 v[136:137], 6, v[166:167]
	v_lshl_add_u64 v[134:135], v[132:133], 0, v[134:135]
	v_lshl_add_u64 v[132:133], v[132:133], 0, v[136:137]
	global_load_dwordx4 v[136:139], v[134:135], off
	s_nop 0
	global_load_dwordx4 v[132:135], v[132:133], off
	s_mov_b32 s4, 0x358637bd
	v_mov_b64_e32 v[196:197], s[4:5]
	v_ashrrev_i32_e32 v195, 31, v194
	s_mov_b64 s[50:51], s[20:21]
	s_waitcnt vmcnt(0)
	v_mov_b32_e32 v206, v203
	v_mov_b32_e32 v207, v204
	v_mov_b32_e32 v203, v205
	v_mov_b32_e32 v204, v145
	v_mov_b32_e32 v205, v146
	v_mov_b32_e32 v145, v147
	v_pk_add_f32 v[202:203], v[206:207], v[202:203]
	v_mov_b32_e32 v146, v149
	v_mov_b32_e32 v147, v150
	v_mov_b32_e32 v149, v151
	v_mov_b32_e32 v150, v153
	v_mov_b32_e32 v151, v154
	v_mov_b32_e32 v153, v155
	v_pk_add_f32 v[144:145], v[204:205], v[144:145]
	v_mov_b32_e32 v155, v202
	v_pk_add_f32 v[146:147], v[146:147], v[148:149]
	v_pk_add_f32 v[148:149], v[150:151], v[152:153]
	v_mov_b32_e32 v154, v144
	v_mov_b32_e32 v202, v145
	v_mov_b32_e32 v144, v148
	v_mov_b32_e32 v145, v146
	v_mov_b32_e32 v146, v149
	v_pk_add_f32 v[148:149], v[154:155], v[202:203]
	v_pk_add_f32 v[144:145], v[144:145], v[146:147]
	ds_bpermute_b32 v147, v219, v149
	ds_bpermute_b32 v146, v219, v148
	ds_bpermute_b32 v151, v219, v145
	ds_bpermute_b32 v150, v219, v144
	v_mov_b32_e32 v152, v141
	v_mov_b32_e32 v153, v142
	v_mov_b32_e32 v141, v143
	s_waitcnt lgkmcnt(0)
	v_pk_add_f32 v[142:143], v[148:149], v[146:147]
	ds_bpermute_b32 v147, v218, v143
	ds_bpermute_b32 v146, v218, v142
	v_pk_add_f32 v[144:145], v[144:145], v[150:151]
	ds_bpermute_b32 v149, v218, v145
	ds_bpermute_b32 v148, v218, v144
	v_mov_b32_e32 v150, v129
	s_waitcnt lgkmcnt(2)
	v_pk_add_f32 v[142:143], v[142:143], v[146:147]
	v_mov_b32_e32 v151, v130
	v_pk_fma_f32 v[142:143], v[142:143], s[30:31], v[196:197] op_sel_hi:[1,0,0]
	s_waitcnt lgkmcnt(0)
	v_pk_add_f32 v[144:145], v[144:145], v[148:149]
	v_mul_f32_e32 v129, 0x4b800000, v143
	v_cmp_gt_f32_e32 vcc, s86, v143
	v_pk_fma_f32 v[146:147], v[144:145], s[30:31], v[196:197] op_sel_hi:[1,0,0]
	v_mul_f32_e32 v130, 0x4b800000, v142
	v_cndmask_b32_e32 v129, v143, v129, vcc
	v_rsq_f32_e32 v129, v129
	v_cmp_gt_f32_e64 s[4:5], s86, v142
	v_mul_f32_e32 v144, 0x4b800000, v147
	v_cmp_gt_f32_e64 s[6:7], s86, v147
	v_cndmask_b32_e64 v130, v142, v130, s[4:5]
	v_rsq_f32_e32 v142, v130
	v_cndmask_b32_e64 v130, v147, v144, s[6:7]
	v_rsq_f32_e32 v143, v130
	v_mul_f32_e32 v130, 0x45800000, v129
	v_cndmask_b32_e32 v144, v129, v130, vcc
	v_mov_b32_e32 v129, v131
	v_pk_add_f32 v[140:141], v[152:153], v[140:141]
	v_pk_add_f32 v[128:129], v[150:151], v[128:129]
	v_mov_b32_e32 v131, v140
	v_mov_b32_e32 v130, v128
	v_mov_b32_e32 v140, v129
	v_pk_add_f32 v[128:129], v[130:131], v[140:141]
	ds_bpermute_b32 v131, v219, v129
	ds_bpermute_b32 v130, v219, v128
	v_mul_f32_e32 v145, 0x45800000, v142
	v_cndmask_b32_e64 v142, v142, v145, s[4:5]
	v_mul_f32_e32 v140, 0x4b800000, v146
	v_cmp_gt_f32_e32 vcc, s86, v146
	s_waitcnt lgkmcnt(0)
	v_pk_add_f32 v[128:129], v[128:129], v[130:131]
	ds_bpermute_b32 v131, v218, v129
	ds_bpermute_b32 v130, v218, v128
	v_cndmask_b32_e32 v140, v146, v140, vcc
	v_rsq_f32_e32 v141, v140
	v_mul_f32_e32 v140, 0x45800000, v143
	v_cndmask_b32_e64 v140, v143, v140, s[6:7]
	s_waitcnt lgkmcnt(0)
	v_pk_add_f32 v[128:129], v[128:129], v[130:131]
	v_mov_b32_e32 v131, v138
	v_pk_fma_f32 v[128:129], v[128:129], s[30:31], v[196:197] op_sel_hi:[1,0,0]
	v_mul_f32_e32 v143, 0x45800000, v141
	v_mul_f32_e32 v130, 0x4b800000, v129
	v_cmp_gt_f32_e64 s[4:5], s86, v129
	v_cmp_gt_f32_e64 s[6:7], s86, v128
	v_pk_mul_f32 v[110:111], v[110:111], v[142:143] op_sel_hi:[1,0]
	v_cndmask_b32_e64 v129, v129, v130, s[4:5]
	v_mov_b32_e32 v130, v137
	v_mov_b32_e32 v137, v139
	v_pk_add_f32 v[130:131], v[130:131], v[136:137]
	v_mov_b32_e32 v136, v133
	v_mov_b32_e32 v137, v134
	v_mov_b32_e32 v133, v135
	v_pk_add_f32 v[132:133], v[136:137], v[132:133]
	v_mov_b32_e32 v135, v130
	v_mov_b32_e32 v134, v132
	v_mov_b32_e32 v130, v133
	v_pk_add_f32 v[130:131], v[134:135], v[130:131]
	ds_bpermute_b32 v133, v219, v131
	ds_bpermute_b32 v132, v219, v130
	v_rsq_f32_e32 v145, v129
	v_mul_f32_e32 v129, 0x4b800000, v128
	v_cndmask_b32_e64 v128, v128, v129, s[6:7]
	v_rsq_f32_e32 v135, v128
	s_waitcnt lgkmcnt(0)
	v_pk_add_f32 v[128:129], v[130:131], v[132:133]
	ds_bpermute_b32 v131, v218, v129
	ds_bpermute_b32 v130, v218, v128
	v_pk_mul_f32 v[126:127], v[126:127], v[144:145] op_sel_hi:[1,0]
	v_pk_mul_f32 v[122:123], v[122:123], v[144:145] op_sel_hi:[1,0]
	v_pk_mul_f32 v[116:117], v[116:117], v[144:145] op_sel_hi:[1,0]
	v_pk_mul_f32 v[124:125], v[124:125], v[144:145] op_sel_hi:[1,0]
	v_pk_mul_f32 v[138:139], v[126:127], s[44:45] op_sel_hi:[1,0]
	v_pk_mul_f32 v[120:121], v[120:121], v[144:145] op_sel_hi:[1,0]
	v_pk_mul_f32 v[122:123], v[126:127], v[122:123]
	v_pk_mul_f32 v[118:119], v[118:119], v[144:145] op_sel_hi:[1,0]
	v_pk_mul_f32 v[126:127], v[116:117], s[44:45] op_sel_hi:[1,0]
	v_pk_mul_f32 v[146:147], v[124:125], s[44:45] op_sel_hi:[1,0]
	v_pk_mul_f32 v[120:121], v[124:125], v[120:121]
	v_pk_mul_f32 v[124:125], v[118:119], s[44:45] op_sel_hi:[1,0]
	v_exp_f32_e32 v126, v126
	v_exp_f32_e32 v127, v127
	s_waitcnt lgkmcnt(0)
	v_pk_add_f32 v[128:129], v[128:129], v[130:131]
	v_exp_f32_e32 v146, v146
	v_exp_f32_e32 v138, v138
	v_exp_f32_e32 v139, v139
	v_exp_f32_e32 v147, v147
	v_exp_f32_e32 v124, v124
	v_exp_f32_e32 v125, v125
	v_pk_fma_f32 v[128:129], v[128:129], s[30:31], v[196:197] op_sel_hi:[1,0,0]
	v_cndmask_b32_e32 v136, v141, v143, vcc
	v_mul_f32_e32 v132, 0x45800000, v145
	v_mul_f32_e32 v130, 0x4b800000, v129
	v_cmp_gt_f32_e32 vcc, s86, v129
	v_cndmask_b32_e64 v134, v145, v132, s[4:5]
	v_cmp_gt_f32_e64 s[4:5], s86, v128
	v_cndmask_b32_e32 v129, v129, v130, vcc
	v_mul_f32_e32 v130, 0x4b800000, v128
	v_pk_add_f32 v[126:127], v[126:127], 1.0 op_sel_hi:[1,0]
	v_rsq_f32_e32 v129, v129
	v_cndmask_b32_e64 v128, v128, v130, s[4:5]
	v_pk_add_f32 v[138:139], v[138:139], 1.0 op_sel_hi:[1,0]
	v_pk_add_f32 v[146:147], v[146:147], 1.0 op_sel_hi:[1,0]
	v_pk_add_f32 v[124:125], v[124:125], 1.0 op_sel_hi:[1,0]
	v_rcp_f32_e32 v126, v126
	v_rcp_f32_e32 v127, v127
	v_rsq_f32_e32 v128, v128
	v_rcp_f32_e32 v146, v146
	v_rcp_f32_e32 v138, v138
	v_rcp_f32_e32 v139, v139
	v_rcp_f32_e32 v147, v147
	v_rcp_f32_e32 v124, v124
	v_rcp_f32_e32 v125, v125
	v_pk_mul_f32 v[112:113], v[112:113], v[144:145] op_sel_hi:[1,0]
	v_pk_mul_f32 v[114:115], v[114:115], v[144:145] op_sel_hi:[1,0]
	v_pk_mul_f32 v[112:113], v[116:117], v[112:113]
	v_mul_f32_e32 v130, 0x45800000, v129
	v_pk_mul_f32 v[114:115], v[118:119], v[114:115]
	v_pk_mul_f32 v[112:113], v[112:113], v[126:127]
	v_cndmask_b32_e32 v130, v129, v130, vcc
	v_mul_f32_e32 v129, 0x45800000, v128
	v_pk_mul_f32 v[122:123], v[122:123], v[138:139]
	v_pk_mul_f32 v[120:121], v[120:121], v[146:147]
	v_pk_mul_f32 v[114:115], v[114:115], v[124:125]
	v_cvt_pk_bf16_f32 v116, v120, v121
	v_cvt_pk_bf16_f32 v117, v122, v123
	v_cvt_pk_bf16_f32 v118, v112, v113
	v_mov_b64_e32 v[112:113], s[10:11]
	v_cndmask_b32_e64 v128, v128, v129, s[4:5]
	v_cvt_pk_bf16_f32 v119, v114, v115
	v_mad_i64_i32 v[120:121], s[4:5], v192, s35, v[112:113]
	v_lshlrev_b64 v[114:115], 1, v[194:195]
	v_lshl_add_u64 v[120:121], v[120:121], 0, v[114:115]
	v_pk_mul_f32 v[108:109], v[108:109], v[142:143] op_sel_hi:[1,0]
	v_pk_mul_f32 v[106:107], v[106:107], v[142:143] op_sel_hi:[1,0]
	v_pk_mul_f32 v[104:105], v[104:105], v[142:143] op_sel_hi:[1,0]
	v_pk_mul_f32 v[102:103], v[102:103], v[142:143] op_sel_hi:[1,0]
	v_pk_mul_f32 v[100:101], v[100:101], v[142:143] op_sel_hi:[1,0]
	global_store_dwordx4 v[120:121], v[116:119], off
	v_pk_mul_f32 v[104:105], v[108:109], v[104:105]
	v_pk_mul_f32 v[106:107], v[110:111], v[106:107]
	v_pk_mul_f32 v[116:117], v[110:111], s[44:45] op_sel_hi:[1,0]
	v_pk_mul_f32 v[118:119], v[108:109], s[44:45] op_sel_hi:[1,0]
	v_pk_mul_f32 v[108:109], v[102:103], s[44:45] op_sel_hi:[1,0]
	v_pk_mul_f32 v[110:111], v[100:101], s[44:45] op_sel_hi:[1,0]
	v_exp_f32_e32 v108, v108
	v_exp_f32_e32 v110, v110
	v_exp_f32_e32 v109, v109
	v_exp_f32_e32 v111, v111
	v_exp_f32_e32 v118, v118
	v_exp_f32_e32 v116, v116
	v_exp_f32_e32 v117, v117
	v_exp_f32_e32 v119, v119
	v_pk_add_f32 v[108:109], v[108:109], 1.0 op_sel_hi:[1,0]
	v_pk_add_f32 v[110:111], v[110:111], 1.0 op_sel_hi:[1,0]
	v_pk_add_f32 v[116:117], v[116:117], 1.0 op_sel_hi:[1,0]
	v_pk_add_f32 v[118:119], v[118:119], 1.0 op_sel_hi:[1,0]
	v_rcp_f32_e32 v110, v110
	v_rcp_f32_e32 v108, v108
	v_rcp_f32_e32 v109, v109
	v_rcp_f32_e32 v111, v111
	v_rcp_f32_e32 v118, v118
	v_rcp_f32_e32 v116, v116
	v_rcp_f32_e32 v117, v117
	v_rcp_f32_e32 v119, v119
	v_pk_mul_f32 v[98:99], v[98:99], v[142:143] op_sel_hi:[1,0]
	v_pk_mul_f32 v[96:97], v[96:97], v[142:143] op_sel_hi:[1,0]
	v_pk_mul_f32 v[98:99], v[102:103], v[98:99]
	v_pk_mul_f32 v[96:97], v[100:101], v[96:97]
	v_pk_mul_f32 v[100:101], v[98:99], v[108:109]
	v_pk_mul_f32 v[98:99], v[96:97], v[110:111]
	v_pk_mul_f32 v[106:107], v[106:107], v[116:117]
	v_pk_mul_f32 v[104:105], v[104:105], v[118:119]
	v_pk_mul_f32 v[94:95], v[94:95], v[140:141] op_sel_hi:[1,0]
	v_cvt_pk_bf16_f32 v96, v104, v105
	v_cvt_pk_bf16_f32 v97, v106, v107
	v_cvt_pk_bf16_f32 v98, v98, v99
	v_cvt_pk_bf16_f32 v99, v100, v101
	v_mad_i64_i32 v[100:101], s[4:5], v190, s35, v[112:113]
	v_lshl_add_u64 v[100:101], v[100:101], 0, v[114:115]
	v_pk_mul_f32 v[92:93], v[92:93], v[140:141] op_sel_hi:[1,0]
	v_pk_mul_f32 v[90:91], v[90:91], v[140:141] op_sel_hi:[1,0]
	v_pk_mul_f32 v[88:89], v[88:89], v[140:141] op_sel_hi:[1,0]
	v_pk_mul_f32 v[86:87], v[86:87], v[140:141] op_sel_hi:[1,0]
	v_pk_mul_f32 v[84:85], v[84:85], v[140:141] op_sel_hi:[1,0]
	global_store_dwordx4 v[100:101], v[96:99], off
	v_pk_mul_f32 v[88:89], v[92:93], v[88:89]
	v_pk_mul_f32 v[90:91], v[94:95], v[90:91]
	v_pk_mul_f32 v[96:97], v[94:95], s[44:45] op_sel_hi:[1,0]
	v_pk_mul_f32 v[98:99], v[92:93], s[44:45] op_sel_hi:[1,0]
	v_pk_mul_f32 v[92:93], v[86:87], s[44:45] op_sel_hi:[1,0]
	v_pk_mul_f32 v[94:95], v[84:85], s[44:45] op_sel_hi:[1,0]
	v_exp_f32_e32 v92, v92
	v_exp_f32_e32 v94, v94
	v_exp_f32_e32 v93, v93
	v_exp_f32_e32 v95, v95
	v_exp_f32_e32 v98, v98
	v_exp_f32_e32 v96, v96
	v_exp_f32_e32 v97, v97
	v_exp_f32_e32 v99, v99
	v_pk_add_f32 v[92:93], v[92:93], 1.0 op_sel_hi:[1,0]
	v_pk_add_f32 v[94:95], v[94:95], 1.0 op_sel_hi:[1,0]
	v_pk_add_f32 v[96:97], v[96:97], 1.0 op_sel_hi:[1,0]
	v_pk_add_f32 v[98:99], v[98:99], 1.0 op_sel_hi:[1,0]
	v_rcp_f32_e32 v94, v94
	v_rcp_f32_e32 v92, v92
	v_rcp_f32_e32 v93, v93
	v_rcp_f32_e32 v95, v95
	v_rcp_f32_e32 v98, v98
	v_rcp_f32_e32 v96, v96
	v_rcp_f32_e32 v97, v97
	v_rcp_f32_e32 v99, v99
	v_pk_mul_f32 v[82:83], v[82:83], v[140:141] op_sel_hi:[1,0]
	v_pk_mul_f32 v[80:81], v[80:81], v[140:141] op_sel_hi:[1,0]
	v_pk_mul_f32 v[82:83], v[86:87], v[82:83]
	v_pk_mul_f32 v[80:81], v[84:85], v[80:81]
	v_pk_mul_f32 v[84:85], v[82:83], v[92:93]
	v_pk_mul_f32 v[82:83], v[80:81], v[94:95]
	v_pk_mul_f32 v[90:91], v[90:91], v[96:97]
	v_pk_mul_f32 v[88:89], v[88:89], v[98:99]
	v_pk_mul_f32 v[78:79], v[78:79], v[136:137] op_sel_hi:[1,0]
	v_cvt_pk_bf16_f32 v80, v88, v89
	v_cvt_pk_bf16_f32 v81, v90, v91
	v_cvt_pk_bf16_f32 v82, v82, v83
	v_cvt_pk_bf16_f32 v83, v84, v85
	v_mad_i64_i32 v[84:85], s[4:5], v188, s35, v[112:113]
	v_lshl_add_u64 v[84:85], v[84:85], 0, v[114:115]
	v_pk_mul_f32 v[76:77], v[76:77], v[136:137] op_sel_hi:[1,0]
	v_pk_mul_f32 v[74:75], v[74:75], v[136:137] op_sel_hi:[1,0]
	v_pk_mul_f32 v[72:73], v[72:73], v[136:137] op_sel_hi:[1,0]
	v_pk_mul_f32 v[70:71], v[70:71], v[136:137] op_sel_hi:[1,0]
	v_pk_mul_f32 v[68:69], v[68:69], v[136:137] op_sel_hi:[1,0]
	global_store_dwordx4 v[84:85], v[80:83], off
	v_pk_mul_f32 v[72:73], v[76:77], v[72:73]
	v_pk_mul_f32 v[74:75], v[78:79], v[74:75]
	v_pk_mul_f32 v[80:81], v[78:79], s[44:45] op_sel_hi:[1,0]
	v_pk_mul_f32 v[82:83], v[76:77], s[44:45] op_sel_hi:[1,0]
	v_pk_mul_f32 v[76:77], v[70:71], s[44:45] op_sel_hi:[1,0]
	v_pk_mul_f32 v[78:79], v[68:69], s[44:45] op_sel_hi:[1,0]
	v_exp_f32_e32 v76, v76
	v_exp_f32_e32 v78, v78
	v_exp_f32_e32 v77, v77
	v_exp_f32_e32 v79, v79
	v_exp_f32_e32 v82, v82
	v_exp_f32_e32 v80, v80
	v_exp_f32_e32 v81, v81
	v_exp_f32_e32 v83, v83
	v_pk_add_f32 v[76:77], v[76:77], 1.0 op_sel_hi:[1,0]
	v_pk_add_f32 v[78:79], v[78:79], 1.0 op_sel_hi:[1,0]
	v_pk_add_f32 v[80:81], v[80:81], 1.0 op_sel_hi:[1,0]
	v_pk_add_f32 v[82:83], v[82:83], 1.0 op_sel_hi:[1,0]
	v_rcp_f32_e32 v78, v78
	v_rcp_f32_e32 v76, v76
	v_rcp_f32_e32 v77, v77
	v_rcp_f32_e32 v79, v79
	v_rcp_f32_e32 v82, v82
	v_rcp_f32_e32 v80, v80
	v_rcp_f32_e32 v81, v81
	v_rcp_f32_e32 v83, v83
	v_pk_mul_f32 v[66:67], v[66:67], v[136:137] op_sel_hi:[1,0]
	v_pk_mul_f32 v[64:65], v[64:65], v[136:137] op_sel_hi:[1,0]
	v_pk_mul_f32 v[66:67], v[70:71], v[66:67]
	v_pk_mul_f32 v[64:65], v[68:69], v[64:65]
	v_pk_mul_f32 v[68:69], v[66:67], v[76:77]
	v_pk_mul_f32 v[66:67], v[64:65], v[78:79]
	v_pk_mul_f32 v[74:75], v[74:75], v[80:81]
	v_pk_mul_f32 v[72:73], v[72:73], v[82:83]
	v_pk_mul_f32 v[62:63], v[62:63], v[134:135] op_sel_hi:[1,0]
	v_cvt_pk_bf16_f32 v64, v72, v73
	v_cvt_pk_bf16_f32 v65, v74, v75
	v_cvt_pk_bf16_f32 v66, v66, v67
	v_cvt_pk_bf16_f32 v67, v68, v69
	v_mad_i64_i32 v[68:69], s[4:5], v174, s35, v[112:113]
	v_lshl_add_u64 v[68:69], v[68:69], 0, v[114:115]
	v_pk_mul_f32 v[60:61], v[60:61], v[134:135] op_sel_hi:[1,0]
	v_pk_mul_f32 v[58:59], v[58:59], v[134:135] op_sel_hi:[1,0]
	v_pk_mul_f32 v[56:57], v[56:57], v[134:135] op_sel_hi:[1,0]
	v_pk_mul_f32 v[54:55], v[54:55], v[134:135] op_sel_hi:[1,0]
	v_pk_mul_f32 v[52:53], v[52:53], v[134:135] op_sel_hi:[1,0]
	global_store_dwordx4 v[68:69], v[64:67], off
	v_pk_mul_f32 v[56:57], v[60:61], v[56:57]
	v_pk_mul_f32 v[58:59], v[62:63], v[58:59]
	v_pk_mul_f32 v[64:65], v[62:63], s[44:45] op_sel_hi:[1,0]
	v_pk_mul_f32 v[66:67], v[60:61], s[44:45] op_sel_hi:[1,0]
	v_pk_mul_f32 v[60:61], v[54:55], s[44:45] op_sel_hi:[1,0]
	v_pk_mul_f32 v[62:63], v[52:53], s[44:45] op_sel_hi:[1,0]
	v_exp_f32_e32 v60, v60
	v_exp_f32_e32 v62, v62
	v_exp_f32_e32 v61, v61
	v_exp_f32_e32 v63, v63
	v_exp_f32_e32 v66, v66
	v_exp_f32_e32 v64, v64
	v_exp_f32_e32 v65, v65
	v_exp_f32_e32 v67, v67
	v_pk_add_f32 v[60:61], v[60:61], 1.0 op_sel_hi:[1,0]
	v_pk_add_f32 v[62:63], v[62:63], 1.0 op_sel_hi:[1,0]
	v_pk_add_f32 v[64:65], v[64:65], 1.0 op_sel_hi:[1,0]
	v_pk_add_f32 v[66:67], v[66:67], 1.0 op_sel_hi:[1,0]
	v_rcp_f32_e32 v62, v62
	v_rcp_f32_e32 v60, v60
	v_rcp_f32_e32 v61, v61
	v_rcp_f32_e32 v63, v63
	v_rcp_f32_e32 v66, v66
	v_rcp_f32_e32 v64, v64
	v_rcp_f32_e32 v65, v65
	v_rcp_f32_e32 v67, v67
	v_pk_mul_f32 v[50:51], v[50:51], v[134:135] op_sel_hi:[1,0]
	v_pk_mul_f32 v[48:49], v[48:49], v[134:135] op_sel_hi:[1,0]
	v_pk_mul_f32 v[50:51], v[54:55], v[50:51]
	v_pk_mul_f32 v[48:49], v[52:53], v[48:49]
	v_mul_f32_e32 v132, 0x45800000, v135
	v_pk_mul_f32 v[52:53], v[50:51], v[60:61]
	v_pk_mul_f32 v[50:51], v[48:49], v[62:63]
	v_cndmask_b32_e64 v132, v135, v132, s[6:7]
	v_pk_mul_f32 v[58:59], v[58:59], v[64:65]
	v_pk_mul_f32 v[56:57], v[56:57], v[66:67]
	v_pk_mul_f32 v[46:47], v[46:47], v[132:133] op_sel_hi:[1,0]
	v_cvt_pk_bf16_f32 v48, v56, v57
	v_cvt_pk_bf16_f32 v49, v58, v59
	v_cvt_pk_bf16_f32 v50, v50, v51
	v_cvt_pk_bf16_f32 v51, v52, v53
	v_mad_i64_i32 v[52:53], s[4:5], v172, s35, v[112:113]
	v_lshl_add_u64 v[52:53], v[52:53], 0, v[114:115]
	v_pk_mul_f32 v[44:45], v[44:45], v[132:133] op_sel_hi:[1,0]
	v_pk_mul_f32 v[42:43], v[42:43], v[132:133] op_sel_hi:[1,0]
	v_pk_mul_f32 v[40:41], v[40:41], v[132:133] op_sel_hi:[1,0]
	v_pk_mul_f32 v[38:39], v[38:39], v[132:133] op_sel_hi:[1,0]
	v_pk_mul_f32 v[36:37], v[36:37], v[132:133] op_sel_hi:[1,0]
	global_store_dwordx4 v[52:53], v[48:51], off
	v_pk_mul_f32 v[40:41], v[44:45], v[40:41]
	v_pk_mul_f32 v[42:43], v[46:47], v[42:43]
	v_pk_mul_f32 v[48:49], v[46:47], s[44:45] op_sel_hi:[1,0]
	v_pk_mul_f32 v[50:51], v[44:45], s[44:45] op_sel_hi:[1,0]
	v_pk_mul_f32 v[44:45], v[38:39], s[44:45] op_sel_hi:[1,0]
	v_pk_mul_f32 v[46:47], v[36:37], s[44:45] op_sel_hi:[1,0]
	v_exp_f32_e32 v44, v44
	v_exp_f32_e32 v46, v46
	v_exp_f32_e32 v45, v45
	v_exp_f32_e32 v47, v47
	v_exp_f32_e32 v50, v50
	v_exp_f32_e32 v48, v48
	v_exp_f32_e32 v49, v49
	v_exp_f32_e32 v51, v51
	v_pk_add_f32 v[44:45], v[44:45], 1.0 op_sel_hi:[1,0]
	v_pk_add_f32 v[46:47], v[46:47], 1.0 op_sel_hi:[1,0]
	v_pk_add_f32 v[48:49], v[48:49], 1.0 op_sel_hi:[1,0]
	v_pk_add_f32 v[50:51], v[50:51], 1.0 op_sel_hi:[1,0]
	v_rcp_f32_e32 v46, v46
	v_rcp_f32_e32 v44, v44
	v_rcp_f32_e32 v45, v45
	v_rcp_f32_e32 v47, v47
	v_rcp_f32_e32 v50, v50
	v_rcp_f32_e32 v48, v48
	v_rcp_f32_e32 v49, v49
	v_rcp_f32_e32 v51, v51
	v_pk_mul_f32 v[34:35], v[34:35], v[132:133] op_sel_hi:[1,0]
	v_pk_mul_f32 v[32:33], v[32:33], v[132:133] op_sel_hi:[1,0]
	v_pk_mul_f32 v[34:35], v[38:39], v[34:35]
	v_pk_mul_f32 v[32:33], v[36:37], v[32:33]
	v_pk_mul_f32 v[36:37], v[34:35], v[44:45]
	v_pk_mul_f32 v[34:35], v[32:33], v[46:47]
	v_pk_mul_f32 v[42:43], v[42:43], v[48:49]
	v_pk_mul_f32 v[40:41], v[40:41], v[50:51]
	v_pk_mul_f32 v[30:31], v[30:31], v[130:131] op_sel_hi:[1,0]
	v_cvt_pk_bf16_f32 v32, v40, v41
	v_cvt_pk_bf16_f32 v33, v42, v43
	v_cvt_pk_bf16_f32 v34, v34, v35
	v_cvt_pk_bf16_f32 v35, v36, v37
	v_mad_i64_i32 v[36:37], s[4:5], v170, s35, v[112:113]
	v_lshl_add_u64 v[36:37], v[36:37], 0, v[114:115]
	v_pk_mul_f32 v[28:29], v[28:29], v[130:131] op_sel_hi:[1,0]
	v_pk_mul_f32 v[26:27], v[26:27], v[130:131] op_sel_hi:[1,0]
	v_pk_mul_f32 v[24:25], v[24:25], v[130:131] op_sel_hi:[1,0]
	v_pk_mul_f32 v[22:23], v[22:23], v[130:131] op_sel_hi:[1,0]
	v_pk_mul_f32 v[20:21], v[20:21], v[130:131] op_sel_hi:[1,0]
	global_store_dwordx4 v[36:37], v[32:35], off
	v_pk_mul_f32 v[24:25], v[28:29], v[24:25]
	v_pk_mul_f32 v[26:27], v[30:31], v[26:27]
	v_pk_mul_f32 v[32:33], v[30:31], s[44:45] op_sel_hi:[1,0]
	v_pk_mul_f32 v[34:35], v[28:29], s[44:45] op_sel_hi:[1,0]
	v_pk_mul_f32 v[28:29], v[22:23], s[44:45] op_sel_hi:[1,0]
	v_pk_mul_f32 v[30:31], v[20:21], s[44:45] op_sel_hi:[1,0]
	v_exp_f32_e32 v28, v28
	v_exp_f32_e32 v30, v30
	v_exp_f32_e32 v29, v29
	v_exp_f32_e32 v31, v31
	v_exp_f32_e32 v34, v34
	v_exp_f32_e32 v32, v32
	v_exp_f32_e32 v33, v33
	v_exp_f32_e32 v35, v35
	v_pk_add_f32 v[28:29], v[28:29], 1.0 op_sel_hi:[1,0]
	v_pk_add_f32 v[30:31], v[30:31], 1.0 op_sel_hi:[1,0]
	v_pk_add_f32 v[32:33], v[32:33], 1.0 op_sel_hi:[1,0]
	v_pk_add_f32 v[34:35], v[34:35], 1.0 op_sel_hi:[1,0]
	v_rcp_f32_e32 v30, v30
	v_rcp_f32_e32 v28, v28
	v_rcp_f32_e32 v29, v29
	v_rcp_f32_e32 v31, v31
	v_rcp_f32_e32 v34, v34
	v_rcp_f32_e32 v32, v32
	v_rcp_f32_e32 v33, v33
	v_rcp_f32_e32 v35, v35
	v_pk_mul_f32 v[18:19], v[18:19], v[130:131] op_sel_hi:[1,0]
	v_pk_mul_f32 v[16:17], v[16:17], v[130:131] op_sel_hi:[1,0]
	v_pk_mul_f32 v[18:19], v[22:23], v[18:19]
	v_pk_mul_f32 v[16:17], v[20:21], v[16:17]
	v_pk_mul_f32 v[20:21], v[18:19], v[28:29]
	v_pk_mul_f32 v[18:19], v[16:17], v[30:31]
	v_pk_mul_f32 v[26:27], v[26:27], v[32:33]
	v_pk_mul_f32 v[24:25], v[24:25], v[34:35]
	v_pk_mul_f32 v[14:15], v[14:15], v[128:129] op_sel_hi:[1,0]
	v_cvt_pk_bf16_f32 v16, v24, v25
	v_cvt_pk_bf16_f32 v17, v26, v27
	v_cvt_pk_bf16_f32 v18, v18, v19
	v_cvt_pk_bf16_f32 v19, v20, v21
	v_mad_i64_i32 v[20:21], s[4:5], v168, s35, v[112:113]
	v_lshl_add_u64 v[20:21], v[20:21], 0, v[114:115]
	v_pk_mul_f32 v[12:13], v[12:13], v[128:129] op_sel_hi:[1,0]
	v_pk_mul_f32 v[10:11], v[10:11], v[128:129] op_sel_hi:[1,0]
	v_pk_mul_f32 v[8:9], v[8:9], v[128:129] op_sel_hi:[1,0]
	v_pk_mul_f32 v[6:7], v[6:7], v[128:129] op_sel_hi:[1,0]
	v_pk_mul_f32 v[4:5], v[4:5], v[128:129] op_sel_hi:[1,0]
	global_store_dwordx4 v[20:21], v[16:19], off
	v_pk_mul_f32 v[8:9], v[12:13], v[8:9]
	v_pk_mul_f32 v[10:11], v[14:15], v[10:11]
	v_pk_mul_f32 v[16:17], v[14:15], s[44:45] op_sel_hi:[1,0]
	v_pk_mul_f32 v[18:19], v[12:13], s[44:45] op_sel_hi:[1,0]
	v_pk_mul_f32 v[12:13], v[6:7], s[44:45] op_sel_hi:[1,0]
	v_pk_mul_f32 v[14:15], v[4:5], s[44:45] op_sel_hi:[1,0]
	v_exp_f32_e32 v12, v12
	v_exp_f32_e32 v14, v14
	v_exp_f32_e32 v13, v13
	v_exp_f32_e32 v15, v15
	v_exp_f32_e32 v18, v18
	v_exp_f32_e32 v16, v16
	v_exp_f32_e32 v17, v17
	v_exp_f32_e32 v19, v19
	v_pk_add_f32 v[12:13], v[12:13], 1.0 op_sel_hi:[1,0]
	v_pk_add_f32 v[14:15], v[14:15], 1.0 op_sel_hi:[1,0]
	v_pk_add_f32 v[16:17], v[16:17], 1.0 op_sel_hi:[1,0]
	v_pk_add_f32 v[18:19], v[18:19], 1.0 op_sel_hi:[1,0]
	v_rcp_f32_e32 v14, v14
	v_rcp_f32_e32 v12, v12
	v_rcp_f32_e32 v13, v13
	v_rcp_f32_e32 v15, v15
	v_rcp_f32_e32 v18, v18
	v_rcp_f32_e32 v16, v16
	v_rcp_f32_e32 v17, v17
	v_rcp_f32_e32 v19, v19
	v_pk_mul_f32 v[2:3], v[2:3], v[128:129] op_sel_hi:[1,0]
	v_pk_mul_f32 v[0:1], v[0:1], v[128:129] op_sel_hi:[1,0]
	v_pk_mul_f32 v[2:3], v[6:7], v[2:3]
	v_pk_mul_f32 v[0:1], v[4:5], v[0:1]
	v_pk_mul_f32 v[4:5], v[2:3], v[12:13]
	v_pk_mul_f32 v[2:3], v[0:1], v[14:15]
	v_pk_mul_f32 v[10:11], v[10:11], v[16:17]
	v_pk_mul_f32 v[8:9], v[8:9], v[18:19]
	s_andn2_b64 vcc, exec, s[2:3]
	v_cvt_pk_bf16_f32 v0, v8, v9
	v_cvt_pk_bf16_f32 v1, v10, v11
	v_cvt_pk_bf16_f32 v2, v2, v3
	v_cvt_pk_bf16_f32 v3, v4, v5
	v_mad_i64_i32 v[4:5], s[4:5], v166, s35, v[112:113]
	v_lshl_add_u64 v[4:5], v[4:5], 0, v[114:115]
	s_mov_b32 s4, s16
	s_mov_b32 s5, s12
	s_mov_b64 s[6:7], s[18:19]
	global_store_dwordx4 v[4:5], v[0:3], off
	s_cbranch_vccnz .LBB0_1429
	s_waitcnt vmcnt(0)
	s_cmpk_gt_u32 s24, 0xff
	s_cbranch_scc1 .LBB0_1440
	s_barrier
